# removed mid-block s_setprio 0/1 toggles inside the 32-MFMA blocks of the GEMM loops
# speedup vs baseline: 1.0075x; 1.0075x over previous
.LBB0_379:
	v_add_u32_e32 v145, s48, v151
	ds_read_b128 v[164:167], v145
	ds_read_b128 v[168:171], v145 offset:1024
	ds_read_b128 v[172:175], v145 offset:2048
	ds_read_b128 v[176:179], v145 offset:3072
	v_add_u32_e32 v145, s49, v151
	ds_read_b128 v[184:187], v145
	ds_read_b128 v[188:191], v145 offset:1024
	ds_read_b128 v[192:195], v145 offset:2048
	ds_read_b128 v[196:199], v145 offset:3072
	s_add_u32 s30, s8, 0xfffc0080
	s_addc_u32 s31, s9, -1
	s_and_b64 s[28:29], s[28:29], exec
	s_cselect_b32 s31, s23, s31
	s_cselect_b32 s30, s61, s30
	s_cselect_b32 s29, s21, s64
	s_cselect_b32 s28, s62, s63
	v_lshl_add_u64 v[148:149], s[8:9], 0, v[138:139]
	s_add_i32 m0, s39, 0xc000
	ds_read_b128 v[200:203], v153
	ds_read_b128 v[204:207], v153 offset:1024
	ds_read_b128 v[208:211], v153 offset:2048
	ds_read_b128 v[212:215], v153 offset:3072
	ds_read_b128 v[216:219], v153 offset:4096
	ds_read_b128 v[220:223], v153 offset:5120
	ds_read_b128 v[224:227], v153 offset:6144
	ds_read_b128 v[228:231], v153 offset:7168
	global_load_lds_dwordx4 v[148:149], off
	v_lshl_add_u64 v[148:149], s[8:9], 0, v[136:137]
	s_add_i32 m0, s39, 0xe000
	s_nop 0
	global_load_lds_dwordx4 v[148:149], off
	s_waitcnt vmcnt(8)
	s_waitcnt lgkmcnt(0)
	s_barrier
	s_setprio 1
	s_waitcnt lgkmcnt(0)
	v_mfma_f32_16x16x32_bf16 v[124:127], v[164:167], v[200:203], v[124:127]
	v_mfma_f32_16x16x32_bf16 v[120:123], v[172:175], v[200:203], v[120:123]
	v_mfma_f32_16x16x32_bf16 v[108:111], v[164:167], v[208:211], v[108:111]
	v_mfma_f32_16x16x32_bf16 v[104:107], v[172:175], v[208:211], v[104:107]
	v_mfma_f32_16x16x32_bf16 v[92:95], v[164:167], v[216:219], v[92:95]
	v_mfma_f32_16x16x32_bf16 v[88:91], v[172:175], v[216:219], v[88:91]
	v_mfma_f32_16x16x32_bf16 v[76:79], v[164:167], v[224:227], v[76:79]
	v_mfma_f32_16x16x32_bf16 v[72:75], v[172:175], v[224:227], v[72:75]
	v_mfma_f32_16x16x32_bf16 v[124:127], v[168:171], v[204:207], v[124:127]
	v_mfma_f32_16x16x32_bf16 v[120:123], v[176:179], v[204:207], v[120:123]
	v_mfma_f32_16x16x32_bf16 v[108:111], v[168:171], v[212:215], v[108:111]
	v_mfma_f32_16x16x32_bf16 v[104:107], v[176:179], v[212:215], v[104:107]
	v_mfma_f32_16x16x32_bf16 v[92:95], v[168:171], v[220:223], v[92:95]
	v_mfma_f32_16x16x32_bf16 v[88:91], v[176:179], v[220:223], v[88:91]
	v_mfma_f32_16x16x32_bf16 v[76:79], v[168:171], v[228:231], v[76:79]
	v_mfma_f32_16x16x32_bf16 v[72:75], v[176:179], v[228:231], v[72:75]
	v_mfma_f32_16x16x32_bf16 v[116:119], v[184:187], v[200:203], v[116:119]
	v_mfma_f32_16x16x32_bf16 v[112:115], v[192:195], v[200:203], v[112:115]
	v_mfma_f32_16x16x32_bf16 v[100:103], v[184:187], v[208:211], v[100:103]
	v_mfma_f32_16x16x32_bf16 v[96:99], v[192:195], v[208:211], v[96:99]
	v_mfma_f32_16x16x32_bf16 v[84:87], v[184:187], v[216:219], v[84:87]
	v_mfma_f32_16x16x32_bf16 v[80:83], v[192:195], v[216:219], v[80:83]
	v_mfma_f32_16x16x32_bf16 v[68:71], v[184:187], v[224:227], v[68:71]
	v_mfma_f32_16x16x32_bf16 v[64:67], v[192:195], v[224:227], v[64:67]
	v_mfma_f32_16x16x32_bf16 v[116:119], v[188:191], v[204:207], v[116:119]
	v_mfma_f32_16x16x32_bf16 v[112:115], v[196:199], v[204:207], v[112:115]
	v_mfma_f32_16x16x32_bf16 v[100:103], v[188:191], v[212:215], v[100:103]
	v_mfma_f32_16x16x32_bf16 v[96:99], v[196:199], v[212:215], v[96:99]
	v_mfma_f32_16x16x32_bf16 v[84:87], v[188:191], v[220:223], v[84:87]
	v_mfma_f32_16x16x32_bf16 v[80:83], v[196:199], v[220:223], v[80:83]
	v_mfma_f32_16x16x32_bf16 v[68:71], v[188:191], v[228:231], v[68:71]
	v_mfma_f32_16x16x32_bf16 v[64:67], v[196:199], v[228:231], v[64:67]
	s_setprio 0
	s_barrier
	s_add_i32 s66, s48, s36
	v_lshl_add_u64 v[148:149], s[28:29], 0, v[132:133]
	s_mov_b32 m0, s66
	ds_read_b128 v[200:203], v153 offset:16384
	ds_read_b128 v[204:207], v153 offset:17408
	ds_read_b128 v[208:211], v153 offset:18432
	ds_read_b128 v[212:215], v153 offset:19456
	ds_read_b128 v[216:219], v153 offset:20480
	ds_read_b128 v[220:223], v153 offset:21504
	ds_read_b128 v[224:227], v153 offset:22528
	ds_read_b128 v[228:231], v153 offset:23552
	global_load_lds_dwordx4 v[148:149], off
	s_add_i32 m0, s66, 0x2000
	s_add_u32 s66, s28, 0x40000
	v_lshl_add_u64 v[232:233], s[28:29], 0, v[128:129]
	s_addc_u32 s67, s29, 0
	s_add_i32 s68, s49, s36
	global_load_lds_dwordx4 v[232:233], off
	v_lshl_add_u64 v[234:235], s[66:67], 0, v[132:133]
	s_mov_b32 m0, s68
	v_lshl_add_u64 v[236:237], s[30:31], 0, v[130:131]
	global_load_lds_dwordx4 v[234:235], off
	v_lshl_add_u64 v[234:235], s[66:67], 0, v[128:129]
	s_add_i32 m0, s68, 0x2000
	s_nop 0
	global_load_lds_dwordx4 v[234:235], off
	v_lshl_add_u64 v[234:235], s[30:31], 0, v[134:135]
	s_mov_b32 m0, s39
	s_nop 0
	global_load_lds_dwordx4 v[234:235], off
	s_mov_b32 m0, s40
	s_nop 0
	global_load_lds_dwordx4 v[236:237], off
	s_waitcnt vmcnt(8)
	s_waitcnt lgkmcnt(0)
	s_barrier
	s_setprio 1
	s_waitcnt lgkmcnt(0)
	v_mfma_f32_16x16x32_bf16 v[60:63], v[164:167], v[200:203], v[60:63]
	v_mfma_f32_16x16x32_bf16 v[56:59], v[172:175], v[200:203], v[56:59]
	v_mfma_f32_16x16x32_bf16 v[44:47], v[164:167], v[208:211], v[44:47]
	v_mfma_f32_16x16x32_bf16 v[40:43], v[172:175], v[208:211], v[40:43]
	v_mfma_f32_16x16x32_bf16 v[28:31], v[164:167], v[216:219], v[28:31]
	v_mfma_f32_16x16x32_bf16 v[24:27], v[172:175], v[216:219], v[24:27]
	v_mfma_f32_16x16x32_bf16 v[12:15], v[164:167], v[224:227], v[12:15]
	v_mfma_f32_16x16x32_bf16 v[8:11], v[172:175], v[224:227], v[8:11]
	v_mfma_f32_16x16x32_bf16 v[60:63], v[168:171], v[204:207], v[60:63]
	v_mfma_f32_16x16x32_bf16 v[56:59], v[176:179], v[204:207], v[56:59]
	v_mfma_f32_16x16x32_bf16 v[44:47], v[168:171], v[212:215], v[44:47]
	v_mfma_f32_16x16x32_bf16 v[40:43], v[176:179], v[212:215], v[40:43]
	v_mfma_f32_16x16x32_bf16 v[28:31], v[168:171], v[220:223], v[28:31]
	v_mfma_f32_16x16x32_bf16 v[24:27], v[176:179], v[220:223], v[24:27]
	v_mfma_f32_16x16x32_bf16 v[12:15], v[168:171], v[228:231], v[12:15]
	v_mfma_f32_16x16x32_bf16 v[8:11], v[176:179], v[228:231], v[8:11]
	v_mfma_f32_16x16x32_bf16 v[52:55], v[184:187], v[200:203], v[52:55]
	v_mfma_f32_16x16x32_bf16 v[48:51], v[192:195], v[200:203], v[48:51]
	v_mfma_f32_16x16x32_bf16 v[36:39], v[184:187], v[208:211], v[36:39]
	v_mfma_f32_16x16x32_bf16 v[32:35], v[192:195], v[208:211], v[32:35]
	v_mfma_f32_16x16x32_bf16 v[20:23], v[184:187], v[216:219], v[20:23]
	v_mfma_f32_16x16x32_bf16 v[16:19], v[192:195], v[216:219], v[16:19]
	v_mfma_f32_16x16x32_bf16 v[4:7], v[184:187], v[224:227], v[4:7]
	v_mfma_f32_16x16x32_bf16 v[0:3], v[192:195], v[224:227], v[0:3]
	v_mfma_f32_16x16x32_bf16 v[52:55], v[188:191], v[204:207], v[52:55]
	v_mfma_f32_16x16x32_bf16 v[48:51], v[196:199], v[204:207], v[48:51]
	v_mfma_f32_16x16x32_bf16 v[36:39], v[188:191], v[212:215], v[36:39]
	v_mfma_f32_16x16x32_bf16 v[32:35], v[196:199], v[212:215], v[32:35]
	v_mfma_f32_16x16x32_bf16 v[20:23], v[188:191], v[220:223], v[20:23]
	v_mfma_f32_16x16x32_bf16 v[16:19], v[196:199], v[220:223], v[16:19]
	v_mfma_f32_16x16x32_bf16 v[4:7], v[188:191], v[228:231], v[4:7]
	v_mfma_f32_16x16x32_bf16 v[0:3], v[196:199], v[228:231], v[0:3]
	s_setprio 0
	s_barrier
	s_add_i32 s66, 0, 0x18000
	v_add_u32_e32 v145, s66, v151
	s_add_i32 s67, 0, 0x1c000
	ds_read_b128 v[164:167], v145
	ds_read_b128 v[168:171], v145 offset:1024
	ds_read_b128 v[172:175], v145 offset:2048
	ds_read_b128 v[176:179], v145 offset:3072
	v_add_u32_e32 v145, s67, v151
	ds_read_b128 v[184:187], v145
	ds_read_b128 v[188:191], v145 offset:1024
	ds_read_b128 v[192:195], v145 offset:2048
	ds_read_b128 v[196:199], v145 offset:3072
	s_add_u32 s30, s30, 0x40000
	s_addc_u32 s31, s31, 0
	s_mov_b32 m0, s41
	v_lshl_add_u64 v[238:239], s[30:31], 0, v[134:135]
	ds_read_b128 v[200:203], v153 offset:32768
	ds_read_b128 v[204:207], v153 offset:33792
	ds_read_b128 v[208:211], v153 offset:34816
	ds_read_b128 v[212:215], v153 offset:35840
	ds_read_b128 v[216:219], v153 offset:36864
	ds_read_b128 v[220:223], v153 offset:37888
	ds_read_b128 v[224:227], v153 offset:38912
	ds_read_b128 v[228:231], v153 offset:39936
	global_load_lds_dwordx4 v[238:239], off
	v_lshl_add_u64 v[238:239], s[30:31], 0, v[130:131]
	s_mov_b32 m0, s42
	s_nop 0
	global_load_lds_dwordx4 v[238:239], off
	s_waitcnt vmcnt(8)
	s_waitcnt lgkmcnt(0)
	s_barrier
	s_setprio 1
	s_waitcnt lgkmcnt(0)
	v_mfma_f32_16x16x32_bf16 v[124:127], v[164:167], v[200:203], v[124:127]
	v_mfma_f32_16x16x32_bf16 v[120:123], v[172:175], v[200:203], v[120:123]
	v_mfma_f32_16x16x32_bf16 v[108:111], v[164:167], v[208:211], v[108:111]
	v_mfma_f32_16x16x32_bf16 v[104:107], v[172:175], v[208:211], v[104:107]
	v_mfma_f32_16x16x32_bf16 v[92:95], v[164:167], v[216:219], v[92:95]
	v_mfma_f32_16x16x32_bf16 v[88:91], v[172:175], v[216:219], v[88:91]
	v_mfma_f32_16x16x32_bf16 v[76:79], v[164:167], v[224:227], v[76:79]
	v_mfma_f32_16x16x32_bf16 v[72:75], v[172:175], v[224:227], v[72:75]
	v_mfma_f32_16x16x32_bf16 v[124:127], v[168:171], v[204:207], v[124:127]
	v_mfma_f32_16x16x32_bf16 v[120:123], v[176:179], v[204:207], v[120:123]
	v_mfma_f32_16x16x32_bf16 v[108:111], v[168:171], v[212:215], v[108:111]
	v_mfma_f32_16x16x32_bf16 v[104:107], v[176:179], v[212:215], v[104:107]
	v_mfma_f32_16x16x32_bf16 v[92:95], v[168:171], v[220:223], v[92:95]
	v_mfma_f32_16x16x32_bf16 v[88:91], v[176:179], v[220:223], v[88:91]
	v_mfma_f32_16x16x32_bf16 v[76:79], v[168:171], v[228:231], v[76:79]
	v_mfma_f32_16x16x32_bf16 v[72:75], v[176:179], v[228:231], v[72:75]
	v_mfma_f32_16x16x32_bf16 v[116:119], v[184:187], v[200:203], v[116:119]
	v_mfma_f32_16x16x32_bf16 v[112:115], v[192:195], v[200:203], v[112:115]
	v_mfma_f32_16x16x32_bf16 v[100:103], v[184:187], v[208:211], v[100:103]
	v_mfma_f32_16x16x32_bf16 v[96:99], v[192:195], v[208:211], v[96:99]
	v_mfma_f32_16x16x32_bf16 v[84:87], v[184:187], v[216:219], v[84:87]
	v_mfma_f32_16x16x32_bf16 v[80:83], v[192:195], v[216:219], v[80:83]
	v_mfma_f32_16x16x32_bf16 v[68:71], v[184:187], v[224:227], v[68:71]
	v_mfma_f32_16x16x32_bf16 v[64:67], v[192:195], v[224:227], v[64:67]
	v_mfma_f32_16x16x32_bf16 v[116:119], v[188:191], v[204:207], v[116:119]
	v_mfma_f32_16x16x32_bf16 v[112:115], v[196:199], v[204:207], v[112:115]
	v_mfma_f32_16x16x32_bf16 v[100:103], v[188:191], v[212:215], v[100:103]
	v_mfma_f32_16x16x32_bf16 v[96:99], v[196:199], v[212:215], v[96:99]
	v_mfma_f32_16x16x32_bf16 v[84:87], v[188:191], v[220:223], v[84:87]
	v_mfma_f32_16x16x32_bf16 v[80:83], v[196:199], v[220:223], v[80:83]
	v_mfma_f32_16x16x32_bf16 v[68:71], v[188:191], v[228:231], v[68:71]
	v_mfma_f32_16x16x32_bf16 v[64:67], v[196:199], v[228:231], v[64:67]
	s_setprio 0
	s_barrier
	s_add_i32 s30, s66, s36
	v_lshl_add_u64 v[148:149], v[148:149], 0, s[16:17]
	s_mov_b32 m0, s30
	ds_read_b128 v[200:203], v153 offset:49152
	ds_read_b128 v[204:207], v153 offset:50176
	ds_read_b128 v[208:211], v153 offset:51200
	ds_read_b128 v[212:215], v153 offset:52224
	ds_read_b128 v[216:219], v153 offset:53248
	ds_read_b128 v[220:223], v153 offset:54272
	ds_read_b128 v[224:227], v153 offset:55296
	ds_read_b128 v[228:231], v153 offset:56320
	global_load_lds_dwordx4 v[148:149], off
	s_add_i32 m0, s30, 0x2000
	s_add_u32 s28, s28, 0x40080
	v_lshl_add_u64 v[148:149], v[232:233], 0, s[16:17]
	s_addc_u32 s29, s29, 0
	s_add_i32 s30, s67, s36
	global_load_lds_dwordx4 v[148:149], off
	v_lshl_add_u64 v[148:149], s[28:29], 0, v[132:133]
	s_mov_b32 m0, s30
	s_nop 0
	global_load_lds_dwordx4 v[148:149], off
	v_lshl_add_u64 v[148:149], s[28:29], 0, v[128:129]
	s_add_i32 m0, s30, 0x2000
	s_nop 0
	global_load_lds_dwordx4 v[148:149], off
	v_lshl_add_u64 v[148:149], v[234:235], 0, s[16:17]
	s_mov_b32 m0, s44
	s_nop 0
	global_load_lds_dwordx4 v[148:149], off
	v_lshl_add_u64 v[148:149], v[236:237], 0, s[16:17]
	s_mov_b32 m0, s45
	s_nop 0
	global_load_lds_dwordx4 v[148:149], off
	s_waitcnt vmcnt(8)
	s_waitcnt lgkmcnt(0)
	s_barrier
	s_setprio 1
	s_waitcnt lgkmcnt(0)
	v_mfma_f32_16x16x32_bf16 v[60:63], v[164:167], v[200:203], v[60:63]
	v_mfma_f32_16x16x32_bf16 v[56:59], v[172:175], v[200:203], v[56:59]
	v_mfma_f32_16x16x32_bf16 v[44:47], v[164:167], v[208:211], v[44:47]
	v_mfma_f32_16x16x32_bf16 v[40:43], v[172:175], v[208:211], v[40:43]
	v_mfma_f32_16x16x32_bf16 v[28:31], v[164:167], v[216:219], v[28:31]
	v_mfma_f32_16x16x32_bf16 v[24:27], v[172:175], v[216:219], v[24:27]
	v_mfma_f32_16x16x32_bf16 v[12:15], v[164:167], v[224:227], v[12:15]
	v_mfma_f32_16x16x32_bf16 v[8:11], v[172:175], v[224:227], v[8:11]
	v_mfma_f32_16x16x32_bf16 v[60:63], v[168:171], v[204:207], v[60:63]
	v_mfma_f32_16x16x32_bf16 v[56:59], v[176:179], v[204:207], v[56:59]
	v_mfma_f32_16x16x32_bf16 v[44:47], v[168:171], v[212:215], v[44:47]
	v_mfma_f32_16x16x32_bf16 v[40:43], v[176:179], v[212:215], v[40:43]
	v_mfma_f32_16x16x32_bf16 v[28:31], v[168:171], v[220:223], v[28:31]
	v_mfma_f32_16x16x32_bf16 v[24:27], v[176:179], v[220:223], v[24:27]
	v_mfma_f32_16x16x32_bf16 v[12:15], v[168:171], v[228:231], v[12:15]
	v_mfma_f32_16x16x32_bf16 v[8:11], v[176:179], v[228:231], v[8:11]
	v_mfma_f32_16x16x32_bf16 v[52:55], v[184:187], v[200:203], v[52:55]
	v_mfma_f32_16x16x32_bf16 v[48:51], v[192:195], v[200:203], v[48:51]
	v_mfma_f32_16x16x32_bf16 v[36:39], v[184:187], v[208:211], v[36:39]
	v_mfma_f32_16x16x32_bf16 v[32:35], v[192:195], v[208:211], v[32:35]
	v_mfma_f32_16x16x32_bf16 v[20:23], v[184:187], v[216:219], v[20:23]
	v_mfma_f32_16x16x32_bf16 v[16:19], v[192:195], v[216:219], v[16:19]
	v_mfma_f32_16x16x32_bf16 v[4:7], v[184:187], v[224:227], v[4:7]
	v_mfma_f32_16x16x32_bf16 v[0:3], v[192:195], v[224:227], v[0:3]
	v_mfma_f32_16x16x32_bf16 v[52:55], v[188:191], v[204:207], v[52:55]
	v_mfma_f32_16x16x32_bf16 v[48:51], v[196:199], v[204:207], v[48:51]
	v_mfma_f32_16x16x32_bf16 v[36:39], v[188:191], v[212:215], v[36:39]
	v_mfma_f32_16x16x32_bf16 v[32:35], v[196:199], v[212:215], v[32:35]
	v_mfma_f32_16x16x32_bf16 v[20:23], v[188:191], v[220:223], v[20:23]
	v_mfma_f32_16x16x32_bf16 v[16:19], v[196:199], v[220:223], v[16:19]
	v_mfma_f32_16x16x32_bf16 v[4:7], v[188:191], v[228:231], v[4:7]
	v_mfma_f32_16x16x32_bf16 v[0:3], v[196:199], v[228:231], v[0:3]
	s_setprio 0
	s_barrier
	s_add_i32 s65, s65, 2
	s_add_u32 s63, s63, 0x100
	s_addc_u32 s64, s64, 0
	s_add_u32 s8, s8, 0x100
	s_addc_u32 s9, s9, 0
	s_cmp_gt_u32 s65, 13
	s_cbranch_scc1 .LBB0_382

.LBB0_466:
	s_waitcnt lgkmcnt(0)
	ds_read_b128 v[138:141], v151
	ds_read_b128 v[142:145], v151 offset:1024
	ds_read_b128 v[156:159], v151 offset:2048
	ds_read_b128 v[160:163], v151 offset:3072
	ds_read_b128 v[164:167], v152
	ds_read_b128 v[168:171], v152 offset:1024
	ds_read_b128 v[172:175], v152 offset:2048
	ds_read_b128 v[176:179], v152 offset:3072
	s_add_i32 vcc_hi, s44, 2
	s_add_u32 s45, s42, 0xfff50080
	s_addc_u32 s46, s43, -1
	s_cmp_eq_u32 s37, s44
	s_cselect_b32 s44, s40, s97
	s_cselect_b32 s47, s39, s46
	s_cselect_b32 s46, s38, s45
	s_cselect_b32 s45, s41, vcc_lo
	v_lshl_add_u64 v[146:147], s[42:43], 0, v[136:137]
	s_add_i32 m0, s60, 0xc000
	ds_read_b128 v[184:187], v153
	ds_read_b128 v[188:191], v153 offset:1024
	ds_read_b128 v[192:195], v153 offset:2048
	ds_read_b128 v[196:199], v153 offset:3072
	ds_read_b128 v[200:203], v153 offset:4096
	ds_read_b128 v[204:207], v153 offset:5120
	ds_read_b128 v[208:211], v153 offset:6144
	ds_read_b128 v[212:215], v153 offset:7168
	global_load_lds_dwordx4 v[146:147], off
	v_lshl_add_u64 v[146:147], s[42:43], 0, v[134:135]
	s_add_i32 m0, s60, 0xe000
	s_nop 0
	global_load_lds_dwordx4 v[146:147], off
	s_waitcnt vmcnt(8)
	s_waitcnt lgkmcnt(0)
	s_barrier
	s_setprio 1
	s_waitcnt lgkmcnt(0)
	v_mfma_f32_16x16x32_bf16 v[124:127], v[138:141], v[184:187], v[124:127]
	v_mfma_f32_16x16x32_bf16 v[120:123], v[156:159], v[184:187], v[120:123]
	v_mfma_f32_16x16x32_bf16 v[108:111], v[138:141], v[192:195], v[108:111]
	v_mfma_f32_16x16x32_bf16 v[104:107], v[156:159], v[192:195], v[104:107]
	v_mfma_f32_16x16x32_bf16 v[92:95], v[138:141], v[200:203], v[92:95]
	v_mfma_f32_16x16x32_bf16 v[88:91], v[156:159], v[200:203], v[88:91]
	v_mfma_f32_16x16x32_bf16 v[76:79], v[138:141], v[208:211], v[76:79]
	v_mfma_f32_16x16x32_bf16 v[72:75], v[156:159], v[208:211], v[72:75]
	v_mfma_f32_16x16x32_bf16 v[124:127], v[142:145], v[188:191], v[124:127]
	v_mfma_f32_16x16x32_bf16 v[120:123], v[160:163], v[188:191], v[120:123]
	v_mfma_f32_16x16x32_bf16 v[108:111], v[142:145], v[196:199], v[108:111]
	v_mfma_f32_16x16x32_bf16 v[104:107], v[160:163], v[196:199], v[104:107]
	v_mfma_f32_16x16x32_bf16 v[92:95], v[142:145], v[204:207], v[92:95]
	v_mfma_f32_16x16x32_bf16 v[88:91], v[160:163], v[204:207], v[88:91]
	v_mfma_f32_16x16x32_bf16 v[76:79], v[142:145], v[212:215], v[76:79]
	v_mfma_f32_16x16x32_bf16 v[72:75], v[160:163], v[212:215], v[72:75]
	v_mfma_f32_16x16x32_bf16 v[116:119], v[164:167], v[184:187], v[116:119]
	v_mfma_f32_16x16x32_bf16 v[112:115], v[172:175], v[184:187], v[112:115]
	v_mfma_f32_16x16x32_bf16 v[100:103], v[164:167], v[192:195], v[100:103]
	v_mfma_f32_16x16x32_bf16 v[96:99], v[172:175], v[192:195], v[96:99]
	v_mfma_f32_16x16x32_bf16 v[84:87], v[164:167], v[200:203], v[84:87]
	v_mfma_f32_16x16x32_bf16 v[80:83], v[172:175], v[200:203], v[80:83]
	v_mfma_f32_16x16x32_bf16 v[68:71], v[164:167], v[208:211], v[68:71]
	v_mfma_f32_16x16x32_bf16 v[64:67], v[172:175], v[208:211], v[64:67]
	v_mfma_f32_16x16x32_bf16 v[116:119], v[168:171], v[188:191], v[116:119]
	v_mfma_f32_16x16x32_bf16 v[112:115], v[176:179], v[188:191], v[112:115]
	v_mfma_f32_16x16x32_bf16 v[100:103], v[168:171], v[196:199], v[100:103]
	v_mfma_f32_16x16x32_bf16 v[96:99], v[176:179], v[196:199], v[96:99]
	v_mfma_f32_16x16x32_bf16 v[84:87], v[168:171], v[204:207], v[84:87]
	v_mfma_f32_16x16x32_bf16 v[80:83], v[176:179], v[204:207], v[80:83]
	v_mfma_f32_16x16x32_bf16 v[68:71], v[168:171], v[212:215], v[68:71]
	v_mfma_f32_16x16x32_bf16 v[64:67], v[176:179], v[212:215], v[64:67]
	s_setprio 0
	s_barrier
	s_add_i32 s90, s84, s59
	v_lshl_add_u64 v[146:147], s[44:45], 0, v[128:129]
	s_mov_b32 m0, s90
	ds_read_b128 v[184:187], v153 offset:16384
	ds_read_b128 v[188:191], v153 offset:17408
	ds_read_b128 v[192:195], v153 offset:18432
	ds_read_b128 v[196:199], v153 offset:19456
	ds_read_b128 v[200:203], v153 offset:20480
	ds_read_b128 v[204:207], v153 offset:21504
	ds_read_b128 v[208:211], v153 offset:22528
	ds_read_b128 v[212:215], v153 offset:23552
	global_load_lds_dwordx4 v[146:147], off
	s_add_i32 m0, s90, 0x2000
	s_add_u32 s90, s44, 0xb0000
	v_lshl_add_u64 v[216:217], s[44:45], 0, v[130:131]
	s_addc_u32 s91, s45, 0
	s_add_i32 s80, s85, s59
	global_load_lds_dwordx4 v[216:217], off
	v_lshl_add_u64 v[218:219], s[90:91], 0, v[128:129]
	s_mov_b32 m0, s80
	v_lshl_add_u64 v[220:221], s[46:47], 0, v[130:131]
	global_load_lds_dwordx4 v[218:219], off
	v_lshl_add_u64 v[218:219], s[90:91], 0, v[130:131]
	s_add_i32 m0, s80, 0x2000
	s_nop 0
	global_load_lds_dwordx4 v[218:219], off
	v_lshl_add_u64 v[218:219], s[46:47], 0, v[128:129]
	s_mov_b32 m0, s60
	s_nop 0
	global_load_lds_dwordx4 v[218:219], off
	s_mov_b32 m0, s61
	s_nop 0
	global_load_lds_dwordx4 v[220:221], off
	s_waitcnt vmcnt(8)
	s_waitcnt lgkmcnt(0)
	s_barrier
	s_setprio 1
	s_waitcnt lgkmcnt(0)
	v_mfma_f32_16x16x32_bf16 v[60:63], v[138:141], v[184:187], v[60:63]
	v_mfma_f32_16x16x32_bf16 v[56:59], v[156:159], v[184:187], v[56:59]
	v_mfma_f32_16x16x32_bf16 v[44:47], v[138:141], v[192:195], v[44:47]
	v_mfma_f32_16x16x32_bf16 v[40:43], v[156:159], v[192:195], v[40:43]
	v_mfma_f32_16x16x32_bf16 v[28:31], v[138:141], v[200:203], v[28:31]
	v_mfma_f32_16x16x32_bf16 v[24:27], v[156:159], v[200:203], v[24:27]
	v_mfma_f32_16x16x32_bf16 v[12:15], v[138:141], v[208:211], v[12:15]
	v_mfma_f32_16x16x32_bf16 v[8:11], v[156:159], v[208:211], v[8:11]
	v_mfma_f32_16x16x32_bf16 v[60:63], v[142:145], v[188:191], v[60:63]
	v_mfma_f32_16x16x32_bf16 v[56:59], v[160:163], v[188:191], v[56:59]
	v_mfma_f32_16x16x32_bf16 v[44:47], v[142:145], v[196:199], v[44:47]
	v_mfma_f32_16x16x32_bf16 v[40:43], v[160:163], v[196:199], v[40:43]
	v_mfma_f32_16x16x32_bf16 v[28:31], v[142:145], v[204:207], v[28:31]
	v_mfma_f32_16x16x32_bf16 v[24:27], v[160:163], v[204:207], v[24:27]
	v_mfma_f32_16x16x32_bf16 v[12:15], v[142:145], v[212:215], v[12:15]
	v_mfma_f32_16x16x32_bf16 v[8:11], v[160:163], v[212:215], v[8:11]
	v_mfma_f32_16x16x32_bf16 v[52:55], v[164:167], v[184:187], v[52:55]
	v_mfma_f32_16x16x32_bf16 v[48:51], v[172:175], v[184:187], v[48:51]
	v_mfma_f32_16x16x32_bf16 v[36:39], v[164:167], v[192:195], v[36:39]
	v_mfma_f32_16x16x32_bf16 v[32:35], v[172:175], v[192:195], v[32:35]
	v_mfma_f32_16x16x32_bf16 v[20:23], v[164:167], v[200:203], v[20:23]
	v_mfma_f32_16x16x32_bf16 v[16:19], v[172:175], v[200:203], v[16:19]
	v_mfma_f32_16x16x32_bf16 v[4:7], v[164:167], v[208:211], v[4:7]
	v_mfma_f32_16x16x32_bf16 v[0:3], v[172:175], v[208:211], v[0:3]
	v_mfma_f32_16x16x32_bf16 v[52:55], v[168:171], v[188:191], v[52:55]
	v_mfma_f32_16x16x32_bf16 v[48:51], v[176:179], v[188:191], v[48:51]
	v_mfma_f32_16x16x32_bf16 v[36:39], v[168:171], v[196:199], v[36:39]
	v_mfma_f32_16x16x32_bf16 v[32:35], v[176:179], v[196:199], v[32:35]
	v_mfma_f32_16x16x32_bf16 v[20:23], v[168:171], v[204:207], v[20:23]
	v_mfma_f32_16x16x32_bf16 v[16:19], v[176:179], v[204:207], v[16:19]
	v_mfma_f32_16x16x32_bf16 v[4:7], v[168:171], v[212:215], v[4:7]
	v_mfma_f32_16x16x32_bf16 v[0:3], v[176:179], v[212:215], v[0:3]
	s_setprio 0
	s_barrier
	s_add_i32 s80, 0, 0x18000
	v_add_u32_e32 v132, s80, v149
	s_add_i32 s90, 0, 0x1c000
	ds_read_b128 v[138:141], v132
	ds_read_b128 v[142:145], v132 offset:1024
	ds_read_b128 v[156:159], v132 offset:2048
	ds_read_b128 v[160:163], v132 offset:3072
	v_add_u32_e32 v132, s90, v149
	ds_read_b128 v[164:167], v132
	ds_read_b128 v[168:171], v132 offset:1024
	ds_read_b128 v[172:175], v132 offset:2048
	ds_read_b128 v[176:179], v132 offset:3072
	s_add_u32 s46, s46, 0xb0000
	s_addc_u32 s47, s47, 0
	s_mov_b32 m0, s62
	v_lshl_add_u64 v[222:223], s[46:47], 0, v[128:129]
	ds_read_b128 v[184:187], v153 offset:32768
	ds_read_b128 v[188:191], v153 offset:33792
	ds_read_b128 v[192:195], v153 offset:34816
	ds_read_b128 v[196:199], v153 offset:35840
	ds_read_b128 v[200:203], v153 offset:36864
	ds_read_b128 v[204:207], v153 offset:37888
	ds_read_b128 v[208:211], v153 offset:38912
	ds_read_b128 v[212:215], v153 offset:39936
	global_load_lds_dwordx4 v[222:223], off
	v_lshl_add_u64 v[222:223], s[46:47], 0, v[130:131]
	s_mov_b32 m0, s63
	s_nop 0
	global_load_lds_dwordx4 v[222:223], off
	s_waitcnt vmcnt(8)
	s_waitcnt lgkmcnt(0)
	s_barrier
	s_setprio 1
	s_waitcnt lgkmcnt(0)
	v_mfma_f32_16x16x32_bf16 v[124:127], v[138:141], v[184:187], v[124:127]
	v_mfma_f32_16x16x32_bf16 v[120:123], v[156:159], v[184:187], v[120:123]
	v_mfma_f32_16x16x32_bf16 v[108:111], v[138:141], v[192:195], v[108:111]
	v_mfma_f32_16x16x32_bf16 v[104:107], v[156:159], v[192:195], v[104:107]
	v_mfma_f32_16x16x32_bf16 v[92:95], v[138:141], v[200:203], v[92:95]
	v_mfma_f32_16x16x32_bf16 v[88:91], v[156:159], v[200:203], v[88:91]
	v_mfma_f32_16x16x32_bf16 v[76:79], v[138:141], v[208:211], v[76:79]
	v_mfma_f32_16x16x32_bf16 v[72:75], v[156:159], v[208:211], v[72:75]
	v_mfma_f32_16x16x32_bf16 v[124:127], v[142:145], v[188:191], v[124:127]
	v_mfma_f32_16x16x32_bf16 v[120:123], v[160:163], v[188:191], v[120:123]
	v_mfma_f32_16x16x32_bf16 v[108:111], v[142:145], v[196:199], v[108:111]
	v_mfma_f32_16x16x32_bf16 v[104:107], v[160:163], v[196:199], v[104:107]
	v_mfma_f32_16x16x32_bf16 v[92:95], v[142:145], v[204:207], v[92:95]
	v_mfma_f32_16x16x32_bf16 v[88:91], v[160:163], v[204:207], v[88:91]
	v_mfma_f32_16x16x32_bf16 v[76:79], v[142:145], v[212:215], v[76:79]
	v_mfma_f32_16x16x32_bf16 v[72:75], v[160:163], v[212:215], v[72:75]
	v_mfma_f32_16x16x32_bf16 v[116:119], v[164:167], v[184:187], v[116:119]
	v_mfma_f32_16x16x32_bf16 v[112:115], v[172:175], v[184:187], v[112:115]
	v_mfma_f32_16x16x32_bf16 v[100:103], v[164:167], v[192:195], v[100:103]
	v_mfma_f32_16x16x32_bf16 v[96:99], v[172:175], v[192:195], v[96:99]
	v_mfma_f32_16x16x32_bf16 v[84:87], v[164:167], v[200:203], v[84:87]
	v_mfma_f32_16x16x32_bf16 v[80:83], v[172:175], v[200:203], v[80:83]
	v_mfma_f32_16x16x32_bf16 v[68:71], v[164:167], v[208:211], v[68:71]
	v_mfma_f32_16x16x32_bf16 v[64:67], v[172:175], v[208:211], v[64:67]
	v_mfma_f32_16x16x32_bf16 v[116:119], v[168:171], v[188:191], v[116:119]
	v_mfma_f32_16x16x32_bf16 v[112:115], v[176:179], v[188:191], v[112:115]
	v_mfma_f32_16x16x32_bf16 v[100:103], v[168:171], v[196:199], v[100:103]
	v_mfma_f32_16x16x32_bf16 v[96:99], v[176:179], v[196:199], v[96:99]
	v_mfma_f32_16x16x32_bf16 v[84:87], v[168:171], v[204:207], v[84:87]
	v_mfma_f32_16x16x32_bf16 v[80:83], v[176:179], v[204:207], v[80:83]
	v_mfma_f32_16x16x32_bf16 v[68:71], v[168:171], v[212:215], v[68:71]
	v_mfma_f32_16x16x32_bf16 v[64:67], v[176:179], v[212:215], v[64:67]
	s_setprio 0
	s_barrier
	s_add_i32 s46, s80, s59
	v_lshl_add_u64 v[146:147], v[146:147], 0, s[30:31]
	s_mov_b32 m0, s46
	ds_read_b128 v[184:187], v153 offset:49152
	ds_read_b128 v[188:191], v153 offset:50176
	ds_read_b128 v[192:195], v153 offset:51200
	ds_read_b128 v[196:199], v153 offset:52224
	ds_read_b128 v[200:203], v153 offset:53248
	ds_read_b128 v[204:207], v153 offset:54272
	ds_read_b128 v[208:211], v153 offset:55296
	ds_read_b128 v[212:215], v153 offset:56320
	global_load_lds_dwordx4 v[146:147], off
	s_add_i32 m0, s46, 0x2000
	s_add_u32 s44, s44, 0xb0080
	v_lshl_add_u64 v[146:147], v[216:217], 0, s[30:31]
	s_addc_u32 s45, s45, 0
	s_add_i32 s46, s90, s59
	global_load_lds_dwordx4 v[146:147], off
	v_lshl_add_u64 v[146:147], s[44:45], 0, v[128:129]
	s_mov_b32 m0, s46
	s_nop 0
	global_load_lds_dwordx4 v[146:147], off
	v_lshl_add_u64 v[146:147], s[44:45], 0, v[130:131]
	s_add_i32 m0, s46, 0x2000
	s_nop 0
	global_load_lds_dwordx4 v[146:147], off
	v_lshl_add_u64 v[146:147], v[218:219], 0, s[30:31]
	s_mov_b32 m0, s67
	s_nop 0
	global_load_lds_dwordx4 v[146:147], off
	v_lshl_add_u64 v[146:147], v[220:221], 0, s[30:31]
	s_mov_b32 m0, s68
	s_nop 0
	global_load_lds_dwordx4 v[146:147], off
	s_waitcnt vmcnt(8)
	s_waitcnt lgkmcnt(0)
	s_barrier
	s_setprio 1
	s_waitcnt lgkmcnt(0)
	v_mfma_f32_16x16x32_bf16 v[60:63], v[138:141], v[184:187], v[60:63]
	v_mfma_f32_16x16x32_bf16 v[56:59], v[156:159], v[184:187], v[56:59]
	v_mfma_f32_16x16x32_bf16 v[44:47], v[138:141], v[192:195], v[44:47]
	v_mfma_f32_16x16x32_bf16 v[40:43], v[156:159], v[192:195], v[40:43]
	v_mfma_f32_16x16x32_bf16 v[28:31], v[138:141], v[200:203], v[28:31]
	v_mfma_f32_16x16x32_bf16 v[24:27], v[156:159], v[200:203], v[24:27]
	v_mfma_f32_16x16x32_bf16 v[12:15], v[138:141], v[208:211], v[12:15]
	v_mfma_f32_16x16x32_bf16 v[8:11], v[156:159], v[208:211], v[8:11]
	v_mfma_f32_16x16x32_bf16 v[60:63], v[142:145], v[188:191], v[60:63]
	v_mfma_f32_16x16x32_bf16 v[56:59], v[160:163], v[188:191], v[56:59]
	v_mfma_f32_16x16x32_bf16 v[44:47], v[142:145], v[196:199], v[44:47]
	v_mfma_f32_16x16x32_bf16 v[40:43], v[160:163], v[196:199], v[40:43]
	v_mfma_f32_16x16x32_bf16 v[28:31], v[142:145], v[204:207], v[28:31]
	v_mfma_f32_16x16x32_bf16 v[24:27], v[160:163], v[204:207], v[24:27]
	v_mfma_f32_16x16x32_bf16 v[12:15], v[142:145], v[212:215], v[12:15]
	v_mfma_f32_16x16x32_bf16 v[8:11], v[160:163], v[212:215], v[8:11]
	v_mfma_f32_16x16x32_bf16 v[52:55], v[164:167], v[184:187], v[52:55]
	v_mfma_f32_16x16x32_bf16 v[48:51], v[172:175], v[184:187], v[48:51]
	v_mfma_f32_16x16x32_bf16 v[36:39], v[164:167], v[192:195], v[36:39]
	v_mfma_f32_16x16x32_bf16 v[32:35], v[172:175], v[192:195], v[32:35]
	v_mfma_f32_16x16x32_bf16 v[20:23], v[164:167], v[200:203], v[20:23]
	v_mfma_f32_16x16x32_bf16 v[16:19], v[172:175], v[200:203], v[16:19]
	v_mfma_f32_16x16x32_bf16 v[4:7], v[164:167], v[208:211], v[4:7]
	v_mfma_f32_16x16x32_bf16 v[0:3], v[172:175], v[208:211], v[0:3]
	v_mfma_f32_16x16x32_bf16 v[52:55], v[168:171], v[188:191], v[52:55]
	v_mfma_f32_16x16x32_bf16 v[48:51], v[176:179], v[188:191], v[48:51]
	v_mfma_f32_16x16x32_bf16 v[36:39], v[168:171], v[196:199], v[36:39]
	v_mfma_f32_16x16x32_bf16 v[32:35], v[176:179], v[196:199], v[32:35]
	v_mfma_f32_16x16x32_bf16 v[20:23], v[168:171], v[204:207], v[20:23]
	v_mfma_f32_16x16x32_bf16 v[16:19], v[176:179], v[204:207], v[16:19]
	v_mfma_f32_16x16x32_bf16 v[4:7], v[168:171], v[212:215], v[4:7]
	v_mfma_f32_16x16x32_bf16 v[0:3], v[176:179], v[212:215], v[0:3]
	s_setprio 0
	s_barrier
	s_add_u32 s97, s97, 0x100
	s_addc_u32 vcc_lo, vcc_lo, 0
	s_add_u32 s42, s42, 0x100
	s_addc_u32 s43, s43, 0
	s_cmp_ge_i32 vcc_hi, s96
	s_mov_b32 s44, vcc_hi
	s_cbranch_scc0 .LBB0_466
	s_and_b64 vcc, exec, s[34:35]
	s_cbranch_vccz .LBB0_469

.LBB0_606:
	v_add_u32_e32 v142, s71, v173
	ds_read_b128 v[130:133], v142
	ds_read_b128 v[134:137], v142 offset:1024
	ds_read_b128 v[138:141], v142 offset:2048
	ds_read_b128 v[164:167], v142 offset:3072
	v_add_u32_e32 v142, s72, v173
	ds_read_b128 v[168:171], v142
	ds_read_b128 v[190:193], v142 offset:1024
	ds_read_b128 v[194:197], v142 offset:2048
	ds_read_b128 v[198:201], v142 offset:3072
	s_add_u32 s48, s8, 0xfffc0080
	s_addc_u32 s49, s9, -1
	s_and_b64 s[10:11], s[10:11], exec
	s_cselect_b32 s49, s33, s49
	s_cselect_b32 s48, s43, s48
	s_cselect_b32 s11, s41, s87
	s_cselect_b32 s10, s85, s86
	v_lshl_add_u64 v[142:143], s[8:9], 0, v[156:157]
	s_add_i32 m0, s62, 0xc000
	ds_read_b128 v[202:205], v176
	ds_read_b128 v[206:209], v176 offset:1024
	ds_read_b128 v[210:213], v176 offset:2048
	ds_read_b128 v[214:217], v176 offset:3072
	ds_read_b128 v[218:221], v176 offset:4096
	ds_read_b128 v[222:225], v176 offset:5120
	ds_read_b128 v[226:229], v176 offset:6144
	ds_read_b128 v[230:233], v176 offset:7168
	global_load_lds_dwordx4 v[142:143], off
	v_lshl_add_u64 v[142:143], s[8:9], 0, v[154:155]
	s_add_i32 m0, s62, 0xe000
	s_nop 0
	global_load_lds_dwordx4 v[142:143], off
	s_waitcnt vmcnt(8)
	s_waitcnt lgkmcnt(0)
	s_barrier
	s_setprio 1
	s_waitcnt lgkmcnt(0)
	v_mfma_f32_16x16x32_bf16 v[124:127], v[130:133], v[202:205], v[124:127]
	v_mfma_f32_16x16x32_bf16 v[120:123], v[138:141], v[202:205], v[120:123]
	v_mfma_f32_16x16x32_bf16 v[108:111], v[130:133], v[210:213], v[108:111]
	v_mfma_f32_16x16x32_bf16 v[104:107], v[138:141], v[210:213], v[104:107]
	v_mfma_f32_16x16x32_bf16 v[92:95], v[130:133], v[218:221], v[92:95]
	v_mfma_f32_16x16x32_bf16 v[88:91], v[138:141], v[218:221], v[88:91]
	v_mfma_f32_16x16x32_bf16 v[76:79], v[130:133], v[226:229], v[76:79]
	v_mfma_f32_16x16x32_bf16 v[72:75], v[138:141], v[226:229], v[72:75]
	v_mfma_f32_16x16x32_bf16 v[124:127], v[134:137], v[206:209], v[124:127]
	v_mfma_f32_16x16x32_bf16 v[120:123], v[164:167], v[206:209], v[120:123]
	v_mfma_f32_16x16x32_bf16 v[108:111], v[134:137], v[214:217], v[108:111]
	v_mfma_f32_16x16x32_bf16 v[104:107], v[164:167], v[214:217], v[104:107]
	v_mfma_f32_16x16x32_bf16 v[92:95], v[134:137], v[222:225], v[92:95]
	v_mfma_f32_16x16x32_bf16 v[88:91], v[164:167], v[222:225], v[88:91]
	v_mfma_f32_16x16x32_bf16 v[76:79], v[134:137], v[230:233], v[76:79]
	v_mfma_f32_16x16x32_bf16 v[72:75], v[164:167], v[230:233], v[72:75]
	v_mfma_f32_16x16x32_bf16 v[116:119], v[168:171], v[202:205], v[116:119]
	v_mfma_f32_16x16x32_bf16 v[112:115], v[194:197], v[202:205], v[112:115]
	v_mfma_f32_16x16x32_bf16 v[100:103], v[168:171], v[210:213], v[100:103]
	v_mfma_f32_16x16x32_bf16 v[96:99], v[194:197], v[210:213], v[96:99]
	v_mfma_f32_16x16x32_bf16 v[84:87], v[168:171], v[218:221], v[84:87]
	v_mfma_f32_16x16x32_bf16 v[80:83], v[194:197], v[218:221], v[80:83]
	v_mfma_f32_16x16x32_bf16 v[68:71], v[168:171], v[226:229], v[68:71]
	v_mfma_f32_16x16x32_bf16 v[64:67], v[194:197], v[226:229], v[64:67]
	v_mfma_f32_16x16x32_bf16 v[116:119], v[190:193], v[206:209], v[116:119]
	v_mfma_f32_16x16x32_bf16 v[112:115], v[198:201], v[206:209], v[112:115]
	v_mfma_f32_16x16x32_bf16 v[100:103], v[190:193], v[214:217], v[100:103]
	v_mfma_f32_16x16x32_bf16 v[96:99], v[198:201], v[214:217], v[96:99]
	v_mfma_f32_16x16x32_bf16 v[84:87], v[190:193], v[222:225], v[84:87]
	v_mfma_f32_16x16x32_bf16 v[80:83], v[198:201], v[222:225], v[80:83]
	v_mfma_f32_16x16x32_bf16 v[68:71], v[190:193], v[230:233], v[68:71]
	v_mfma_f32_16x16x32_bf16 v[64:67], v[198:201], v[230:233], v[64:67]
	s_setprio 0
	s_barrier
	s_add_i32 s76, s71, s59
	v_lshl_add_u64 v[142:143], s[10:11], 0, v[148:149]
	s_mov_b32 m0, s76
	ds_read_b128 v[202:205], v176 offset:16384
	ds_read_b128 v[206:209], v176 offset:17408
	ds_read_b128 v[210:213], v176 offset:18432
	ds_read_b128 v[214:217], v176 offset:19456
	ds_read_b128 v[218:221], v176 offset:20480
	ds_read_b128 v[222:225], v176 offset:21504
	ds_read_b128 v[226:229], v176 offset:22528
	ds_read_b128 v[230:233], v176 offset:23552
	global_load_lds_dwordx4 v[142:143], off
	s_add_i32 m0, s76, 0x2000
	s_add_u32 s90, s10, 0x40000
	v_lshl_add_u64 v[234:235], s[10:11], 0, v[144:145]
	s_addc_u32 s91, s11, 0
	s_add_i32 s76, s72, s59
	global_load_lds_dwordx4 v[234:235], off
	v_lshl_add_u64 v[236:237], s[90:91], 0, v[148:149]
	s_mov_b32 m0, s76
	v_lshl_add_u64 v[238:239], s[48:49], 0, v[146:147]
	global_load_lds_dwordx4 v[236:237], off
	v_lshl_add_u64 v[236:237], s[90:91], 0, v[144:145]
	s_add_i32 m0, s76, 0x2000
	s_nop 0
	global_load_lds_dwordx4 v[236:237], off
	v_lshl_add_u64 v[236:237], s[48:49], 0, v[150:151]
	s_mov_b32 m0, s62
	s_nop 0
	global_load_lds_dwordx4 v[236:237], off
	s_mov_b32 m0, s63
	s_nop 0
	global_load_lds_dwordx4 v[238:239], off
	s_waitcnt vmcnt(8)
	s_waitcnt lgkmcnt(0)
	s_barrier
	s_setprio 1
	s_waitcnt lgkmcnt(0)
	v_mfma_f32_16x16x32_bf16 v[60:63], v[130:133], v[202:205], v[60:63]
	v_mfma_f32_16x16x32_bf16 v[56:59], v[138:141], v[202:205], v[56:59]
	v_mfma_f32_16x16x32_bf16 v[44:47], v[130:133], v[210:213], v[44:47]
	v_mfma_f32_16x16x32_bf16 v[40:43], v[138:141], v[210:213], v[40:43]
	v_mfma_f32_16x16x32_bf16 v[28:31], v[130:133], v[218:221], v[28:31]
	v_mfma_f32_16x16x32_bf16 v[24:27], v[138:141], v[218:221], v[24:27]
	v_mfma_f32_16x16x32_bf16 v[12:15], v[130:133], v[226:229], v[12:15]
	v_mfma_f32_16x16x32_bf16 v[8:11], v[138:141], v[226:229], v[8:11]
	v_mfma_f32_16x16x32_bf16 v[60:63], v[134:137], v[206:209], v[60:63]
	v_mfma_f32_16x16x32_bf16 v[56:59], v[164:167], v[206:209], v[56:59]
	v_mfma_f32_16x16x32_bf16 v[44:47], v[134:137], v[214:217], v[44:47]
	v_mfma_f32_16x16x32_bf16 v[40:43], v[164:167], v[214:217], v[40:43]
	v_mfma_f32_16x16x32_bf16 v[28:31], v[134:137], v[222:225], v[28:31]
	v_mfma_f32_16x16x32_bf16 v[24:27], v[164:167], v[222:225], v[24:27]
	v_mfma_f32_16x16x32_bf16 v[12:15], v[134:137], v[230:233], v[12:15]
	v_mfma_f32_16x16x32_bf16 v[8:11], v[164:167], v[230:233], v[8:11]
	v_mfma_f32_16x16x32_bf16 v[52:55], v[168:171], v[202:205], v[52:55]
	v_mfma_f32_16x16x32_bf16 v[48:51], v[194:197], v[202:205], v[48:51]
	v_mfma_f32_16x16x32_bf16 v[36:39], v[168:171], v[210:213], v[36:39]
	v_mfma_f32_16x16x32_bf16 v[32:35], v[194:197], v[210:213], v[32:35]
	v_mfma_f32_16x16x32_bf16 v[20:23], v[168:171], v[218:221], v[20:23]
	v_mfma_f32_16x16x32_bf16 v[16:19], v[194:197], v[218:221], v[16:19]
	v_mfma_f32_16x16x32_bf16 v[4:7], v[168:171], v[226:229], v[4:7]
	v_mfma_f32_16x16x32_bf16 v[0:3], v[194:197], v[226:229], v[0:3]
	v_mfma_f32_16x16x32_bf16 v[52:55], v[190:193], v[206:209], v[52:55]
	v_mfma_f32_16x16x32_bf16 v[48:51], v[198:201], v[206:209], v[48:51]
	v_mfma_f32_16x16x32_bf16 v[36:39], v[190:193], v[214:217], v[36:39]
	v_mfma_f32_16x16x32_bf16 v[32:35], v[198:201], v[214:217], v[32:35]
	v_mfma_f32_16x16x32_bf16 v[20:23], v[190:193], v[222:225], v[20:23]
	v_mfma_f32_16x16x32_bf16 v[16:19], v[198:201], v[222:225], v[16:19]
	v_mfma_f32_16x16x32_bf16 v[4:7], v[190:193], v[230:233], v[4:7]
	v_mfma_f32_16x16x32_bf16 v[0:3], v[198:201], v[230:233], v[0:3]
	s_setprio 0
	s_barrier
	s_add_i32 s76, 0, 0x18000
	v_add_u32_e32 v152, s76, v173
	s_add_i32 s79, 0, 0x1c000
	ds_read_b128 v[130:133], v152
	ds_read_b128 v[134:137], v152 offset:1024
	ds_read_b128 v[138:141], v152 offset:2048
	ds_read_b128 v[164:167], v152 offset:3072
	v_add_u32_e32 v152, s79, v173
	ds_read_b128 v[168:171], v152
	ds_read_b128 v[190:193], v152 offset:1024
	ds_read_b128 v[194:197], v152 offset:2048
	ds_read_b128 v[198:201], v152 offset:3072
	s_add_u32 s48, s48, 0x40000
	s_addc_u32 s49, s49, 0
	s_mov_b32 m0, s64
	v_lshl_add_u64 v[240:241], s[48:49], 0, v[150:151]
	ds_read_b128 v[202:205], v176 offset:32768
	ds_read_b128 v[206:209], v176 offset:33792
	ds_read_b128 v[210:213], v176 offset:34816
	ds_read_b128 v[214:217], v176 offset:35840
	ds_read_b128 v[218:221], v176 offset:36864
	ds_read_b128 v[222:225], v176 offset:37888
	ds_read_b128 v[226:229], v176 offset:38912
	ds_read_b128 v[230:233], v176 offset:39936
	global_load_lds_dwordx4 v[240:241], off
	v_lshl_add_u64 v[240:241], s[48:49], 0, v[146:147]
	s_mov_b32 m0, s65
	s_nop 0
	global_load_lds_dwordx4 v[240:241], off
	s_waitcnt vmcnt(8)
	s_waitcnt lgkmcnt(0)
	s_barrier
	s_setprio 1
	s_waitcnt lgkmcnt(0)
	v_mfma_f32_16x16x32_bf16 v[124:127], v[130:133], v[202:205], v[124:127]
	v_mfma_f32_16x16x32_bf16 v[120:123], v[138:141], v[202:205], v[120:123]
	v_mfma_f32_16x16x32_bf16 v[108:111], v[130:133], v[210:213], v[108:111]
	v_mfma_f32_16x16x32_bf16 v[104:107], v[138:141], v[210:213], v[104:107]
	v_mfma_f32_16x16x32_bf16 v[92:95], v[130:133], v[218:221], v[92:95]
	v_mfma_f32_16x16x32_bf16 v[88:91], v[138:141], v[218:221], v[88:91]
	v_mfma_f32_16x16x32_bf16 v[76:79], v[130:133], v[226:229], v[76:79]
	v_mfma_f32_16x16x32_bf16 v[72:75], v[138:141], v[226:229], v[72:75]
	v_mfma_f32_16x16x32_bf16 v[124:127], v[134:137], v[206:209], v[124:127]
	v_mfma_f32_16x16x32_bf16 v[120:123], v[164:167], v[206:209], v[120:123]
	v_mfma_f32_16x16x32_bf16 v[108:111], v[134:137], v[214:217], v[108:111]
	v_mfma_f32_16x16x32_bf16 v[104:107], v[164:167], v[214:217], v[104:107]
	v_mfma_f32_16x16x32_bf16 v[92:95], v[134:137], v[222:225], v[92:95]
	v_mfma_f32_16x16x32_bf16 v[88:91], v[164:167], v[222:225], v[88:91]
	v_mfma_f32_16x16x32_bf16 v[76:79], v[134:137], v[230:233], v[76:79]
	v_mfma_f32_16x16x32_bf16 v[72:75], v[164:167], v[230:233], v[72:75]
	v_mfma_f32_16x16x32_bf16 v[116:119], v[168:171], v[202:205], v[116:119]
	v_mfma_f32_16x16x32_bf16 v[112:115], v[194:197], v[202:205], v[112:115]
	v_mfma_f32_16x16x32_bf16 v[100:103], v[168:171], v[210:213], v[100:103]
	v_mfma_f32_16x16x32_bf16 v[96:99], v[194:197], v[210:213], v[96:99]
	v_mfma_f32_16x16x32_bf16 v[84:87], v[168:171], v[218:221], v[84:87]
	v_mfma_f32_16x16x32_bf16 v[80:83], v[194:197], v[218:221], v[80:83]
	v_mfma_f32_16x16x32_bf16 v[68:71], v[168:171], v[226:229], v[68:71]
	v_mfma_f32_16x16x32_bf16 v[64:67], v[194:197], v[226:229], v[64:67]
	v_mfma_f32_16x16x32_bf16 v[116:119], v[190:193], v[206:209], v[116:119]
	v_mfma_f32_16x16x32_bf16 v[112:115], v[198:201], v[206:209], v[112:115]
	v_mfma_f32_16x16x32_bf16 v[100:103], v[190:193], v[214:217], v[100:103]
	v_mfma_f32_16x16x32_bf16 v[96:99], v[198:201], v[214:217], v[96:99]
	v_mfma_f32_16x16x32_bf16 v[84:87], v[190:193], v[222:225], v[84:87]
	v_mfma_f32_16x16x32_bf16 v[80:83], v[198:201], v[222:225], v[80:83]
	v_mfma_f32_16x16x32_bf16 v[68:71], v[190:193], v[230:233], v[68:71]
	v_mfma_f32_16x16x32_bf16 v[64:67], v[198:201], v[230:233], v[64:67]
	s_setprio 0
	s_barrier
	s_add_i32 s48, s76, s59
	v_lshl_add_u64 v[142:143], v[142:143], 0, s[22:23]
	s_mov_b32 m0, s48
	ds_read_b128 v[202:205], v176 offset:49152
	ds_read_b128 v[206:209], v176 offset:50176
	ds_read_b128 v[210:213], v176 offset:51200
	ds_read_b128 v[214:217], v176 offset:52224
	ds_read_b128 v[218:221], v176 offset:53248
	ds_read_b128 v[222:225], v176 offset:54272
	ds_read_b128 v[226:229], v176 offset:55296
	ds_read_b128 v[230:233], v176 offset:56320
	global_load_lds_dwordx4 v[142:143], off
	s_add_i32 m0, s48, 0x2000
	s_add_u32 s10, s10, 0x40080
	v_lshl_add_u64 v[142:143], v[234:235], 0, s[22:23]
	s_addc_u32 s11, s11, 0
	s_add_i32 s48, s79, s59
	global_load_lds_dwordx4 v[142:143], off
	v_lshl_add_u64 v[142:143], s[10:11], 0, v[148:149]
	s_mov_b32 m0, s48
	s_nop 0
	global_load_lds_dwordx4 v[142:143], off
	v_lshl_add_u64 v[142:143], s[10:11], 0, v[144:145]
	s_add_i32 m0, s48, 0x2000
	s_nop 0
	global_load_lds_dwordx4 v[142:143], off
	v_lshl_add_u64 v[142:143], v[236:237], 0, s[22:23]
	s_mov_b32 m0, s67
	s_nop 0
	global_load_lds_dwordx4 v[142:143], off
	v_lshl_add_u64 v[142:143], v[238:239], 0, s[22:23]
	s_mov_b32 m0, s68
	s_nop 0
	global_load_lds_dwordx4 v[142:143], off
	s_waitcnt vmcnt(8)
	s_waitcnt lgkmcnt(0)
	s_barrier
	s_setprio 1
	s_waitcnt lgkmcnt(0)
	v_mfma_f32_16x16x32_bf16 v[60:63], v[130:133], v[202:205], v[60:63]
	v_mfma_f32_16x16x32_bf16 v[56:59], v[138:141], v[202:205], v[56:59]
	v_mfma_f32_16x16x32_bf16 v[44:47], v[130:133], v[210:213], v[44:47]
	v_mfma_f32_16x16x32_bf16 v[40:43], v[138:141], v[210:213], v[40:43]
	v_mfma_f32_16x16x32_bf16 v[28:31], v[130:133], v[218:221], v[28:31]
	v_mfma_f32_16x16x32_bf16 v[24:27], v[138:141], v[218:221], v[24:27]
	v_mfma_f32_16x16x32_bf16 v[12:15], v[130:133], v[226:229], v[12:15]
	v_mfma_f32_16x16x32_bf16 v[8:11], v[138:141], v[226:229], v[8:11]
	v_mfma_f32_16x16x32_bf16 v[60:63], v[134:137], v[206:209], v[60:63]
	v_mfma_f32_16x16x32_bf16 v[56:59], v[164:167], v[206:209], v[56:59]
	v_mfma_f32_16x16x32_bf16 v[44:47], v[134:137], v[214:217], v[44:47]
	v_mfma_f32_16x16x32_bf16 v[40:43], v[164:167], v[214:217], v[40:43]
	v_mfma_f32_16x16x32_bf16 v[28:31], v[134:137], v[222:225], v[28:31]
	v_mfma_f32_16x16x32_bf16 v[24:27], v[164:167], v[222:225], v[24:27]
	v_mfma_f32_16x16x32_bf16 v[12:15], v[134:137], v[230:233], v[12:15]
	v_mfma_f32_16x16x32_bf16 v[8:11], v[164:167], v[230:233], v[8:11]
	v_mfma_f32_16x16x32_bf16 v[52:55], v[168:171], v[202:205], v[52:55]
	v_mfma_f32_16x16x32_bf16 v[48:51], v[194:197], v[202:205], v[48:51]
	v_mfma_f32_16x16x32_bf16 v[36:39], v[168:171], v[210:213], v[36:39]
	v_mfma_f32_16x16x32_bf16 v[32:35], v[194:197], v[210:213], v[32:35]
	v_mfma_f32_16x16x32_bf16 v[20:23], v[168:171], v[218:221], v[20:23]
	v_mfma_f32_16x16x32_bf16 v[16:19], v[194:197], v[218:221], v[16:19]
	v_mfma_f32_16x16x32_bf16 v[4:7], v[168:171], v[226:229], v[4:7]
	v_mfma_f32_16x16x32_bf16 v[0:3], v[194:197], v[226:229], v[0:3]
	v_mfma_f32_16x16x32_bf16 v[52:55], v[190:193], v[206:209], v[52:55]
	v_mfma_f32_16x16x32_bf16 v[48:51], v[198:201], v[206:209], v[48:51]
	v_mfma_f32_16x16x32_bf16 v[36:39], v[190:193], v[214:217], v[36:39]
	v_mfma_f32_16x16x32_bf16 v[32:35], v[198:201], v[214:217], v[32:35]
	v_mfma_f32_16x16x32_bf16 v[20:23], v[190:193], v[222:225], v[20:23]
	v_mfma_f32_16x16x32_bf16 v[16:19], v[198:201], v[222:225], v[16:19]
	v_mfma_f32_16x16x32_bf16 v[4:7], v[190:193], v[230:233], v[4:7]
	v_mfma_f32_16x16x32_bf16 v[0:3], v[198:201], v[230:233], v[0:3]
	s_setprio 0
	s_barrier
	s_add_i32 s88, s88, 2
	s_add_u32 s86, s86, 0x100
	s_addc_u32 s87, s87, 0
	s_add_u32 s8, s8, 0x100
	s_addc_u32 s9, s9, 0
	s_cmp_gt_u32 s88, 13
	s_cbranch_scc1 .LBB0_609

.LBB0_1604:
	ds_read_b128 v[136:139], v145
	ds_read_b128 v[150:153], v145 offset:1024
	ds_read_b128 v[154:157], v145 offset:2048
	ds_read_b128 v[158:161], v145 offset:3072
	ds_read_b128 v[162:165], v146
	ds_read_b128 v[166:169], v146 offset:1024
	ds_read_b128 v[170:173], v146 offset:2048
	ds_read_b128 v[174:177], v146 offset:3072
	s_add_i32 s89, s48, 2
	s_add_u32 s49, s46, 0xfffc0080
	s_addc_u32 s60, s47, -1
	s_cmp_eq_u32 s31, s48
	s_cselect_b32 s48, s40, s35
	s_cselect_b32 s61, s39, s60
	s_cselect_b32 s60, s38, s49
	s_cselect_b32 s49, s41, s37
	v_lshl_add_u64 v[140:141], s[46:47], 0, v[134:135]
	s_add_i32 m0, s45, 0xc000
	ds_read_b128 v[184:187], v147
	ds_read_b128 v[188:191], v147 offset:1024
	ds_read_b128 v[192:195], v147 offset:2048
	ds_read_b128 v[196:199], v147 offset:3072
	ds_read_b128 v[200:203], v147 offset:4096
	ds_read_b128 v[204:207], v147 offset:5120
	ds_read_b128 v[208:211], v147 offset:6144
	ds_read_b128 v[212:215], v147 offset:7168
	global_load_lds_dwordx4 v[140:141], off
	v_lshl_add_u64 v[140:141], s[46:47], 0, v[132:133]
	s_add_i32 m0, s45, 0xe000
	s_nop 0
	global_load_lds_dwordx4 v[140:141], off
	s_waitcnt vmcnt(8)
	s_waitcnt lgkmcnt(0)
	s_barrier
	s_setprio 1
	s_waitcnt lgkmcnt(0)
	v_mfma_f32_16x16x32_bf16 v[124:127], v[136:139], v[184:187], v[124:127]
	v_mfma_f32_16x16x32_bf16 v[120:123], v[154:157], v[184:187], v[120:123]
	v_mfma_f32_16x16x32_bf16 v[116:119], v[136:139], v[192:195], v[116:119]
	v_mfma_f32_16x16x32_bf16 v[112:115], v[154:157], v[192:195], v[112:115]
	v_mfma_f32_16x16x32_bf16 v[104:107], v[136:139], v[200:203], v[104:107]
	v_mfma_f32_16x16x32_bf16 v[96:99], v[154:157], v[200:203], v[96:99]
	v_mfma_f32_16x16x32_bf16 v[88:91], v[136:139], v[208:211], v[88:91]
	v_mfma_f32_16x16x32_bf16 v[80:83], v[154:157], v[208:211], v[80:83]
	v_mfma_f32_16x16x32_bf16 v[124:127], v[150:153], v[188:191], v[124:127]
	v_mfma_f32_16x16x32_bf16 v[120:123], v[158:161], v[188:191], v[120:123]
	v_mfma_f32_16x16x32_bf16 v[116:119], v[150:153], v[196:199], v[116:119]
	v_mfma_f32_16x16x32_bf16 v[112:115], v[158:161], v[196:199], v[112:115]
	v_mfma_f32_16x16x32_bf16 v[104:107], v[150:153], v[204:207], v[104:107]
	v_mfma_f32_16x16x32_bf16 v[96:99], v[158:161], v[204:207], v[96:99]
	v_mfma_f32_16x16x32_bf16 v[88:91], v[150:153], v[212:215], v[88:91]
	v_mfma_f32_16x16x32_bf16 v[80:83], v[158:161], v[212:215], v[80:83]
	v_mfma_f32_16x16x32_bf16 v[108:111], v[162:165], v[184:187], v[108:111]
	v_mfma_f32_16x16x32_bf16 v[100:103], v[170:173], v[184:187], v[100:103]
	v_mfma_f32_16x16x32_bf16 v[92:95], v[162:165], v[192:195], v[92:95]
	v_mfma_f32_16x16x32_bf16 v[84:87], v[170:173], v[192:195], v[84:87]
	v_mfma_f32_16x16x32_bf16 v[76:79], v[162:165], v[200:203], v[76:79]
	v_mfma_f32_16x16x32_bf16 v[72:75], v[170:173], v[200:203], v[72:75]
	v_mfma_f32_16x16x32_bf16 v[68:71], v[162:165], v[208:211], v[68:71]
	v_mfma_f32_16x16x32_bf16 v[64:67], v[170:173], v[208:211], v[64:67]
	v_mfma_f32_16x16x32_bf16 v[108:111], v[166:169], v[188:191], v[108:111]
	v_mfma_f32_16x16x32_bf16 v[100:103], v[174:177], v[188:191], v[100:103]
	v_mfma_f32_16x16x32_bf16 v[92:95], v[166:169], v[196:199], v[92:95]
	v_mfma_f32_16x16x32_bf16 v[84:87], v[174:177], v[196:199], v[84:87]
	v_mfma_f32_16x16x32_bf16 v[76:79], v[166:169], v[204:207], v[76:79]
	v_mfma_f32_16x16x32_bf16 v[72:75], v[174:177], v[204:207], v[72:75]
	v_mfma_f32_16x16x32_bf16 v[68:71], v[166:169], v[212:215], v[68:71]
	v_mfma_f32_16x16x32_bf16 v[64:67], v[174:177], v[212:215], v[64:67]
	s_setprio 0
	s_barrier
	s_add_i32 s76, s85, s63
	v_lshl_add_u64 v[140:141], s[48:49], 0, v[128:129]
	s_mov_b32 m0, s76
	ds_read_b128 v[184:187], v147 offset:16384
	ds_read_b128 v[188:191], v147 offset:17408
	ds_read_b128 v[192:195], v147 offset:18432
	ds_read_b128 v[196:199], v147 offset:19456
	ds_read_b128 v[200:203], v147 offset:20480
	ds_read_b128 v[204:207], v147 offset:21504
	ds_read_b128 v[208:211], v147 offset:22528
	ds_read_b128 v[212:215], v147 offset:23552
	global_load_lds_dwordx4 v[140:141], off
	s_add_i32 m0, s76, 0x2000
	s_add_u32 s90, s48, 0x40000
	v_lshl_add_u64 v[178:179], s[48:49], 0, v[130:131]
	s_addc_u32 s91, s49, 0
	s_add_i32 s76, s86, s63
	global_load_lds_dwordx4 v[178:179], off
	v_lshl_add_u64 v[216:217], s[90:91], 0, v[128:129]
	s_mov_b32 m0, s76
	v_lshl_add_u64 v[218:219], s[60:61], 0, v[130:131]
	global_load_lds_dwordx4 v[216:217], off
	v_lshl_add_u64 v[216:217], s[90:91], 0, v[130:131]
	s_add_i32 m0, s76, 0x2000
	s_nop 0
	global_load_lds_dwordx4 v[216:217], off
	v_lshl_add_u64 v[216:217], s[60:61], 0, v[128:129]
	s_mov_b32 m0, s45
	s_nop 0
	global_load_lds_dwordx4 v[216:217], off
	s_mov_b32 m0, s64
	s_nop 0
	global_load_lds_dwordx4 v[218:219], off
	s_waitcnt vmcnt(8)
	s_waitcnt lgkmcnt(0)
	s_barrier
	s_setprio 1
	s_waitcnt lgkmcnt(0)
	v_mfma_f32_16x16x32_bf16 v[60:63], v[136:139], v[184:187], v[60:63]
	v_mfma_f32_16x16x32_bf16 v[56:59], v[154:157], v[184:187], v[56:59]
	v_mfma_f32_16x16x32_bf16 v[52:55], v[136:139], v[192:195], v[52:55]
	v_mfma_f32_16x16x32_bf16 v[48:51], v[154:157], v[192:195], v[48:51]
	v_mfma_f32_16x16x32_bf16 v[40:43], v[136:139], v[200:203], v[40:43]
	v_mfma_f32_16x16x32_bf16 v[32:35], v[154:157], v[200:203], v[32:35]
	v_mfma_f32_16x16x32_bf16 v[24:27], v[136:139], v[208:211], v[24:27]
	v_mfma_f32_16x16x32_bf16 v[16:19], v[154:157], v[208:211], v[16:19]
	v_mfma_f32_16x16x32_bf16 v[60:63], v[150:153], v[188:191], v[60:63]
	v_mfma_f32_16x16x32_bf16 v[56:59], v[158:161], v[188:191], v[56:59]
	v_mfma_f32_16x16x32_bf16 v[52:55], v[150:153], v[196:199], v[52:55]
	v_mfma_f32_16x16x32_bf16 v[48:51], v[158:161], v[196:199], v[48:51]
	v_mfma_f32_16x16x32_bf16 v[40:43], v[150:153], v[204:207], v[40:43]
	v_mfma_f32_16x16x32_bf16 v[32:35], v[158:161], v[204:207], v[32:35]
	v_mfma_f32_16x16x32_bf16 v[24:27], v[150:153], v[212:215], v[24:27]
	v_mfma_f32_16x16x32_bf16 v[16:19], v[158:161], v[212:215], v[16:19]
	v_mfma_f32_16x16x32_bf16 v[44:47], v[162:165], v[184:187], v[44:47]
	v_mfma_f32_16x16x32_bf16 v[36:39], v[170:173], v[184:187], v[36:39]
	v_mfma_f32_16x16x32_bf16 v[28:31], v[162:165], v[192:195], v[28:31]
	v_mfma_f32_16x16x32_bf16 v[20:23], v[170:173], v[192:195], v[20:23]
	v_mfma_f32_16x16x32_bf16 v[12:15], v[162:165], v[200:203], v[12:15]
	v_mfma_f32_16x16x32_bf16 v[8:11], v[170:173], v[200:203], v[8:11]
	v_mfma_f32_16x16x32_bf16 v[4:7], v[162:165], v[208:211], v[4:7]
	v_mfma_f32_16x16x32_bf16 v[0:3], v[170:173], v[208:211], v[0:3]
	v_mfma_f32_16x16x32_bf16 v[44:47], v[166:169], v[188:191], v[44:47]
	v_mfma_f32_16x16x32_bf16 v[36:39], v[174:177], v[188:191], v[36:39]
	v_mfma_f32_16x16x32_bf16 v[28:31], v[166:169], v[196:199], v[28:31]
	v_mfma_f32_16x16x32_bf16 v[20:23], v[174:177], v[196:199], v[20:23]
	v_mfma_f32_16x16x32_bf16 v[12:15], v[166:169], v[204:207], v[12:15]
	v_mfma_f32_16x16x32_bf16 v[8:11], v[174:177], v[204:207], v[8:11]
	v_mfma_f32_16x16x32_bf16 v[4:7], v[166:169], v[212:215], v[4:7]
	v_mfma_f32_16x16x32_bf16 v[0:3], v[174:177], v[212:215], v[0:3]
	s_setprio 0
	s_barrier
	s_add_i32 s76, 0, 0x18000
	v_add_u32_e32 v149, s76, v143
	s_add_i32 s79, 0, 0x1c000
	ds_read_b128 v[136:139], v149
	ds_read_b128 v[150:153], v149 offset:1024
	ds_read_b128 v[154:157], v149 offset:2048
	ds_read_b128 v[158:161], v149 offset:3072
	v_add_u32_e32 v149, s79, v143
	ds_read_b128 v[162:165], v149
	ds_read_b128 v[166:169], v149 offset:1024
	ds_read_b128 v[170:173], v149 offset:2048
	ds_read_b128 v[174:177], v149 offset:3072
	s_add_u32 s60, s60, 0x40000
	s_addc_u32 s61, s61, 0
	s_mov_b32 m0, s65
	v_lshl_add_u64 v[220:221], s[60:61], 0, v[128:129]
	ds_read_b128 v[184:187], v147 offset:32768
	ds_read_b128 v[188:191], v147 offset:33792
	ds_read_b128 v[192:195], v147 offset:34816
	ds_read_b128 v[196:199], v147 offset:35840
	ds_read_b128 v[200:203], v147 offset:36864
	ds_read_b128 v[204:207], v147 offset:37888
	ds_read_b128 v[208:211], v147 offset:38912
	ds_read_b128 v[212:215], v147 offset:39936
	global_load_lds_dwordx4 v[220:221], off
	v_lshl_add_u64 v[220:221], s[60:61], 0, v[130:131]
	s_mov_b32 m0, s66
	s_nop 0
	global_load_lds_dwordx4 v[220:221], off
	s_waitcnt vmcnt(8)
	s_waitcnt lgkmcnt(0)
	s_barrier
	s_setprio 1
	s_waitcnt lgkmcnt(0)
	v_mfma_f32_16x16x32_bf16 v[124:127], v[136:139], v[184:187], v[124:127]
	v_mfma_f32_16x16x32_bf16 v[120:123], v[154:157], v[184:187], v[120:123]
	v_mfma_f32_16x16x32_bf16 v[116:119], v[136:139], v[192:195], v[116:119]
	v_mfma_f32_16x16x32_bf16 v[112:115], v[154:157], v[192:195], v[112:115]
	v_mfma_f32_16x16x32_bf16 v[104:107], v[136:139], v[200:203], v[104:107]
	v_mfma_f32_16x16x32_bf16 v[96:99], v[154:157], v[200:203], v[96:99]
	v_mfma_f32_16x16x32_bf16 v[88:91], v[136:139], v[208:211], v[88:91]
	v_mfma_f32_16x16x32_bf16 v[80:83], v[154:157], v[208:211], v[80:83]
	v_mfma_f32_16x16x32_bf16 v[124:127], v[150:153], v[188:191], v[124:127]
	v_mfma_f32_16x16x32_bf16 v[120:123], v[158:161], v[188:191], v[120:123]
	v_mfma_f32_16x16x32_bf16 v[116:119], v[150:153], v[196:199], v[116:119]
	v_mfma_f32_16x16x32_bf16 v[112:115], v[158:161], v[196:199], v[112:115]
	v_mfma_f32_16x16x32_bf16 v[104:107], v[150:153], v[204:207], v[104:107]
	v_mfma_f32_16x16x32_bf16 v[96:99], v[158:161], v[204:207], v[96:99]
	v_mfma_f32_16x16x32_bf16 v[88:91], v[150:153], v[212:215], v[88:91]
	v_mfma_f32_16x16x32_bf16 v[80:83], v[158:161], v[212:215], v[80:83]
	v_mfma_f32_16x16x32_bf16 v[108:111], v[162:165], v[184:187], v[108:111]
	v_mfma_f32_16x16x32_bf16 v[100:103], v[170:173], v[184:187], v[100:103]
	v_mfma_f32_16x16x32_bf16 v[92:95], v[162:165], v[192:195], v[92:95]
	v_mfma_f32_16x16x32_bf16 v[84:87], v[170:173], v[192:195], v[84:87]
	v_mfma_f32_16x16x32_bf16 v[76:79], v[162:165], v[200:203], v[76:79]
	v_mfma_f32_16x16x32_bf16 v[72:75], v[170:173], v[200:203], v[72:75]
	v_mfma_f32_16x16x32_bf16 v[68:71], v[162:165], v[208:211], v[68:71]
	v_mfma_f32_16x16x32_bf16 v[64:67], v[170:173], v[208:211], v[64:67]
	v_mfma_f32_16x16x32_bf16 v[108:111], v[166:169], v[188:191], v[108:111]
	v_mfma_f32_16x16x32_bf16 v[100:103], v[174:177], v[188:191], v[100:103]
	v_mfma_f32_16x16x32_bf16 v[92:95], v[166:169], v[196:199], v[92:95]
	v_mfma_f32_16x16x32_bf16 v[84:87], v[174:177], v[196:199], v[84:87]
	v_mfma_f32_16x16x32_bf16 v[76:79], v[166:169], v[204:207], v[76:79]
	v_mfma_f32_16x16x32_bf16 v[72:75], v[174:177], v[204:207], v[72:75]
	v_mfma_f32_16x16x32_bf16 v[68:71], v[166:169], v[212:215], v[68:71]
	v_mfma_f32_16x16x32_bf16 v[64:67], v[174:177], v[212:215], v[64:67]
	s_setprio 0
	s_barrier
	s_add_i32 s60, s76, s63
	v_lshl_add_u64 v[140:141], v[140:141], 0, s[26:27]
	s_mov_b32 m0, s60
	ds_read_b128 v[184:187], v147 offset:49152
	ds_read_b128 v[188:191], v147 offset:50176
	ds_read_b128 v[192:195], v147 offset:51200
	ds_read_b128 v[196:199], v147 offset:52224
	ds_read_b128 v[200:203], v147 offset:53248
	ds_read_b128 v[204:207], v147 offset:54272
	ds_read_b128 v[208:211], v147 offset:55296
	ds_read_b128 v[212:215], v147 offset:56320
	global_load_lds_dwordx4 v[140:141], off
	s_add_i32 m0, s60, 0x2000
	s_add_u32 s48, s48, 0x40080
	v_lshl_add_u64 v[140:141], v[178:179], 0, s[26:27]
	s_addc_u32 s49, s49, 0
	s_add_i32 s60, s79, s63
	global_load_lds_dwordx4 v[140:141], off
	v_lshl_add_u64 v[140:141], s[48:49], 0, v[128:129]
	s_mov_b32 m0, s60
	s_nop 0
	global_load_lds_dwordx4 v[140:141], off
	v_lshl_add_u64 v[140:141], s[48:49], 0, v[130:131]
	s_add_i32 m0, s60, 0x2000
	s_nop 0
	global_load_lds_dwordx4 v[140:141], off
	v_lshl_add_u64 v[140:141], v[216:217], 0, s[26:27]
	s_mov_b32 m0, s69
	s_nop 0
	global_load_lds_dwordx4 v[140:141], off
	v_lshl_add_u64 v[140:141], v[218:219], 0, s[26:27]
	s_mov_b32 m0, s70
	s_nop 0
	global_load_lds_dwordx4 v[140:141], off
	s_waitcnt vmcnt(8)
	s_waitcnt lgkmcnt(0)
	s_barrier
	s_setprio 1
	s_waitcnt lgkmcnt(0)
	v_mfma_f32_16x16x32_bf16 v[60:63], v[136:139], v[184:187], v[60:63]
	v_mfma_f32_16x16x32_bf16 v[56:59], v[154:157], v[184:187], v[56:59]
	v_mfma_f32_16x16x32_bf16 v[52:55], v[136:139], v[192:195], v[52:55]
	v_mfma_f32_16x16x32_bf16 v[48:51], v[154:157], v[192:195], v[48:51]
	v_mfma_f32_16x16x32_bf16 v[40:43], v[136:139], v[200:203], v[40:43]
	v_mfma_f32_16x16x32_bf16 v[32:35], v[154:157], v[200:203], v[32:35]
	v_mfma_f32_16x16x32_bf16 v[24:27], v[136:139], v[208:211], v[24:27]
	v_mfma_f32_16x16x32_bf16 v[16:19], v[154:157], v[208:211], v[16:19]
	v_mfma_f32_16x16x32_bf16 v[60:63], v[150:153], v[188:191], v[60:63]
	v_mfma_f32_16x16x32_bf16 v[56:59], v[158:161], v[188:191], v[56:59]
	v_mfma_f32_16x16x32_bf16 v[52:55], v[150:153], v[196:199], v[52:55]
	v_mfma_f32_16x16x32_bf16 v[48:51], v[158:161], v[196:199], v[48:51]
	v_mfma_f32_16x16x32_bf16 v[40:43], v[150:153], v[204:207], v[40:43]
	v_mfma_f32_16x16x32_bf16 v[32:35], v[158:161], v[204:207], v[32:35]
	v_mfma_f32_16x16x32_bf16 v[24:27], v[150:153], v[212:215], v[24:27]
	v_mfma_f32_16x16x32_bf16 v[16:19], v[158:161], v[212:215], v[16:19]
	v_mfma_f32_16x16x32_bf16 v[44:47], v[162:165], v[184:187], v[44:47]
	v_mfma_f32_16x16x32_bf16 v[36:39], v[170:173], v[184:187], v[36:39]
	v_mfma_f32_16x16x32_bf16 v[28:31], v[162:165], v[192:195], v[28:31]
	v_mfma_f32_16x16x32_bf16 v[20:23], v[170:173], v[192:195], v[20:23]
	v_mfma_f32_16x16x32_bf16 v[12:15], v[162:165], v[200:203], v[12:15]
	v_mfma_f32_16x16x32_bf16 v[8:11], v[170:173], v[200:203], v[8:11]
	v_mfma_f32_16x16x32_bf16 v[4:7], v[162:165], v[208:211], v[4:7]
	v_mfma_f32_16x16x32_bf16 v[0:3], v[170:173], v[208:211], v[0:3]
	v_mfma_f32_16x16x32_bf16 v[44:47], v[166:169], v[188:191], v[44:47]
	v_mfma_f32_16x16x32_bf16 v[36:39], v[174:177], v[188:191], v[36:39]
	v_mfma_f32_16x16x32_bf16 v[28:31], v[166:169], v[196:199], v[28:31]
	v_mfma_f32_16x16x32_bf16 v[20:23], v[174:177], v[196:199], v[20:23]
	v_mfma_f32_16x16x32_bf16 v[12:15], v[166:169], v[204:207], v[12:15]
	v_mfma_f32_16x16x32_bf16 v[8:11], v[174:177], v[204:207], v[8:11]
	v_mfma_f32_16x16x32_bf16 v[4:7], v[166:169], v[212:215], v[4:7]
	v_mfma_f32_16x16x32_bf16 v[0:3], v[174:177], v[212:215], v[0:3]
	s_setprio 0
	s_barrier
	s_add_u32 s35, s35, 0x100
	s_addc_u32 s37, s37, 0
	s_add_u32 s46, s46, 0x100
	s_addc_u32 s47, s47, 0
	s_cmp_ge_i32 s89, s43
	s_mov_b32 s48, s89
	s_cbranch_scc0 .LBB0_1604
	s_and_b64 vcc, exec, s[28:29]
	s_cbranch_vccz .LBB0_1607
	s_barrier

.LBB0_1828:
	ds_read_b128 v[136:139], v145
	ds_read_b128 v[150:153], v145 offset:1024
	ds_read_b128 v[154:157], v145 offset:2048
	ds_read_b128 v[158:161], v145 offset:3072
	ds_read_b128 v[162:165], v146
	ds_read_b128 v[166:169], v146 offset:1024
	ds_read_b128 v[170:173], v146 offset:2048
	ds_read_b128 v[174:177], v146 offset:3072
	s_add_i32 s90, s40, 2
	s_add_u32 s41, s38, 0xfff50080
	s_addc_u32 s42, s39, -1
	s_cmp_eq_u32 s31, s40
	s_cselect_b32 s40, s36, s88
	s_cselect_b32 s43, s35, s42
	s_cselect_b32 s42, s34, s41
	s_cselect_b32 s41, s37, s89
	v_lshl_add_u64 v[140:141], s[38:39], 0, v[134:135]
	s_add_i32 m0, s48, 0xc000
	ds_read_b128 v[184:187], v147
	ds_read_b128 v[188:191], v147 offset:1024
	ds_read_b128 v[192:195], v147 offset:2048
	ds_read_b128 v[196:199], v147 offset:3072
	ds_read_b128 v[200:203], v147 offset:4096
	ds_read_b128 v[204:207], v147 offset:5120
	ds_read_b128 v[208:211], v147 offset:6144
	ds_read_b128 v[212:215], v147 offset:7168
	global_load_lds_dwordx4 v[140:141], off
	v_lshl_add_u64 v[140:141], s[38:39], 0, v[132:133]
	s_add_i32 m0, s48, 0xe000
	s_nop 0
	global_load_lds_dwordx4 v[140:141], off
	s_waitcnt vmcnt(8)
	s_waitcnt lgkmcnt(0)
	s_barrier
	s_setprio 1
	s_waitcnt lgkmcnt(0)
	v_mfma_f32_16x16x32_bf16 v[124:127], v[136:139], v[184:187], v[124:127]
	v_mfma_f32_16x16x32_bf16 v[120:123], v[154:157], v[184:187], v[120:123]
	v_mfma_f32_16x16x32_bf16 v[108:111], v[136:139], v[192:195], v[108:111]
	v_mfma_f32_16x16x32_bf16 v[104:107], v[154:157], v[192:195], v[104:107]
	v_mfma_f32_16x16x32_bf16 v[92:95], v[136:139], v[200:203], v[92:95]
	v_mfma_f32_16x16x32_bf16 v[88:91], v[154:157], v[200:203], v[88:91]
	v_mfma_f32_16x16x32_bf16 v[76:79], v[136:139], v[208:211], v[76:79]
	v_mfma_f32_16x16x32_bf16 v[72:75], v[154:157], v[208:211], v[72:75]
	v_mfma_f32_16x16x32_bf16 v[124:127], v[150:153], v[188:191], v[124:127]
	v_mfma_f32_16x16x32_bf16 v[120:123], v[158:161], v[188:191], v[120:123]
	v_mfma_f32_16x16x32_bf16 v[108:111], v[150:153], v[196:199], v[108:111]
	v_mfma_f32_16x16x32_bf16 v[104:107], v[158:161], v[196:199], v[104:107]
	v_mfma_f32_16x16x32_bf16 v[92:95], v[150:153], v[204:207], v[92:95]
	v_mfma_f32_16x16x32_bf16 v[88:91], v[158:161], v[204:207], v[88:91]
	v_mfma_f32_16x16x32_bf16 v[76:79], v[150:153], v[212:215], v[76:79]
	v_mfma_f32_16x16x32_bf16 v[72:75], v[158:161], v[212:215], v[72:75]
	v_mfma_f32_16x16x32_bf16 v[116:119], v[162:165], v[184:187], v[116:119]
	v_mfma_f32_16x16x32_bf16 v[112:115], v[170:173], v[184:187], v[112:115]
	v_mfma_f32_16x16x32_bf16 v[100:103], v[162:165], v[192:195], v[100:103]
	v_mfma_f32_16x16x32_bf16 v[96:99], v[170:173], v[192:195], v[96:99]
	v_mfma_f32_16x16x32_bf16 v[84:87], v[162:165], v[200:203], v[84:87]
	v_mfma_f32_16x16x32_bf16 v[80:83], v[170:173], v[200:203], v[80:83]
	v_mfma_f32_16x16x32_bf16 v[68:71], v[162:165], v[208:211], v[68:71]
	v_mfma_f32_16x16x32_bf16 v[64:67], v[170:173], v[208:211], v[64:67]
	v_mfma_f32_16x16x32_bf16 v[116:119], v[166:169], v[188:191], v[116:119]
	v_mfma_f32_16x16x32_bf16 v[112:115], v[174:177], v[188:191], v[112:115]
	v_mfma_f32_16x16x32_bf16 v[100:103], v[166:169], v[196:199], v[100:103]
	v_mfma_f32_16x16x32_bf16 v[96:99], v[174:177], v[196:199], v[96:99]
	v_mfma_f32_16x16x32_bf16 v[84:87], v[166:169], v[204:207], v[84:87]
	v_mfma_f32_16x16x32_bf16 v[80:83], v[174:177], v[204:207], v[80:83]
	v_mfma_f32_16x16x32_bf16 v[68:71], v[166:169], v[212:215], v[68:71]
	v_mfma_f32_16x16x32_bf16 v[64:67], v[174:177], v[212:215], v[64:67]
	s_setprio 0
	s_barrier
	s_add_i32 s76, s75, s47
	v_lshl_add_u64 v[140:141], s[40:41], 0, v[128:129]
	s_mov_b32 m0, s76
	ds_read_b128 v[184:187], v147 offset:16384
	ds_read_b128 v[188:191], v147 offset:17408
	ds_read_b128 v[192:195], v147 offset:18432
	ds_read_b128 v[196:199], v147 offset:19456
	ds_read_b128 v[200:203], v147 offset:20480
	ds_read_b128 v[204:207], v147 offset:21504
	ds_read_b128 v[208:211], v147 offset:22528
	ds_read_b128 v[212:215], v147 offset:23552
	global_load_lds_dwordx4 v[140:141], off
	s_add_i32 m0, s76, 0x2000
	s_add_u32 s92, s40, 0xb0000
	v_lshl_add_u64 v[178:179], s[40:41], 0, v[130:131]
	s_addc_u32 s93, s41, 0
	s_add_i32 s76, s78, s47
	global_load_lds_dwordx4 v[178:179], off
	v_lshl_add_u64 v[216:217], s[92:93], 0, v[128:129]
	s_mov_b32 m0, s76
	v_lshl_add_u64 v[218:219], s[42:43], 0, v[130:131]
	global_load_lds_dwordx4 v[216:217], off
	v_lshl_add_u64 v[216:217], s[92:93], 0, v[130:131]
	s_add_i32 m0, s76, 0x2000
	s_nop 0
	global_load_lds_dwordx4 v[216:217], off
	v_lshl_add_u64 v[216:217], s[42:43], 0, v[128:129]
	s_mov_b32 m0, s48
	s_nop 0
	global_load_lds_dwordx4 v[216:217], off
	s_mov_b32 m0, s49
	s_nop 0
	global_load_lds_dwordx4 v[218:219], off
	s_waitcnt vmcnt(8)
	s_waitcnt lgkmcnt(0)
	s_barrier
	s_setprio 1
	s_waitcnt lgkmcnt(0)
	v_mfma_f32_16x16x32_bf16 v[60:63], v[136:139], v[184:187], v[60:63]
	v_mfma_f32_16x16x32_bf16 v[56:59], v[154:157], v[184:187], v[56:59]
	v_mfma_f32_16x16x32_bf16 v[44:47], v[136:139], v[192:195], v[44:47]
	v_mfma_f32_16x16x32_bf16 v[40:43], v[154:157], v[192:195], v[40:43]
	v_mfma_f32_16x16x32_bf16 v[28:31], v[136:139], v[200:203], v[28:31]
	v_mfma_f32_16x16x32_bf16 v[24:27], v[154:157], v[200:203], v[24:27]
	v_mfma_f32_16x16x32_bf16 v[12:15], v[136:139], v[208:211], v[12:15]
	v_mfma_f32_16x16x32_bf16 v[8:11], v[154:157], v[208:211], v[8:11]
	v_mfma_f32_16x16x32_bf16 v[60:63], v[150:153], v[188:191], v[60:63]
	v_mfma_f32_16x16x32_bf16 v[56:59], v[158:161], v[188:191], v[56:59]
	v_mfma_f32_16x16x32_bf16 v[44:47], v[150:153], v[196:199], v[44:47]
	v_mfma_f32_16x16x32_bf16 v[40:43], v[158:161], v[196:199], v[40:43]
	v_mfma_f32_16x16x32_bf16 v[28:31], v[150:153], v[204:207], v[28:31]
	v_mfma_f32_16x16x32_bf16 v[24:27], v[158:161], v[204:207], v[24:27]
	v_mfma_f32_16x16x32_bf16 v[12:15], v[150:153], v[212:215], v[12:15]
	v_mfma_f32_16x16x32_bf16 v[8:11], v[158:161], v[212:215], v[8:11]
	v_mfma_f32_16x16x32_bf16 v[52:55], v[162:165], v[184:187], v[52:55]
	v_mfma_f32_16x16x32_bf16 v[48:51], v[170:173], v[184:187], v[48:51]
	v_mfma_f32_16x16x32_bf16 v[36:39], v[162:165], v[192:195], v[36:39]
	v_mfma_f32_16x16x32_bf16 v[32:35], v[170:173], v[192:195], v[32:35]
	v_mfma_f32_16x16x32_bf16 v[20:23], v[162:165], v[200:203], v[20:23]
	v_mfma_f32_16x16x32_bf16 v[16:19], v[170:173], v[200:203], v[16:19]
	v_mfma_f32_16x16x32_bf16 v[4:7], v[162:165], v[208:211], v[4:7]
	v_mfma_f32_16x16x32_bf16 v[0:3], v[170:173], v[208:211], v[0:3]
	v_mfma_f32_16x16x32_bf16 v[52:55], v[166:169], v[188:191], v[52:55]
	v_mfma_f32_16x16x32_bf16 v[48:51], v[174:177], v[188:191], v[48:51]
	v_mfma_f32_16x16x32_bf16 v[36:39], v[166:169], v[196:199], v[36:39]
	v_mfma_f32_16x16x32_bf16 v[32:35], v[174:177], v[196:199], v[32:35]
	v_mfma_f32_16x16x32_bf16 v[20:23], v[166:169], v[204:207], v[20:23]
	v_mfma_f32_16x16x32_bf16 v[16:19], v[174:177], v[204:207], v[16:19]
	v_mfma_f32_16x16x32_bf16 v[4:7], v[166:169], v[212:215], v[4:7]
	v_mfma_f32_16x16x32_bf16 v[0:3], v[174:177], v[212:215], v[0:3]
	s_setprio 0
	s_barrier
	s_add_i32 s76, 0, 0x18000
	v_add_u32_e32 v149, s76, v143
	s_add_i32 s79, 0, 0x1c000
	ds_read_b128 v[136:139], v149
	ds_read_b128 v[150:153], v149 offset:1024
	ds_read_b128 v[154:157], v149 offset:2048
	ds_read_b128 v[158:161], v149 offset:3072
	v_add_u32_e32 v149, s79, v143
	ds_read_b128 v[162:165], v149
	ds_read_b128 v[166:169], v149 offset:1024
	ds_read_b128 v[170:173], v149 offset:2048
	ds_read_b128 v[174:177], v149 offset:3072
	s_add_u32 s42, s42, 0xb0000
	s_addc_u32 s43, s43, 0
	s_mov_b32 m0, s57
	v_lshl_add_u64 v[220:221], s[42:43], 0, v[128:129]
	ds_read_b128 v[184:187], v147 offset:32768
	ds_read_b128 v[188:191], v147 offset:33792
	ds_read_b128 v[192:195], v147 offset:34816
	ds_read_b128 v[196:199], v147 offset:35840
	ds_read_b128 v[200:203], v147 offset:36864
	ds_read_b128 v[204:207], v147 offset:37888
	ds_read_b128 v[208:211], v147 offset:38912
	ds_read_b128 v[212:215], v147 offset:39936
	global_load_lds_dwordx4 v[220:221], off
	v_lshl_add_u64 v[220:221], s[42:43], 0, v[130:131]
	s_mov_b32 m0, s59
	s_nop 0
	global_load_lds_dwordx4 v[220:221], off
	s_waitcnt vmcnt(8)
	s_waitcnt lgkmcnt(0)
	s_barrier
	s_setprio 1
	s_waitcnt lgkmcnt(0)
	v_mfma_f32_16x16x32_bf16 v[124:127], v[136:139], v[184:187], v[124:127]
	v_mfma_f32_16x16x32_bf16 v[120:123], v[154:157], v[184:187], v[120:123]
	v_mfma_f32_16x16x32_bf16 v[108:111], v[136:139], v[192:195], v[108:111]
	v_mfma_f32_16x16x32_bf16 v[104:107], v[154:157], v[192:195], v[104:107]
	v_mfma_f32_16x16x32_bf16 v[92:95], v[136:139], v[200:203], v[92:95]
	v_mfma_f32_16x16x32_bf16 v[88:91], v[154:157], v[200:203], v[88:91]
	v_mfma_f32_16x16x32_bf16 v[76:79], v[136:139], v[208:211], v[76:79]
	v_mfma_f32_16x16x32_bf16 v[72:75], v[154:157], v[208:211], v[72:75]
	v_mfma_f32_16x16x32_bf16 v[124:127], v[150:153], v[188:191], v[124:127]
	v_mfma_f32_16x16x32_bf16 v[120:123], v[158:161], v[188:191], v[120:123]
	v_mfma_f32_16x16x32_bf16 v[108:111], v[150:153], v[196:199], v[108:111]
	v_mfma_f32_16x16x32_bf16 v[104:107], v[158:161], v[196:199], v[104:107]
	v_mfma_f32_16x16x32_bf16 v[92:95], v[150:153], v[204:207], v[92:95]
	v_mfma_f32_16x16x32_bf16 v[88:91], v[158:161], v[204:207], v[88:91]
	v_mfma_f32_16x16x32_bf16 v[76:79], v[150:153], v[212:215], v[76:79]
	v_mfma_f32_16x16x32_bf16 v[72:75], v[158:161], v[212:215], v[72:75]
	v_mfma_f32_16x16x32_bf16 v[116:119], v[162:165], v[184:187], v[116:119]
	v_mfma_f32_16x16x32_bf16 v[112:115], v[170:173], v[184:187], v[112:115]
	v_mfma_f32_16x16x32_bf16 v[100:103], v[162:165], v[192:195], v[100:103]
	v_mfma_f32_16x16x32_bf16 v[96:99], v[170:173], v[192:195], v[96:99]
	v_mfma_f32_16x16x32_bf16 v[84:87], v[162:165], v[200:203], v[84:87]
	v_mfma_f32_16x16x32_bf16 v[80:83], v[170:173], v[200:203], v[80:83]
	v_mfma_f32_16x16x32_bf16 v[68:71], v[162:165], v[208:211], v[68:71]
	v_mfma_f32_16x16x32_bf16 v[64:67], v[170:173], v[208:211], v[64:67]
	v_mfma_f32_16x16x32_bf16 v[116:119], v[166:169], v[188:191], v[116:119]
	v_mfma_f32_16x16x32_bf16 v[112:115], v[174:177], v[188:191], v[112:115]
	v_mfma_f32_16x16x32_bf16 v[100:103], v[166:169], v[196:199], v[100:103]
	v_mfma_f32_16x16x32_bf16 v[96:99], v[174:177], v[196:199], v[96:99]
	v_mfma_f32_16x16x32_bf16 v[84:87], v[166:169], v[204:207], v[84:87]
	v_mfma_f32_16x16x32_bf16 v[80:83], v[174:177], v[204:207], v[80:83]
	v_mfma_f32_16x16x32_bf16 v[68:71], v[166:169], v[212:215], v[68:71]
	v_mfma_f32_16x16x32_bf16 v[64:67], v[174:177], v[212:215], v[64:67]
	s_setprio 0
	s_barrier
	s_add_i32 s42, s76, s47
	v_lshl_add_u64 v[140:141], v[140:141], 0, s[26:27]
	s_mov_b32 m0, s42
	ds_read_b128 v[184:187], v147 offset:49152
	ds_read_b128 v[188:191], v147 offset:50176
	ds_read_b128 v[192:195], v147 offset:51200
	ds_read_b128 v[196:199], v147 offset:52224
	ds_read_b128 v[200:203], v147 offset:53248
	ds_read_b128 v[204:207], v147 offset:54272
	ds_read_b128 v[208:211], v147 offset:55296
	ds_read_b128 v[212:215], v147 offset:56320
	global_load_lds_dwordx4 v[140:141], off
	s_add_i32 m0, s42, 0x2000
	s_add_u32 s40, s40, 0xb0080
	v_lshl_add_u64 v[140:141], v[178:179], 0, s[26:27]
	s_addc_u32 s41, s41, 0
	s_add_i32 s42, s79, s47
	global_load_lds_dwordx4 v[140:141], off
	v_lshl_add_u64 v[140:141], s[40:41], 0, v[128:129]
	s_mov_b32 m0, s42
	s_nop 0
	global_load_lds_dwordx4 v[140:141], off
	v_lshl_add_u64 v[140:141], s[40:41], 0, v[130:131]
	s_add_i32 m0, s42, 0x2000
	s_nop 0
	global_load_lds_dwordx4 v[140:141], off
	v_lshl_add_u64 v[140:141], v[216:217], 0, s[26:27]
	s_mov_b32 m0, s62
	s_nop 0
	global_load_lds_dwordx4 v[140:141], off
	v_lshl_add_u64 v[140:141], v[218:219], 0, s[26:27]
	s_mov_b32 m0, s63
	s_nop 0
	global_load_lds_dwordx4 v[140:141], off
	s_waitcnt vmcnt(8)
	s_waitcnt lgkmcnt(0)
	s_barrier
	s_setprio 1
	s_waitcnt lgkmcnt(0)
	v_mfma_f32_16x16x32_bf16 v[60:63], v[136:139], v[184:187], v[60:63]
	v_mfma_f32_16x16x32_bf16 v[56:59], v[154:157], v[184:187], v[56:59]
	v_mfma_f32_16x16x32_bf16 v[44:47], v[136:139], v[192:195], v[44:47]
	v_mfma_f32_16x16x32_bf16 v[40:43], v[154:157], v[192:195], v[40:43]
	v_mfma_f32_16x16x32_bf16 v[28:31], v[136:139], v[200:203], v[28:31]
	v_mfma_f32_16x16x32_bf16 v[24:27], v[154:157], v[200:203], v[24:27]
	v_mfma_f32_16x16x32_bf16 v[12:15], v[136:139], v[208:211], v[12:15]
	v_mfma_f32_16x16x32_bf16 v[8:11], v[154:157], v[208:211], v[8:11]
	v_mfma_f32_16x16x32_bf16 v[60:63], v[150:153], v[188:191], v[60:63]
	v_mfma_f32_16x16x32_bf16 v[56:59], v[158:161], v[188:191], v[56:59]
	v_mfma_f32_16x16x32_bf16 v[44:47], v[150:153], v[196:199], v[44:47]
	v_mfma_f32_16x16x32_bf16 v[40:43], v[158:161], v[196:199], v[40:43]
	v_mfma_f32_16x16x32_bf16 v[28:31], v[150:153], v[204:207], v[28:31]
	v_mfma_f32_16x16x32_bf16 v[24:27], v[158:161], v[204:207], v[24:27]
	v_mfma_f32_16x16x32_bf16 v[12:15], v[150:153], v[212:215], v[12:15]
	v_mfma_f32_16x16x32_bf16 v[8:11], v[158:161], v[212:215], v[8:11]
	v_mfma_f32_16x16x32_bf16 v[52:55], v[162:165], v[184:187], v[52:55]
	v_mfma_f32_16x16x32_bf16 v[48:51], v[170:173], v[184:187], v[48:51]
	v_mfma_f32_16x16x32_bf16 v[36:39], v[162:165], v[192:195], v[36:39]
	v_mfma_f32_16x16x32_bf16 v[32:35], v[170:173], v[192:195], v[32:35]
	v_mfma_f32_16x16x32_bf16 v[20:23], v[162:165], v[200:203], v[20:23]
	v_mfma_f32_16x16x32_bf16 v[16:19], v[170:173], v[200:203], v[16:19]
	v_mfma_f32_16x16x32_bf16 v[4:7], v[162:165], v[208:211], v[4:7]
	v_mfma_f32_16x16x32_bf16 v[0:3], v[170:173], v[208:211], v[0:3]
	v_mfma_f32_16x16x32_bf16 v[52:55], v[166:169], v[188:191], v[52:55]
	v_mfma_f32_16x16x32_bf16 v[48:51], v[174:177], v[188:191], v[48:51]
	v_mfma_f32_16x16x32_bf16 v[36:39], v[166:169], v[196:199], v[36:39]
	v_mfma_f32_16x16x32_bf16 v[32:35], v[174:177], v[196:199], v[32:35]
	v_mfma_f32_16x16x32_bf16 v[20:23], v[166:169], v[204:207], v[20:23]
	v_mfma_f32_16x16x32_bf16 v[16:19], v[174:177], v[204:207], v[16:19]
	v_mfma_f32_16x16x32_bf16 v[4:7], v[166:169], v[212:215], v[4:7]
	v_mfma_f32_16x16x32_bf16 v[0:3], v[174:177], v[212:215], v[0:3]
	s_setprio 0
	s_barrier
	s_add_u32 s88, s88, 0x100
	s_addc_u32 s89, s89, 0
	s_add_u32 s38, s38, 0x100
	s_addc_u32 s39, s39, 0
	s_cmp_ge_i32 s90, s87
	s_mov_b32 s40, s90
	s_cbranch_scc0 .LBB0_1828
	s_and_b64 vcc, exec, s[28:29]
	s_cbranch_vccz .LBB0_1831

.LBB0_2195:
	v_add_u32_e32 v141, s47, v147
	ds_read_b128 v[160:163], v141
	ds_read_b128 v[164:167], v141 offset:1024
	ds_read_b128 v[168:171], v141 offset:2048
	ds_read_b128 v[172:175], v141 offset:3072
	v_add_u32_e32 v141, s48, v147
	ds_read_b128 v[176:179], v141
	ds_read_b128 v[184:187], v141 offset:1024
	ds_read_b128 v[188:191], v141 offset:2048
	ds_read_b128 v[192:195], v141 offset:3072
	s_add_u32 s30, s8, 0xfffc0080
	s_addc_u32 s31, s9, -1
	s_and_b64 s[28:29], s[28:29], exec
	s_cselect_b32 s31, s23, s31
	s_cselect_b32 s30, s60, s30
	s_cselect_b32 s29, s21, s63
	s_cselect_b32 s28, s61, s62
	v_lshl_add_u64 v[144:145], s[8:9], 0, v[134:135]
	s_add_i32 m0, s38, 0xc000
	ds_read_b128 v[196:199], v149
	ds_read_b128 v[200:203], v149 offset:1024
	ds_read_b128 v[204:207], v149 offset:2048
	ds_read_b128 v[208:211], v149 offset:3072
	ds_read_b128 v[212:215], v149 offset:4096
	ds_read_b128 v[216:219], v149 offset:5120
	ds_read_b128 v[220:223], v149 offset:6144
	ds_read_b128 v[224:227], v149 offset:7168
	global_load_lds_dwordx4 v[144:145], off
	v_lshl_add_u64 v[144:145], s[8:9], 0, v[132:133]
	s_add_i32 m0, s38, 0xe000
	s_nop 0
	global_load_lds_dwordx4 v[144:145], off
	s_waitcnt vmcnt(8)
	s_waitcnt lgkmcnt(0)
	s_barrier
	s_setprio 1
	s_waitcnt lgkmcnt(0)
	v_mfma_f32_16x16x32_bf16 v[124:127], v[160:163], v[196:199], v[124:127]
	v_mfma_f32_16x16x32_bf16 v[120:123], v[168:171], v[196:199], v[120:123]
	v_mfma_f32_16x16x32_bf16 v[112:115], v[160:163], v[204:207], v[112:115]
	v_mfma_f32_16x16x32_bf16 v[104:107], v[168:171], v[204:207], v[104:107]
	v_mfma_f32_16x16x32_bf16 v[96:99], v[160:163], v[212:215], v[96:99]
	v_mfma_f32_16x16x32_bf16 v[88:91], v[168:171], v[212:215], v[88:91]
	v_mfma_f32_16x16x32_bf16 v[80:83], v[160:163], v[220:223], v[80:83]
	v_mfma_f32_16x16x32_bf16 v[72:75], v[168:171], v[220:223], v[72:75]
	v_mfma_f32_16x16x32_bf16 v[124:127], v[164:167], v[200:203], v[124:127]
	v_mfma_f32_16x16x32_bf16 v[120:123], v[172:175], v[200:203], v[120:123]
	v_mfma_f32_16x16x32_bf16 v[112:115], v[164:167], v[208:211], v[112:115]
	v_mfma_f32_16x16x32_bf16 v[104:107], v[172:175], v[208:211], v[104:107]
	v_mfma_f32_16x16x32_bf16 v[96:99], v[164:167], v[216:219], v[96:99]
	v_mfma_f32_16x16x32_bf16 v[88:91], v[172:175], v[216:219], v[88:91]
	v_mfma_f32_16x16x32_bf16 v[80:83], v[164:167], v[224:227], v[80:83]
	v_mfma_f32_16x16x32_bf16 v[72:75], v[172:175], v[224:227], v[72:75]
	v_mfma_f32_16x16x32_bf16 v[116:119], v[176:179], v[196:199], v[116:119]
	v_mfma_f32_16x16x32_bf16 v[108:111], v[188:191], v[196:199], v[108:111]
	v_mfma_f32_16x16x32_bf16 v[100:103], v[176:179], v[204:207], v[100:103]
	v_mfma_f32_16x16x32_bf16 v[92:95], v[188:191], v[204:207], v[92:95]
	v_mfma_f32_16x16x32_bf16 v[84:87], v[176:179], v[212:215], v[84:87]
	v_mfma_f32_16x16x32_bf16 v[76:79], v[188:191], v[212:215], v[76:79]
	v_mfma_f32_16x16x32_bf16 v[68:71], v[176:179], v[220:223], v[68:71]
	v_mfma_f32_16x16x32_bf16 v[64:67], v[188:191], v[220:223], v[64:67]
	v_mfma_f32_16x16x32_bf16 v[116:119], v[184:187], v[200:203], v[116:119]
	v_mfma_f32_16x16x32_bf16 v[108:111], v[192:195], v[200:203], v[108:111]
	v_mfma_f32_16x16x32_bf16 v[100:103], v[184:187], v[208:211], v[100:103]
	v_mfma_f32_16x16x32_bf16 v[92:95], v[192:195], v[208:211], v[92:95]
	v_mfma_f32_16x16x32_bf16 v[84:87], v[184:187], v[216:219], v[84:87]
	v_mfma_f32_16x16x32_bf16 v[76:79], v[192:195], v[216:219], v[76:79]
	v_mfma_f32_16x16x32_bf16 v[68:71], v[184:187], v[224:227], v[68:71]
	v_mfma_f32_16x16x32_bf16 v[64:67], v[192:195], v[224:227], v[64:67]
	s_setprio 0
	s_barrier
	s_add_i32 s65, s47, s36
	v_lshl_add_u64 v[144:145], s[28:29], 0, v[130:131]
	s_mov_b32 m0, s65
	ds_read_b128 v[196:199], v149 offset:16384
	ds_read_b128 v[200:203], v149 offset:17408
	ds_read_b128 v[204:207], v149 offset:18432
	ds_read_b128 v[208:211], v149 offset:19456
	ds_read_b128 v[212:215], v149 offset:20480
	ds_read_b128 v[216:219], v149 offset:21504
	ds_read_b128 v[220:223], v149 offset:22528
	ds_read_b128 v[224:227], v149 offset:23552
	global_load_lds_dwordx4 v[144:145], off
	s_add_i32 m0, s65, 0x2000
	s_add_u32 s66, s28, 0x40000
	v_lshl_add_u64 v[228:229], s[28:29], 0, v[128:129]
	s_addc_u32 s67, s29, 0
	s_add_i32 s65, s48, s36
	global_load_lds_dwordx4 v[228:229], off
	v_lshl_add_u64 v[230:231], s[66:67], 0, v[130:131]
	s_mov_b32 m0, s65
	v_lshl_add_u64 v[232:233], s[30:31], 0, v[128:129]
	global_load_lds_dwordx4 v[230:231], off
	v_lshl_add_u64 v[230:231], s[66:67], 0, v[128:129]
	s_add_i32 m0, s65, 0x2000
	s_nop 0
	global_load_lds_dwordx4 v[230:231], off
	v_lshl_add_u64 v[230:231], s[30:31], 0, v[130:131]
	s_mov_b32 m0, s38
	s_nop 0
	global_load_lds_dwordx4 v[230:231], off
	s_mov_b32 m0, s39
	s_nop 0
	global_load_lds_dwordx4 v[232:233], off
	s_waitcnt vmcnt(8)
	s_waitcnt lgkmcnt(0)
	s_barrier
	s_setprio 1
	s_waitcnt lgkmcnt(0)
	v_mfma_f32_16x16x32_bf16 v[60:63], v[160:163], v[196:199], v[60:63]
	v_mfma_f32_16x16x32_bf16 v[56:59], v[168:171], v[196:199], v[56:59]
	v_mfma_f32_16x16x32_bf16 v[48:51], v[160:163], v[204:207], v[48:51]
	v_mfma_f32_16x16x32_bf16 v[40:43], v[168:171], v[204:207], v[40:43]
	v_mfma_f32_16x16x32_bf16 v[32:35], v[160:163], v[212:215], v[32:35]
	v_mfma_f32_16x16x32_bf16 v[24:27], v[168:171], v[212:215], v[24:27]
	v_mfma_f32_16x16x32_bf16 v[16:19], v[160:163], v[220:223], v[16:19]
	v_mfma_f32_16x16x32_bf16 v[8:11], v[168:171], v[220:223], v[8:11]
	v_mfma_f32_16x16x32_bf16 v[60:63], v[164:167], v[200:203], v[60:63]
	v_mfma_f32_16x16x32_bf16 v[56:59], v[172:175], v[200:203], v[56:59]
	v_mfma_f32_16x16x32_bf16 v[48:51], v[164:167], v[208:211], v[48:51]
	v_mfma_f32_16x16x32_bf16 v[40:43], v[172:175], v[208:211], v[40:43]
	v_mfma_f32_16x16x32_bf16 v[32:35], v[164:167], v[216:219], v[32:35]
	v_mfma_f32_16x16x32_bf16 v[24:27], v[172:175], v[216:219], v[24:27]
	v_mfma_f32_16x16x32_bf16 v[16:19], v[164:167], v[224:227], v[16:19]
	v_mfma_f32_16x16x32_bf16 v[8:11], v[172:175], v[224:227], v[8:11]
	v_mfma_f32_16x16x32_bf16 v[52:55], v[176:179], v[196:199], v[52:55]
	v_mfma_f32_16x16x32_bf16 v[44:47], v[188:191], v[196:199], v[44:47]
	v_mfma_f32_16x16x32_bf16 v[36:39], v[176:179], v[204:207], v[36:39]
	v_mfma_f32_16x16x32_bf16 v[28:31], v[188:191], v[204:207], v[28:31]
	v_mfma_f32_16x16x32_bf16 v[20:23], v[176:179], v[212:215], v[20:23]
	v_mfma_f32_16x16x32_bf16 v[12:15], v[188:191], v[212:215], v[12:15]
	v_mfma_f32_16x16x32_bf16 v[4:7], v[176:179], v[220:223], v[4:7]
	v_mfma_f32_16x16x32_bf16 v[0:3], v[188:191], v[220:223], v[0:3]
	v_mfma_f32_16x16x32_bf16 v[52:55], v[184:187], v[200:203], v[52:55]
	v_mfma_f32_16x16x32_bf16 v[44:47], v[192:195], v[200:203], v[44:47]
	v_mfma_f32_16x16x32_bf16 v[36:39], v[184:187], v[208:211], v[36:39]
	v_mfma_f32_16x16x32_bf16 v[28:31], v[192:195], v[208:211], v[28:31]
	v_mfma_f32_16x16x32_bf16 v[20:23], v[184:187], v[216:219], v[20:23]
	v_mfma_f32_16x16x32_bf16 v[12:15], v[192:195], v[216:219], v[12:15]
	v_mfma_f32_16x16x32_bf16 v[4:7], v[184:187], v[224:227], v[4:7]
	v_mfma_f32_16x16x32_bf16 v[0:3], v[192:195], v[224:227], v[0:3]
	s_setprio 0
	s_barrier
	s_add_i32 s65, 0, 0x18000
	v_add_u32_e32 v141, s65, v147
	s_add_i32 s66, 0, 0x1c000
	ds_read_b128 v[160:163], v141
	ds_read_b128 v[164:167], v141 offset:1024
	ds_read_b128 v[168:171], v141 offset:2048
	ds_read_b128 v[172:175], v141 offset:3072
	v_add_u32_e32 v141, s66, v147
	ds_read_b128 v[176:179], v141
	ds_read_b128 v[184:187], v141 offset:1024
	ds_read_b128 v[188:191], v141 offset:2048
	ds_read_b128 v[192:195], v141 offset:3072
	s_add_u32 s30, s30, 0x40000
	s_addc_u32 s31, s31, 0
	s_mov_b32 m0, s40
	v_lshl_add_u64 v[234:235], s[30:31], 0, v[130:131]
	ds_read_b128 v[196:199], v149 offset:32768
	ds_read_b128 v[200:203], v149 offset:33792
	ds_read_b128 v[204:207], v149 offset:34816
	ds_read_b128 v[208:211], v149 offset:35840
	ds_read_b128 v[212:215], v149 offset:36864
	ds_read_b128 v[216:219], v149 offset:37888
	ds_read_b128 v[220:223], v149 offset:38912
	ds_read_b128 v[224:227], v149 offset:39936
	global_load_lds_dwordx4 v[234:235], off
	v_lshl_add_u64 v[234:235], s[30:31], 0, v[128:129]
	s_mov_b32 m0, s41
	s_nop 0
	global_load_lds_dwordx4 v[234:235], off
	s_waitcnt vmcnt(8)
	s_waitcnt lgkmcnt(0)
	s_barrier
	s_setprio 1
	s_waitcnt lgkmcnt(0)
	v_mfma_f32_16x16x32_bf16 v[124:127], v[160:163], v[196:199], v[124:127]
	v_mfma_f32_16x16x32_bf16 v[120:123], v[168:171], v[196:199], v[120:123]
	v_mfma_f32_16x16x32_bf16 v[112:115], v[160:163], v[204:207], v[112:115]
	v_mfma_f32_16x16x32_bf16 v[104:107], v[168:171], v[204:207], v[104:107]
	v_mfma_f32_16x16x32_bf16 v[96:99], v[160:163], v[212:215], v[96:99]
	v_mfma_f32_16x16x32_bf16 v[88:91], v[168:171], v[212:215], v[88:91]
	v_mfma_f32_16x16x32_bf16 v[80:83], v[160:163], v[220:223], v[80:83]
	v_mfma_f32_16x16x32_bf16 v[72:75], v[168:171], v[220:223], v[72:75]
	v_mfma_f32_16x16x32_bf16 v[124:127], v[164:167], v[200:203], v[124:127]
	v_mfma_f32_16x16x32_bf16 v[120:123], v[172:175], v[200:203], v[120:123]
	v_mfma_f32_16x16x32_bf16 v[112:115], v[164:167], v[208:211], v[112:115]
	v_mfma_f32_16x16x32_bf16 v[104:107], v[172:175], v[208:211], v[104:107]
	v_mfma_f32_16x16x32_bf16 v[96:99], v[164:167], v[216:219], v[96:99]
	v_mfma_f32_16x16x32_bf16 v[88:91], v[172:175], v[216:219], v[88:91]
	v_mfma_f32_16x16x32_bf16 v[80:83], v[164:167], v[224:227], v[80:83]
	v_mfma_f32_16x16x32_bf16 v[72:75], v[172:175], v[224:227], v[72:75]
	v_mfma_f32_16x16x32_bf16 v[116:119], v[176:179], v[196:199], v[116:119]
	v_mfma_f32_16x16x32_bf16 v[108:111], v[188:191], v[196:199], v[108:111]
	v_mfma_f32_16x16x32_bf16 v[100:103], v[176:179], v[204:207], v[100:103]
	v_mfma_f32_16x16x32_bf16 v[92:95], v[188:191], v[204:207], v[92:95]
	v_mfma_f32_16x16x32_bf16 v[84:87], v[176:179], v[212:215], v[84:87]
	v_mfma_f32_16x16x32_bf16 v[76:79], v[188:191], v[212:215], v[76:79]
	v_mfma_f32_16x16x32_bf16 v[68:71], v[176:179], v[220:223], v[68:71]
	v_mfma_f32_16x16x32_bf16 v[64:67], v[188:191], v[220:223], v[64:67]
	v_mfma_f32_16x16x32_bf16 v[116:119], v[184:187], v[200:203], v[116:119]
	v_mfma_f32_16x16x32_bf16 v[108:111], v[192:195], v[200:203], v[108:111]
	v_mfma_f32_16x16x32_bf16 v[100:103], v[184:187], v[208:211], v[100:103]
	v_mfma_f32_16x16x32_bf16 v[92:95], v[192:195], v[208:211], v[92:95]
	v_mfma_f32_16x16x32_bf16 v[84:87], v[184:187], v[216:219], v[84:87]
	v_mfma_f32_16x16x32_bf16 v[76:79], v[192:195], v[216:219], v[76:79]
	v_mfma_f32_16x16x32_bf16 v[68:71], v[184:187], v[224:227], v[68:71]
	v_mfma_f32_16x16x32_bf16 v[64:67], v[192:195], v[224:227], v[64:67]
	s_setprio 0
	s_barrier
	s_add_i32 s30, s65, s36
	v_lshl_add_u64 v[144:145], v[144:145], 0, s[16:17]
	s_mov_b32 m0, s30
	ds_read_b128 v[196:199], v149 offset:49152
	ds_read_b128 v[200:203], v149 offset:50176
	ds_read_b128 v[204:207], v149 offset:51200
	ds_read_b128 v[208:211], v149 offset:52224
	ds_read_b128 v[212:215], v149 offset:53248
	ds_read_b128 v[216:219], v149 offset:54272
	ds_read_b128 v[220:223], v149 offset:55296
	ds_read_b128 v[224:227], v149 offset:56320
	global_load_lds_dwordx4 v[144:145], off
	s_add_i32 m0, s30, 0x2000
	s_add_u32 s28, s28, 0x40080
	v_lshl_add_u64 v[144:145], v[228:229], 0, s[16:17]
	s_addc_u32 s29, s29, 0
	s_add_i32 s30, s66, s36
	global_load_lds_dwordx4 v[144:145], off
	v_lshl_add_u64 v[144:145], s[28:29], 0, v[130:131]
	s_mov_b32 m0, s30
	s_nop 0
	global_load_lds_dwordx4 v[144:145], off
	v_lshl_add_u64 v[144:145], s[28:29], 0, v[128:129]
	s_add_i32 m0, s30, 0x2000
	s_nop 0
	global_load_lds_dwordx4 v[144:145], off
	v_lshl_add_u64 v[144:145], v[230:231], 0, s[16:17]
	s_mov_b32 m0, s43
	s_nop 0
	global_load_lds_dwordx4 v[144:145], off
	v_lshl_add_u64 v[144:145], v[232:233], 0, s[16:17]
	s_mov_b32 m0, s44
	s_nop 0
	global_load_lds_dwordx4 v[144:145], off
	s_waitcnt vmcnt(8)
	s_waitcnt lgkmcnt(0)
	s_barrier
	s_setprio 1
	s_waitcnt lgkmcnt(0)
	v_mfma_f32_16x16x32_bf16 v[60:63], v[160:163], v[196:199], v[60:63]
	v_mfma_f32_16x16x32_bf16 v[56:59], v[168:171], v[196:199], v[56:59]
	v_mfma_f32_16x16x32_bf16 v[48:51], v[160:163], v[204:207], v[48:51]
	v_mfma_f32_16x16x32_bf16 v[40:43], v[168:171], v[204:207], v[40:43]
	v_mfma_f32_16x16x32_bf16 v[32:35], v[160:163], v[212:215], v[32:35]
	v_mfma_f32_16x16x32_bf16 v[24:27], v[168:171], v[212:215], v[24:27]
	v_mfma_f32_16x16x32_bf16 v[16:19], v[160:163], v[220:223], v[16:19]
	v_mfma_f32_16x16x32_bf16 v[8:11], v[168:171], v[220:223], v[8:11]
	v_mfma_f32_16x16x32_bf16 v[60:63], v[164:167], v[200:203], v[60:63]
	v_mfma_f32_16x16x32_bf16 v[56:59], v[172:175], v[200:203], v[56:59]
	v_mfma_f32_16x16x32_bf16 v[48:51], v[164:167], v[208:211], v[48:51]
	v_mfma_f32_16x16x32_bf16 v[40:43], v[172:175], v[208:211], v[40:43]
	v_mfma_f32_16x16x32_bf16 v[32:35], v[164:167], v[216:219], v[32:35]
	v_mfma_f32_16x16x32_bf16 v[24:27], v[172:175], v[216:219], v[24:27]
	v_mfma_f32_16x16x32_bf16 v[16:19], v[164:167], v[224:227], v[16:19]
	v_mfma_f32_16x16x32_bf16 v[8:11], v[172:175], v[224:227], v[8:11]
	v_mfma_f32_16x16x32_bf16 v[52:55], v[176:179], v[196:199], v[52:55]
	v_mfma_f32_16x16x32_bf16 v[44:47], v[188:191], v[196:199], v[44:47]
	v_mfma_f32_16x16x32_bf16 v[36:39], v[176:179], v[204:207], v[36:39]
	v_mfma_f32_16x16x32_bf16 v[28:31], v[188:191], v[204:207], v[28:31]
	v_mfma_f32_16x16x32_bf16 v[20:23], v[176:179], v[212:215], v[20:23]
	v_mfma_f32_16x16x32_bf16 v[12:15], v[188:191], v[212:215], v[12:15]
	v_mfma_f32_16x16x32_bf16 v[4:7], v[176:179], v[220:223], v[4:7]
	v_mfma_f32_16x16x32_bf16 v[0:3], v[188:191], v[220:223], v[0:3]
	v_mfma_f32_16x16x32_bf16 v[52:55], v[184:187], v[200:203], v[52:55]
	v_mfma_f32_16x16x32_bf16 v[44:47], v[192:195], v[200:203], v[44:47]
	v_mfma_f32_16x16x32_bf16 v[36:39], v[184:187], v[208:211], v[36:39]
	v_mfma_f32_16x16x32_bf16 v[28:31], v[192:195], v[208:211], v[28:31]
	v_mfma_f32_16x16x32_bf16 v[20:23], v[184:187], v[216:219], v[20:23]
	v_mfma_f32_16x16x32_bf16 v[12:15], v[192:195], v[216:219], v[12:15]
	v_mfma_f32_16x16x32_bf16 v[4:7], v[184:187], v[224:227], v[4:7]
	v_mfma_f32_16x16x32_bf16 v[0:3], v[192:195], v[224:227], v[0:3]
	s_setprio 0
	s_barrier
	s_add_i32 s64, s64, 2
	s_add_u32 s62, s62, 0x100
	s_addc_u32 s63, s63, 0
	s_add_u32 s8, s8, 0x100
	s_addc_u32 s9, s9, 0
	s_cmp_gt_u32 s64, 13
	s_cbranch_scc1 .LBB0_2198

.LBB0_2325:
	ds_read_b128 v[164:167], v131
	ds_read_b128 v[168:171], v131 offset:1024
	ds_read_b128 v[172:175], v131 offset:2048
	ds_read_b128 v[176:179], v131 offset:3072
	ds_read_b128 v[184:187], v162
	ds_read_b128 v[188:191], v162 offset:1024
	ds_read_b128 v[192:195], v162 offset:2048
	ds_read_b128 v[196:199], v162 offset:3072
	s_add_u32 s24, s22, 0xfffe8080
	s_addc_u32 s25, s23, -1
	s_cmp_eq_u32 s60, 2
	s_cselect_b32 s27, s9, s25
	s_cselect_b32 s26, s8, s24
	s_cselect_b32 s25, s21, s59
	s_cselect_b32 s24, s20, s57
	v_lshl_add_u64 v[232:233], s[22:23], 0, v[144:145]
	s_add_i32 m0, s34, 0xc000
	ds_read_b128 v[200:203], v163
	ds_read_b128 v[204:207], v163 offset:1024
	ds_read_b128 v[208:211], v163 offset:2048
	ds_read_b128 v[212:215], v163 offset:3072
	ds_read_b128 v[216:219], v163 offset:4096
	ds_read_b128 v[220:223], v163 offset:5120
	ds_read_b128 v[224:227], v163 offset:6144
	ds_read_b128 v[228:231], v163 offset:7168
	global_load_lds_dwordx4 v[232:233], off
	v_lshl_add_u64 v[232:233], s[22:23], 0, v[142:143]
	s_add_i32 m0, s34, 0xe000
	s_nop 0
	global_load_lds_dwordx4 v[232:233], off
	s_waitcnt vmcnt(8)
	s_waitcnt lgkmcnt(0)
	s_barrier
	s_setprio 1
	s_waitcnt lgkmcnt(0)
	v_mfma_f32_16x16x32_bf16 v[124:127], v[164:167], v[200:203], v[124:127]
	v_mfma_f32_16x16x32_bf16 v[120:123], v[172:175], v[200:203], v[120:123]
	v_mfma_f32_16x16x32_bf16 v[112:115], v[164:167], v[208:211], v[112:115]
	v_mfma_f32_16x16x32_bf16 v[104:107], v[172:175], v[208:211], v[104:107]
	v_mfma_f32_16x16x32_bf16 v[96:99], v[164:167], v[216:219], v[96:99]
	v_mfma_f32_16x16x32_bf16 v[88:91], v[172:175], v[216:219], v[88:91]
	v_mfma_f32_16x16x32_bf16 v[80:83], v[164:167], v[224:227], v[80:83]
	v_mfma_f32_16x16x32_bf16 v[72:75], v[172:175], v[224:227], v[72:75]
	v_mfma_f32_16x16x32_bf16 v[124:127], v[168:171], v[204:207], v[124:127]
	v_mfma_f32_16x16x32_bf16 v[120:123], v[176:179], v[204:207], v[120:123]
	v_mfma_f32_16x16x32_bf16 v[112:115], v[168:171], v[212:215], v[112:115]
	v_mfma_f32_16x16x32_bf16 v[104:107], v[176:179], v[212:215], v[104:107]
	v_mfma_f32_16x16x32_bf16 v[96:99], v[168:171], v[220:223], v[96:99]
	v_mfma_f32_16x16x32_bf16 v[88:91], v[176:179], v[220:223], v[88:91]
	v_mfma_f32_16x16x32_bf16 v[80:83], v[168:171], v[228:231], v[80:83]
	v_mfma_f32_16x16x32_bf16 v[72:75], v[176:179], v[228:231], v[72:75]
	v_mfma_f32_16x16x32_bf16 v[116:119], v[184:187], v[200:203], v[116:119]
	v_mfma_f32_16x16x32_bf16 v[108:111], v[192:195], v[200:203], v[108:111]
	v_mfma_f32_16x16x32_bf16 v[100:103], v[184:187], v[208:211], v[100:103]
	v_mfma_f32_16x16x32_bf16 v[92:95], v[192:195], v[208:211], v[92:95]
	v_mfma_f32_16x16x32_bf16 v[84:87], v[184:187], v[216:219], v[84:87]
	v_mfma_f32_16x16x32_bf16 v[76:79], v[192:195], v[216:219], v[76:79]
	v_mfma_f32_16x16x32_bf16 v[68:71], v[184:187], v[224:227], v[68:71]
	v_mfma_f32_16x16x32_bf16 v[64:67], v[192:195], v[224:227], v[64:67]
	v_mfma_f32_16x16x32_bf16 v[116:119], v[188:191], v[204:207], v[116:119]
	v_mfma_f32_16x16x32_bf16 v[108:111], v[196:199], v[204:207], v[108:111]
	v_mfma_f32_16x16x32_bf16 v[100:103], v[188:191], v[212:215], v[100:103]
	v_mfma_f32_16x16x32_bf16 v[92:95], v[196:199], v[212:215], v[92:95]
	v_mfma_f32_16x16x32_bf16 v[84:87], v[188:191], v[220:223], v[84:87]
	v_mfma_f32_16x16x32_bf16 v[76:79], v[196:199], v[220:223], v[76:79]
	v_mfma_f32_16x16x32_bf16 v[68:71], v[188:191], v[228:231], v[68:71]
	v_mfma_f32_16x16x32_bf16 v[64:67], v[196:199], v[228:231], v[64:67]
	s_setprio 0
	s_barrier
	s_add_i32 s61, s43, s30
	v_lshl_add_u64 v[232:233], s[24:25], 0, v[134:135]
	s_mov_b32 m0, s61
	ds_read_b128 v[200:203], v163 offset:16384
	ds_read_b128 v[204:207], v163 offset:17408
	ds_read_b128 v[208:211], v163 offset:18432
	ds_read_b128 v[212:215], v163 offset:19456
	ds_read_b128 v[216:219], v163 offset:20480
	ds_read_b128 v[220:223], v163 offset:21504
	ds_read_b128 v[224:227], v163 offset:22528
	ds_read_b128 v[228:231], v163 offset:23552
	global_load_lds_dwordx4 v[232:233], off
	s_add_i32 m0, s61, 0x2000
	s_add_u32 s62, s24, 0x18000
	v_lshl_add_u64 v[234:235], s[24:25], 0, v[138:139]
	s_addc_u32 s63, s25, 0
	s_add_i32 s61, s44, s30
	global_load_lds_dwordx4 v[234:235], off
	v_lshl_add_u64 v[236:237], s[62:63], 0, v[134:135]
	s_mov_b32 m0, s61
	v_lshl_add_u64 v[238:239], s[26:27], 0, v[136:137]
	global_load_lds_dwordx4 v[236:237], off
	v_lshl_add_u64 v[236:237], s[62:63], 0, v[138:139]
	s_add_i32 m0, s61, 0x2000
	s_nop 0
	global_load_lds_dwordx4 v[236:237], off
	v_lshl_add_u64 v[236:237], s[26:27], 0, v[132:133]
	s_mov_b32 m0, s34
	s_nop 0
	global_load_lds_dwordx4 v[236:237], off
	s_mov_b32 m0, s35
	s_nop 0
	global_load_lds_dwordx4 v[238:239], off
	s_waitcnt vmcnt(8)
	s_waitcnt lgkmcnt(0)
	s_barrier
	s_setprio 1
	s_waitcnt lgkmcnt(0)
	v_mfma_f32_16x16x32_bf16 v[60:63], v[164:167], v[200:203], v[60:63]
	v_mfma_f32_16x16x32_bf16 v[56:59], v[172:175], v[200:203], v[56:59]
	v_mfma_f32_16x16x32_bf16 v[48:51], v[164:167], v[208:211], v[48:51]
	v_mfma_f32_16x16x32_bf16 v[40:43], v[172:175], v[208:211], v[40:43]
	v_mfma_f32_16x16x32_bf16 v[32:35], v[164:167], v[216:219], v[32:35]
	v_mfma_f32_16x16x32_bf16 v[24:27], v[172:175], v[216:219], v[24:27]
	v_mfma_f32_16x16x32_bf16 v[16:19], v[164:167], v[224:227], v[16:19]
	v_mfma_f32_16x16x32_bf16 v[8:11], v[172:175], v[224:227], v[8:11]
	v_mfma_f32_16x16x32_bf16 v[60:63], v[168:171], v[204:207], v[60:63]
	v_mfma_f32_16x16x32_bf16 v[56:59], v[176:179], v[204:207], v[56:59]
	v_mfma_f32_16x16x32_bf16 v[48:51], v[168:171], v[212:215], v[48:51]
	v_mfma_f32_16x16x32_bf16 v[40:43], v[176:179], v[212:215], v[40:43]
	v_mfma_f32_16x16x32_bf16 v[32:35], v[168:171], v[220:223], v[32:35]
	v_mfma_f32_16x16x32_bf16 v[24:27], v[176:179], v[220:223], v[24:27]
	v_mfma_f32_16x16x32_bf16 v[16:19], v[168:171], v[228:231], v[16:19]
	v_mfma_f32_16x16x32_bf16 v[8:11], v[176:179], v[228:231], v[8:11]
	v_mfma_f32_16x16x32_bf16 v[52:55], v[184:187], v[200:203], v[52:55]
	v_mfma_f32_16x16x32_bf16 v[44:47], v[192:195], v[200:203], v[44:47]
	v_mfma_f32_16x16x32_bf16 v[36:39], v[184:187], v[208:211], v[36:39]
	v_mfma_f32_16x16x32_bf16 v[28:31], v[192:195], v[208:211], v[28:31]
	v_mfma_f32_16x16x32_bf16 v[20:23], v[184:187], v[216:219], v[20:23]
	v_mfma_f32_16x16x32_bf16 v[12:15], v[192:195], v[216:219], v[12:15]
	v_mfma_f32_16x16x32_bf16 v[4:7], v[184:187], v[224:227], v[4:7]
	v_mfma_f32_16x16x32_bf16 v[0:3], v[192:195], v[224:227], v[0:3]
	v_mfma_f32_16x16x32_bf16 v[52:55], v[188:191], v[204:207], v[52:55]
	v_mfma_f32_16x16x32_bf16 v[44:47], v[196:199], v[204:207], v[44:47]
	v_mfma_f32_16x16x32_bf16 v[36:39], v[188:191], v[212:215], v[36:39]
	v_mfma_f32_16x16x32_bf16 v[28:31], v[196:199], v[212:215], v[28:31]
	v_mfma_f32_16x16x32_bf16 v[20:23], v[188:191], v[220:223], v[20:23]
	v_mfma_f32_16x16x32_bf16 v[12:15], v[196:199], v[220:223], v[12:15]
	v_mfma_f32_16x16x32_bf16 v[4:7], v[188:191], v[228:231], v[4:7]
	v_mfma_f32_16x16x32_bf16 v[0:3], v[196:199], v[228:231], v[0:3]
	s_setprio 0
	s_barrier
	s_add_i32 s61, 0, 0x18000
	s_add_i32 s62, 0, 0x1c000
	v_add_u32_e32 v176, s61, v155
	v_add_u32_e32 v181, s62, v155
	ds_read_b128 v[164:167], v176
	ds_read_b128 v[168:171], v176 offset:1024
	ds_read_b128 v[172:175], v176 offset:2048
	ds_read_b128 v[176:179], v176 offset:3072
	ds_read_b128 v[184:187], v181
	ds_read_b128 v[188:191], v181 offset:1024
	ds_read_b128 v[192:195], v181 offset:2048
	ds_read_b128 v[196:199], v181 offset:3072
	s_add_u32 s26, s26, 0x18000
	s_addc_u32 s27, s27, 0
	s_mov_b32 m0, s36
	v_lshl_add_u64 v[240:241], s[26:27], 0, v[132:133]
	ds_read_b128 v[200:203], v163 offset:32768
	ds_read_b128 v[204:207], v163 offset:33792
	ds_read_b128 v[208:211], v163 offset:34816
	ds_read_b128 v[212:215], v163 offset:35840
	ds_read_b128 v[216:219], v163 offset:36864
	ds_read_b128 v[220:223], v163 offset:37888
	ds_read_b128 v[224:227], v163 offset:38912
	ds_read_b128 v[228:231], v163 offset:39936
	global_load_lds_dwordx4 v[240:241], off
	v_lshl_add_u64 v[240:241], s[26:27], 0, v[136:137]
	s_mov_b32 m0, s37
	s_nop 0
	global_load_lds_dwordx4 v[240:241], off
	s_waitcnt vmcnt(8)
	s_waitcnt lgkmcnt(0)
	s_barrier
	s_setprio 1
	s_waitcnt lgkmcnt(0)
	v_mfma_f32_16x16x32_bf16 v[124:127], v[164:167], v[200:203], v[124:127]
	v_mfma_f32_16x16x32_bf16 v[120:123], v[172:175], v[200:203], v[120:123]
	v_mfma_f32_16x16x32_bf16 v[112:115], v[164:167], v[208:211], v[112:115]
	v_mfma_f32_16x16x32_bf16 v[104:107], v[172:175], v[208:211], v[104:107]
	v_mfma_f32_16x16x32_bf16 v[96:99], v[164:167], v[216:219], v[96:99]
	v_mfma_f32_16x16x32_bf16 v[88:91], v[172:175], v[216:219], v[88:91]
	v_mfma_f32_16x16x32_bf16 v[80:83], v[164:167], v[224:227], v[80:83]
	v_mfma_f32_16x16x32_bf16 v[72:75], v[172:175], v[224:227], v[72:75]
	v_mfma_f32_16x16x32_bf16 v[124:127], v[168:171], v[204:207], v[124:127]
	v_mfma_f32_16x16x32_bf16 v[120:123], v[176:179], v[204:207], v[120:123]
	v_mfma_f32_16x16x32_bf16 v[112:115], v[168:171], v[212:215], v[112:115]
	v_mfma_f32_16x16x32_bf16 v[104:107], v[176:179], v[212:215], v[104:107]
	v_mfma_f32_16x16x32_bf16 v[96:99], v[168:171], v[220:223], v[96:99]
	v_mfma_f32_16x16x32_bf16 v[88:91], v[176:179], v[220:223], v[88:91]
	v_mfma_f32_16x16x32_bf16 v[80:83], v[168:171], v[228:231], v[80:83]
	v_mfma_f32_16x16x32_bf16 v[72:75], v[176:179], v[228:231], v[72:75]
	v_mfma_f32_16x16x32_bf16 v[116:119], v[184:187], v[200:203], v[116:119]
	v_mfma_f32_16x16x32_bf16 v[108:111], v[192:195], v[200:203], v[108:111]
	v_mfma_f32_16x16x32_bf16 v[100:103], v[184:187], v[208:211], v[100:103]
	v_mfma_f32_16x16x32_bf16 v[92:95], v[192:195], v[208:211], v[92:95]
	v_mfma_f32_16x16x32_bf16 v[84:87], v[184:187], v[216:219], v[84:87]
	v_mfma_f32_16x16x32_bf16 v[76:79], v[192:195], v[216:219], v[76:79]
	v_mfma_f32_16x16x32_bf16 v[68:71], v[184:187], v[224:227], v[68:71]
	v_mfma_f32_16x16x32_bf16 v[64:67], v[192:195], v[224:227], v[64:67]
	v_mfma_f32_16x16x32_bf16 v[116:119], v[188:191], v[204:207], v[116:119]
	v_mfma_f32_16x16x32_bf16 v[108:111], v[196:199], v[204:207], v[108:111]
	v_mfma_f32_16x16x32_bf16 v[100:103], v[188:191], v[212:215], v[100:103]
	v_mfma_f32_16x16x32_bf16 v[92:95], v[196:199], v[212:215], v[92:95]
	v_mfma_f32_16x16x32_bf16 v[84:87], v[188:191], v[220:223], v[84:87]
	v_mfma_f32_16x16x32_bf16 v[76:79], v[196:199], v[220:223], v[76:79]
	v_mfma_f32_16x16x32_bf16 v[68:71], v[188:191], v[228:231], v[68:71]
	v_mfma_f32_16x16x32_bf16 v[64:67], v[196:199], v[228:231], v[64:67]
	s_setprio 0
	s_barrier
	s_add_i32 s26, s61, s30
	v_lshl_add_u64 v[232:233], v[232:233], 0, s[14:15]
	s_mov_b32 m0, s26
	ds_read_b128 v[200:203], v163 offset:49152
	ds_read_b128 v[204:207], v163 offset:50176
	ds_read_b128 v[208:211], v163 offset:51200
	ds_read_b128 v[212:215], v163 offset:52224
	ds_read_b128 v[216:219], v163 offset:53248
	ds_read_b128 v[220:223], v163 offset:54272
	ds_read_b128 v[224:227], v163 offset:55296
	ds_read_b128 v[228:231], v163 offset:56320
	global_load_lds_dwordx4 v[232:233], off
	s_add_i32 m0, s26, 0x2000
	s_add_u32 s24, s24, 0x18080
	v_lshl_add_u64 v[232:233], v[234:235], 0, s[14:15]
	s_addc_u32 s25, s25, 0
	s_add_i32 s26, s62, s30
	global_load_lds_dwordx4 v[232:233], off
	v_lshl_add_u64 v[232:233], s[24:25], 0, v[134:135]
	s_mov_b32 m0, s26
	s_nop 0
	global_load_lds_dwordx4 v[232:233], off
	v_lshl_add_u64 v[232:233], s[24:25], 0, v[138:139]
	s_add_i32 m0, s26, 0x2000
	s_nop 0
	global_load_lds_dwordx4 v[232:233], off
	v_lshl_add_u64 v[232:233], v[236:237], 0, s[14:15]
	s_mov_b32 m0, s39
	s_nop 0
	global_load_lds_dwordx4 v[232:233], off
	v_lshl_add_u64 v[232:233], v[238:239], 0, s[14:15]
	s_mov_b32 m0, s40
	s_nop 0
	global_load_lds_dwordx4 v[232:233], off
	s_waitcnt vmcnt(8)
	s_waitcnt lgkmcnt(0)
	s_barrier
	s_setprio 1
	s_waitcnt lgkmcnt(0)
	v_mfma_f32_16x16x32_bf16 v[60:63], v[164:167], v[200:203], v[60:63]
	v_mfma_f32_16x16x32_bf16 v[56:59], v[172:175], v[200:203], v[56:59]
	v_mfma_f32_16x16x32_bf16 v[48:51], v[164:167], v[208:211], v[48:51]
	v_mfma_f32_16x16x32_bf16 v[40:43], v[172:175], v[208:211], v[40:43]
	v_mfma_f32_16x16x32_bf16 v[32:35], v[164:167], v[216:219], v[32:35]
	v_mfma_f32_16x16x32_bf16 v[24:27], v[172:175], v[216:219], v[24:27]
	v_mfma_f32_16x16x32_bf16 v[16:19], v[164:167], v[224:227], v[16:19]
	v_mfma_f32_16x16x32_bf16 v[8:11], v[172:175], v[224:227], v[8:11]
	v_mfma_f32_16x16x32_bf16 v[60:63], v[168:171], v[204:207], v[60:63]
	v_mfma_f32_16x16x32_bf16 v[56:59], v[176:179], v[204:207], v[56:59]
	v_mfma_f32_16x16x32_bf16 v[48:51], v[168:171], v[212:215], v[48:51]
	v_mfma_f32_16x16x32_bf16 v[40:43], v[176:179], v[212:215], v[40:43]
	v_mfma_f32_16x16x32_bf16 v[32:35], v[168:171], v[220:223], v[32:35]
	v_mfma_f32_16x16x32_bf16 v[24:27], v[176:179], v[220:223], v[24:27]
	v_mfma_f32_16x16x32_bf16 v[16:19], v[168:171], v[228:231], v[16:19]
	v_mfma_f32_16x16x32_bf16 v[8:11], v[176:179], v[228:231], v[8:11]
	v_mfma_f32_16x16x32_bf16 v[52:55], v[184:187], v[200:203], v[52:55]
	v_mfma_f32_16x16x32_bf16 v[44:47], v[192:195], v[200:203], v[44:47]
	v_mfma_f32_16x16x32_bf16 v[36:39], v[184:187], v[208:211], v[36:39]
	v_mfma_f32_16x16x32_bf16 v[28:31], v[192:195], v[208:211], v[28:31]
	v_mfma_f32_16x16x32_bf16 v[20:23], v[184:187], v[216:219], v[20:23]
	v_mfma_f32_16x16x32_bf16 v[12:15], v[192:195], v[216:219], v[12:15]
	v_mfma_f32_16x16x32_bf16 v[4:7], v[184:187], v[224:227], v[4:7]
	v_mfma_f32_16x16x32_bf16 v[0:3], v[192:195], v[224:227], v[0:3]
	v_mfma_f32_16x16x32_bf16 v[52:55], v[188:191], v[204:207], v[52:55]
	v_mfma_f32_16x16x32_bf16 v[44:47], v[196:199], v[204:207], v[44:47]
	v_mfma_f32_16x16x32_bf16 v[36:39], v[188:191], v[212:215], v[36:39]
	v_mfma_f32_16x16x32_bf16 v[28:31], v[196:199], v[212:215], v[28:31]
	v_mfma_f32_16x16x32_bf16 v[20:23], v[188:191], v[220:223], v[20:23]
	v_mfma_f32_16x16x32_bf16 v[12:15], v[196:199], v[220:223], v[12:15]
	v_mfma_f32_16x16x32_bf16 v[4:7], v[188:191], v[228:231], v[4:7]
	v_mfma_f32_16x16x32_bf16 v[0:3], v[196:199], v[228:231], v[0:3]
	s_setprio 0
	s_barrier
	s_add_i32 s60, s60, 2
	s_add_u32 s57, s57, 0x100
	s_addc_u32 s59, s59, 0
	s_add_u32 s22, s22, 0x100
	s_addc_u32 s23, s23, 0
	s_cmp_gt_u32 s60, 3
	s_cbranch_scc0 .LBB0_2325
	s_and_b64 vcc, exec, s[16:17]
	s_cbranch_vccz .LBB0_2328
	s_barrier

.LBB0_2345:
	ds_read_b128 v[170:173], v167
	ds_read_b128 v[174:177], v167 offset:1024
	ds_read_b128 v[184:187], v167 offset:2048
	ds_read_b128 v[188:191], v167 offset:3072
	ds_read_b128 v[192:195], v168
	ds_read_b128 v[196:199], v168 offset:1024
	ds_read_b128 v[200:203], v168 offset:2048
	ds_read_b128 v[204:207], v168 offset:3072
	s_add_u32 s22, s20, 0xfffe8080
	s_addc_u32 s23, s21, -1
	s_cmp_eq_u32 s69, 2
	s_cselect_b32 s25, s9, s23
	s_cselect_b32 s24, s8, s22
	s_cselect_b32 s23, s19, s68
	s_cselect_b32 s22, s18, s67
	v_lshl_add_u64 v[154:155], s[20:21], 0, v[146:147]
	s_add_i32 m0, s35, 0xc000
	ds_read_b128 v[208:211], v169
	ds_read_b128 v[212:215], v169 offset:1024
	ds_read_b128 v[216:219], v169 offset:2048
	ds_read_b128 v[220:223], v169 offset:3072
	ds_read_b128 v[224:227], v169 offset:4096
	ds_read_b128 v[228:231], v169 offset:5120
	ds_read_b128 v[232:235], v169 offset:6144
	ds_read_b128 v[236:239], v169 offset:7168
	global_load_lds_dwordx4 v[154:155], off
	v_lshl_add_u64 v[154:155], s[20:21], 0, v[144:145]
	s_add_i32 m0, s35, 0xe000
	s_nop 0
	global_load_lds_dwordx4 v[154:155], off
	s_waitcnt vmcnt(8)
	s_waitcnt lgkmcnt(0)
	s_barrier
	s_setprio 1
	s_waitcnt lgkmcnt(0)
	v_mfma_f32_16x16x32_bf16 v[124:127], v[170:173], v[208:211], v[124:127]
	v_mfma_f32_16x16x32_bf16 v[116:119], v[184:187], v[208:211], v[116:119]
	v_mfma_f32_16x16x32_bf16 v[108:111], v[170:173], v[216:219], v[108:111]
	v_mfma_f32_16x16x32_bf16 v[100:103], v[184:187], v[216:219], v[100:103]
	v_mfma_f32_16x16x32_bf16 v[92:95], v[170:173], v[224:227], v[92:95]
	v_mfma_f32_16x16x32_bf16 v[84:87], v[184:187], v[224:227], v[84:87]
	v_mfma_f32_16x16x32_bf16 v[76:79], v[170:173], v[232:235], v[76:79]
	v_mfma_f32_16x16x32_bf16 v[68:71], v[184:187], v[232:235], v[68:71]
	v_mfma_f32_16x16x32_bf16 v[124:127], v[174:177], v[212:215], v[124:127]
	v_mfma_f32_16x16x32_bf16 v[116:119], v[188:191], v[212:215], v[116:119]
	v_mfma_f32_16x16x32_bf16 v[108:111], v[174:177], v[220:223], v[108:111]
	v_mfma_f32_16x16x32_bf16 v[100:103], v[188:191], v[220:223], v[100:103]
	v_mfma_f32_16x16x32_bf16 v[92:95], v[174:177], v[228:231], v[92:95]
	v_mfma_f32_16x16x32_bf16 v[84:87], v[188:191], v[228:231], v[84:87]
	v_mfma_f32_16x16x32_bf16 v[76:79], v[174:177], v[236:239], v[76:79]
	v_mfma_f32_16x16x32_bf16 v[68:71], v[188:191], v[236:239], v[68:71]
	v_mfma_f32_16x16x32_bf16 v[120:123], v[192:195], v[208:211], v[120:123]
	v_mfma_f32_16x16x32_bf16 v[112:115], v[200:203], v[208:211], v[112:115]
	v_mfma_f32_16x16x32_bf16 v[104:107], v[192:195], v[216:219], v[104:107]
	v_mfma_f32_16x16x32_bf16 v[96:99], v[200:203], v[216:219], v[96:99]
	v_mfma_f32_16x16x32_bf16 v[88:91], v[192:195], v[224:227], v[88:91]
	v_mfma_f32_16x16x32_bf16 v[80:83], v[200:203], v[224:227], v[80:83]
	v_mfma_f32_16x16x32_bf16 v[72:75], v[192:195], v[232:235], v[72:75]
	v_mfma_f32_16x16x32_bf16 v[64:67], v[200:203], v[232:235], v[64:67]
	v_mfma_f32_16x16x32_bf16 v[120:123], v[196:199], v[212:215], v[120:123]
	v_mfma_f32_16x16x32_bf16 v[112:115], v[204:207], v[212:215], v[112:115]
	v_mfma_f32_16x16x32_bf16 v[104:107], v[196:199], v[220:223], v[104:107]
	v_mfma_f32_16x16x32_bf16 v[96:99], v[204:207], v[220:223], v[96:99]
	v_mfma_f32_16x16x32_bf16 v[88:91], v[196:199], v[228:231], v[88:91]
	v_mfma_f32_16x16x32_bf16 v[80:83], v[204:207], v[228:231], v[80:83]
	v_mfma_f32_16x16x32_bf16 v[72:75], v[196:199], v[236:239], v[72:75]
	v_mfma_f32_16x16x32_bf16 v[64:67], v[204:207], v[236:239], v[64:67]
	s_setprio 0
	s_barrier
	s_add_i32 s70, s46, s31
	v_lshl_add_u64 v[154:155], s[22:23], 0, v[134:135]
	s_mov_b32 m0, s70
	ds_read_b128 v[208:211], v169 offset:16384
	ds_read_b128 v[212:215], v169 offset:17408
	ds_read_b128 v[216:219], v169 offset:18432
	ds_read_b128 v[220:223], v169 offset:19456
	ds_read_b128 v[224:227], v169 offset:20480
	ds_read_b128 v[228:231], v169 offset:21504
	ds_read_b128 v[232:235], v169 offset:22528
	ds_read_b128 v[236:239], v169 offset:23552
	global_load_lds_dwordx4 v[154:155], off
	s_add_i32 m0, s70, 0x2000
	s_add_u32 s70, s22, 0x18000
	v_lshl_add_u64 v[178:179], s[22:23], 0, v[138:139]
	s_addc_u32 s71, s23, 0
	s_add_i32 s72, s47, s31
	global_load_lds_dwordx4 v[178:179], off
	v_lshl_add_u64 v[240:241], s[70:71], 0, v[134:135]
	s_mov_b32 m0, s72
	v_lshl_add_u64 v[242:243], s[24:25], 0, v[136:137]
	global_load_lds_dwordx4 v[240:241], off
	v_lshl_add_u64 v[240:241], s[70:71], 0, v[138:139]
	s_add_i32 m0, s72, 0x2000
	s_nop 0
	global_load_lds_dwordx4 v[240:241], off
	v_lshl_add_u64 v[240:241], s[24:25], 0, v[132:133]
	s_mov_b32 m0, s35
	s_nop 0
	global_load_lds_dwordx4 v[240:241], off
	s_mov_b32 m0, s36
	s_nop 0
	global_load_lds_dwordx4 v[242:243], off
	s_waitcnt vmcnt(8)
	s_waitcnt lgkmcnt(0)
	s_barrier
	s_setprio 1
	s_waitcnt lgkmcnt(0)
	v_mfma_f32_16x16x32_bf16 v[60:63], v[170:173], v[208:211], v[60:63]
	v_mfma_f32_16x16x32_bf16 v[52:55], v[184:187], v[208:211], v[52:55]
	v_mfma_f32_16x16x32_bf16 v[44:47], v[170:173], v[216:219], v[44:47]
	v_mfma_f32_16x16x32_bf16 v[36:39], v[184:187], v[216:219], v[36:39]
	v_mfma_f32_16x16x32_bf16 v[28:31], v[170:173], v[224:227], v[28:31]
	v_mfma_f32_16x16x32_bf16 v[20:23], v[184:187], v[224:227], v[20:23]
	v_mfma_f32_16x16x32_bf16 v[12:15], v[170:173], v[232:235], v[12:15]
	v_mfma_f32_16x16x32_bf16 v[4:7], v[184:187], v[232:235], v[4:7]
	v_mfma_f32_16x16x32_bf16 v[60:63], v[174:177], v[212:215], v[60:63]
	v_mfma_f32_16x16x32_bf16 v[52:55], v[188:191], v[212:215], v[52:55]
	v_mfma_f32_16x16x32_bf16 v[44:47], v[174:177], v[220:223], v[44:47]
	v_mfma_f32_16x16x32_bf16 v[36:39], v[188:191], v[220:223], v[36:39]
	v_mfma_f32_16x16x32_bf16 v[28:31], v[174:177], v[228:231], v[28:31]
	v_mfma_f32_16x16x32_bf16 v[20:23], v[188:191], v[228:231], v[20:23]
	v_mfma_f32_16x16x32_bf16 v[12:15], v[174:177], v[236:239], v[12:15]
	v_mfma_f32_16x16x32_bf16 v[4:7], v[188:191], v[236:239], v[4:7]
	v_mfma_f32_16x16x32_bf16 v[56:59], v[192:195], v[208:211], v[56:59]
	v_mfma_f32_16x16x32_bf16 v[48:51], v[200:203], v[208:211], v[48:51]
	v_mfma_f32_16x16x32_bf16 v[40:43], v[192:195], v[216:219], v[40:43]
	v_mfma_f32_16x16x32_bf16 v[32:35], v[200:203], v[216:219], v[32:35]
	v_mfma_f32_16x16x32_bf16 v[24:27], v[192:195], v[224:227], v[24:27]
	v_mfma_f32_16x16x32_bf16 v[16:19], v[200:203], v[224:227], v[16:19]
	v_mfma_f32_16x16x32_bf16 v[8:11], v[192:195], v[232:235], v[8:11]
	v_mfma_f32_16x16x32_bf16 v[0:3], v[200:203], v[232:235], v[0:3]
	v_mfma_f32_16x16x32_bf16 v[56:59], v[196:199], v[212:215], v[56:59]
	v_mfma_f32_16x16x32_bf16 v[48:51], v[204:207], v[212:215], v[48:51]
	v_mfma_f32_16x16x32_bf16 v[40:43], v[196:199], v[220:223], v[40:43]
	v_mfma_f32_16x16x32_bf16 v[32:35], v[204:207], v[220:223], v[32:35]
	v_mfma_f32_16x16x32_bf16 v[24:27], v[196:199], v[228:231], v[24:27]
	v_mfma_f32_16x16x32_bf16 v[16:19], v[204:207], v[228:231], v[16:19]
	v_mfma_f32_16x16x32_bf16 v[8:11], v[196:199], v[236:239], v[8:11]
	v_mfma_f32_16x16x32_bf16 v[0:3], v[204:207], v[236:239], v[0:3]
	s_setprio 0
	s_barrier
	s_add_i32 s70, 0, 0x18000
	v_add_u32_e32 v140, s70, v162
	s_add_i32 s71, 0, 0x1c000
	ds_read_b128 v[170:173], v140
	ds_read_b128 v[174:177], v140 offset:1024
	ds_read_b128 v[184:187], v140 offset:2048
	ds_read_b128 v[188:191], v140 offset:3072
	v_add_u32_e32 v140, s71, v162
	ds_read_b128 v[192:195], v140
	ds_read_b128 v[196:199], v140 offset:1024
	ds_read_b128 v[200:203], v140 offset:2048
	ds_read_b128 v[204:207], v140 offset:3072
	s_add_u32 s24, s24, 0x18000
	s_addc_u32 s25, s25, 0
	s_mov_b32 m0, s37
	v_lshl_add_u64 v[244:245], s[24:25], 0, v[132:133]
	ds_read_b128 v[208:211], v169 offset:32768
	ds_read_b128 v[212:215], v169 offset:33792
	ds_read_b128 v[216:219], v169 offset:34816
	ds_read_b128 v[220:223], v169 offset:35840
	ds_read_b128 v[224:227], v169 offset:36864
	ds_read_b128 v[228:231], v169 offset:37888
	ds_read_b128 v[232:235], v169 offset:38912
	ds_read_b128 v[236:239], v169 offset:39936
	global_load_lds_dwordx4 v[244:245], off
	v_lshl_add_u64 v[244:245], s[24:25], 0, v[136:137]
	s_mov_b32 m0, s38
	s_nop 0
	global_load_lds_dwordx4 v[244:245], off
	s_waitcnt vmcnt(8)
	s_waitcnt lgkmcnt(0)
	s_barrier
	s_setprio 1
	s_waitcnt lgkmcnt(0)
	v_mfma_f32_16x16x32_bf16 v[124:127], v[170:173], v[208:211], v[124:127]
	v_mfma_f32_16x16x32_bf16 v[116:119], v[184:187], v[208:211], v[116:119]
	v_mfma_f32_16x16x32_bf16 v[108:111], v[170:173], v[216:219], v[108:111]
	v_mfma_f32_16x16x32_bf16 v[100:103], v[184:187], v[216:219], v[100:103]
	v_mfma_f32_16x16x32_bf16 v[92:95], v[170:173], v[224:227], v[92:95]
	v_mfma_f32_16x16x32_bf16 v[84:87], v[184:187], v[224:227], v[84:87]
	v_mfma_f32_16x16x32_bf16 v[76:79], v[170:173], v[232:235], v[76:79]
	v_mfma_f32_16x16x32_bf16 v[68:71], v[184:187], v[232:235], v[68:71]
	v_mfma_f32_16x16x32_bf16 v[124:127], v[174:177], v[212:215], v[124:127]
	v_mfma_f32_16x16x32_bf16 v[116:119], v[188:191], v[212:215], v[116:119]
	v_mfma_f32_16x16x32_bf16 v[108:111], v[174:177], v[220:223], v[108:111]
	v_mfma_f32_16x16x32_bf16 v[100:103], v[188:191], v[220:223], v[100:103]
	v_mfma_f32_16x16x32_bf16 v[92:95], v[174:177], v[228:231], v[92:95]
	v_mfma_f32_16x16x32_bf16 v[84:87], v[188:191], v[228:231], v[84:87]
	v_mfma_f32_16x16x32_bf16 v[76:79], v[174:177], v[236:239], v[76:79]
	v_mfma_f32_16x16x32_bf16 v[68:71], v[188:191], v[236:239], v[68:71]
	v_mfma_f32_16x16x32_bf16 v[120:123], v[192:195], v[208:211], v[120:123]
	v_mfma_f32_16x16x32_bf16 v[112:115], v[200:203], v[208:211], v[112:115]
	v_mfma_f32_16x16x32_bf16 v[104:107], v[192:195], v[216:219], v[104:107]
	v_mfma_f32_16x16x32_bf16 v[96:99], v[200:203], v[216:219], v[96:99]
	v_mfma_f32_16x16x32_bf16 v[88:91], v[192:195], v[224:227], v[88:91]
	v_mfma_f32_16x16x32_bf16 v[80:83], v[200:203], v[224:227], v[80:83]
	v_mfma_f32_16x16x32_bf16 v[72:75], v[192:195], v[232:235], v[72:75]
	v_mfma_f32_16x16x32_bf16 v[64:67], v[200:203], v[232:235], v[64:67]
	v_mfma_f32_16x16x32_bf16 v[120:123], v[196:199], v[212:215], v[120:123]
	v_mfma_f32_16x16x32_bf16 v[112:115], v[204:207], v[212:215], v[112:115]
	v_mfma_f32_16x16x32_bf16 v[104:107], v[196:199], v[220:223], v[104:107]
	v_mfma_f32_16x16x32_bf16 v[96:99], v[204:207], v[220:223], v[96:99]
	v_mfma_f32_16x16x32_bf16 v[88:91], v[196:199], v[228:231], v[88:91]
	v_mfma_f32_16x16x32_bf16 v[80:83], v[204:207], v[228:231], v[80:83]
	v_mfma_f32_16x16x32_bf16 v[72:75], v[196:199], v[236:239], v[72:75]
	v_mfma_f32_16x16x32_bf16 v[64:67], v[204:207], v[236:239], v[64:67]
	s_setprio 0
	s_barrier
	s_add_i32 s24, s70, s31
	v_lshl_add_u64 v[154:155], v[154:155], 0, s[14:15]
	s_mov_b32 m0, s24
	ds_read_b128 v[208:211], v169 offset:49152
	ds_read_b128 v[212:215], v169 offset:50176
	ds_read_b128 v[216:219], v169 offset:51200
	ds_read_b128 v[220:223], v169 offset:52224
	ds_read_b128 v[224:227], v169 offset:53248
	ds_read_b128 v[228:231], v169 offset:54272
	ds_read_b128 v[232:235], v169 offset:55296
	ds_read_b128 v[236:239], v169 offset:56320
	global_load_lds_dwordx4 v[154:155], off
	s_add_i32 m0, s24, 0x2000
	s_add_u32 s22, s22, 0x18080
	v_lshl_add_u64 v[154:155], v[178:179], 0, s[14:15]
	s_addc_u32 s23, s23, 0
	s_add_i32 s24, s71, s31
	global_load_lds_dwordx4 v[154:155], off
	v_lshl_add_u64 v[154:155], s[22:23], 0, v[134:135]
	s_mov_b32 m0, s24
	s_nop 0
	global_load_lds_dwordx4 v[154:155], off
	v_lshl_add_u64 v[154:155], s[22:23], 0, v[138:139]
	s_add_i32 m0, s24, 0x2000
	s_nop 0
	global_load_lds_dwordx4 v[154:155], off
	v_lshl_add_u64 v[154:155], v[240:241], 0, s[14:15]
	s_mov_b32 m0, s40
	s_nop 0
	global_load_lds_dwordx4 v[154:155], off
	v_lshl_add_u64 v[154:155], v[242:243], 0, s[14:15]
	s_mov_b32 m0, s41
	s_nop 0
	global_load_lds_dwordx4 v[154:155], off
	s_waitcnt vmcnt(8)
	s_waitcnt lgkmcnt(0)
	s_barrier
	s_setprio 1
	s_waitcnt lgkmcnt(0)
	v_mfma_f32_16x16x32_bf16 v[60:63], v[170:173], v[208:211], v[60:63]
	v_mfma_f32_16x16x32_bf16 v[52:55], v[184:187], v[208:211], v[52:55]
	v_mfma_f32_16x16x32_bf16 v[44:47], v[170:173], v[216:219], v[44:47]
	v_mfma_f32_16x16x32_bf16 v[36:39], v[184:187], v[216:219], v[36:39]
	v_mfma_f32_16x16x32_bf16 v[28:31], v[170:173], v[224:227], v[28:31]
	v_mfma_f32_16x16x32_bf16 v[20:23], v[184:187], v[224:227], v[20:23]
	v_mfma_f32_16x16x32_bf16 v[12:15], v[170:173], v[232:235], v[12:15]
	v_mfma_f32_16x16x32_bf16 v[4:7], v[184:187], v[232:235], v[4:7]
	v_mfma_f32_16x16x32_bf16 v[60:63], v[174:177], v[212:215], v[60:63]
	v_mfma_f32_16x16x32_bf16 v[52:55], v[188:191], v[212:215], v[52:55]
	v_mfma_f32_16x16x32_bf16 v[44:47], v[174:177], v[220:223], v[44:47]
	v_mfma_f32_16x16x32_bf16 v[36:39], v[188:191], v[220:223], v[36:39]
	v_mfma_f32_16x16x32_bf16 v[28:31], v[174:177], v[228:231], v[28:31]
	v_mfma_f32_16x16x32_bf16 v[20:23], v[188:191], v[228:231], v[20:23]
	v_mfma_f32_16x16x32_bf16 v[12:15], v[174:177], v[236:239], v[12:15]
	v_mfma_f32_16x16x32_bf16 v[4:7], v[188:191], v[236:239], v[4:7]
	v_mfma_f32_16x16x32_bf16 v[56:59], v[192:195], v[208:211], v[56:59]
	v_mfma_f32_16x16x32_bf16 v[48:51], v[200:203], v[208:211], v[48:51]
	v_mfma_f32_16x16x32_bf16 v[40:43], v[192:195], v[216:219], v[40:43]
	v_mfma_f32_16x16x32_bf16 v[32:35], v[200:203], v[216:219], v[32:35]
	v_mfma_f32_16x16x32_bf16 v[24:27], v[192:195], v[224:227], v[24:27]
	v_mfma_f32_16x16x32_bf16 v[16:19], v[200:203], v[224:227], v[16:19]
	v_mfma_f32_16x16x32_bf16 v[8:11], v[192:195], v[232:235], v[8:11]
	v_mfma_f32_16x16x32_bf16 v[0:3], v[200:203], v[232:235], v[0:3]
	v_mfma_f32_16x16x32_bf16 v[56:59], v[196:199], v[212:215], v[56:59]
	v_mfma_f32_16x16x32_bf16 v[48:51], v[204:207], v[212:215], v[48:51]
	v_mfma_f32_16x16x32_bf16 v[40:43], v[196:199], v[220:223], v[40:43]
	v_mfma_f32_16x16x32_bf16 v[32:35], v[204:207], v[220:223], v[32:35]
	v_mfma_f32_16x16x32_bf16 v[24:27], v[196:199], v[228:231], v[24:27]
	v_mfma_f32_16x16x32_bf16 v[16:19], v[204:207], v[228:231], v[16:19]
	v_mfma_f32_16x16x32_bf16 v[8:11], v[196:199], v[236:239], v[8:11]
	v_mfma_f32_16x16x32_bf16 v[0:3], v[204:207], v[236:239], v[0:3]
	s_setprio 0
	s_barrier
	s_add_i32 s69, s69, 2
	s_add_u32 s67, s67, 0x100
	s_addc_u32 s68, s68, 0
	s_add_u32 s20, s20, 0x100
	s_addc_u32 s21, s21, 0
	s_cmp_gt_u32 s69, 3
	s_cbranch_scc0 .LBB0_2345
	s_and_b64 vcc, exec, s[16:17]
	s_cbranch_vccz .LBB0_2348
	s_barrier

.LBB0_2361:
	s_add_u32 s43, s36, s42
	s_addc_u32 s48, s37, 0
	s_add_u32 s46, s43, 0x100
	s_addc_u32 s47, s48, 0
	s_and_b64 s[44:45], s[40:41], exec
	s_cselect_b32 s45, s25, s47
	s_cselect_b32 s44, s86, s46
	s_add_u32 s42, s34, s42
	s_addc_u32 s46, s35, 0
	s_add_u32 s42, s42, 0x100
	s_addc_u32 s46, s46, 0
	s_and_b64 s[40:41], s[40:41], exec
	s_cselect_b32 s47, s23, s46
	s_cselect_b32 s46, s87, s42
	s_add_u32 s60, s43, 0x10080
	ds_read_b128 v[150:153], v147
	ds_read_b128 v[154:157], v147 offset:1024
	ds_read_b128 v[158:161], v147 offset:2048
	ds_read_b128 v[162:165], v147 offset:3072
	ds_read_b128 v[166:169], v148
	ds_read_b128 v[170:173], v148 offset:1024
	ds_read_b128 v[174:177], v148 offset:2048
	ds_read_b128 v[184:187], v148 offset:3072
	s_addc_u32 s61, s48, 0
	s_add_i32 s94, s74, s63
	s_add_i32 m0, s31, 0xc000
	s_add_i32 s79, s31, 0xe000
	s_add_i32 s76, s94, 0x2000
	s_add_u32 s48, s46, 0x10000
	s_addc_u32 s49, s47, 0
	s_add_i32 s93, s75, s63
	s_add_i32 s92, s93, 0x2000
	s_add_i32 s91, 0, 0x18000
	s_add_i32 s90, 0, 0x1c000
	s_add_u32 s42, s44, 0x10000
	s_addc_u32 s43, s45, 0
	s_add_i32 s89, s91, s63
	s_add_i32 s88, s89, 0x2000
	s_add_u32 s40, s46, 0x10080
	s_addc_u32 s41, s47, 0
	s_add_i32 s96, s90, s63
	s_add_i32 s95, s96, 0x2000
	v_lshl_add_u64 v[142:143], s[60:61], 0, v[138:139]
	ds_read_b128 v[188:191], v149
	ds_read_b128 v[192:195], v149 offset:1024
	ds_read_b128 v[196:199], v149 offset:2048
	ds_read_b128 v[200:203], v149 offset:3072
	ds_read_b128 v[204:207], v149 offset:4096
	ds_read_b128 v[208:211], v149 offset:5120
	ds_read_b128 v[212:215], v149 offset:6144
	ds_read_b128 v[216:219], v149 offset:7168
	global_load_lds_dwordx4 v[142:143], off
	v_lshl_add_u64 v[142:143], s[60:61], 0, v[134:135]
	s_mov_b32 m0, s79
	s_nop 0
	global_load_lds_dwordx4 v[142:143], off
	s_waitcnt vmcnt(8)
	s_waitcnt lgkmcnt(0)
	s_barrier
	s_setprio 1
	s_waitcnt lgkmcnt(0)
	v_mfma_f32_16x16x32_bf16 v[124:127], v[150:153], v[188:191], v[124:127]
	v_mfma_f32_16x16x32_bf16 v[120:123], v[158:161], v[188:191], v[120:123]
	v_mfma_f32_16x16x32_bf16 v[116:119], v[150:153], v[196:199], v[116:119]
	v_mfma_f32_16x16x32_bf16 v[108:111], v[158:161], v[196:199], v[108:111]
	v_mfma_f32_16x16x32_bf16 v[100:103], v[150:153], v[204:207], v[100:103]
	v_mfma_f32_16x16x32_bf16 v[92:95], v[158:161], v[204:207], v[92:95]
	v_mfma_f32_16x16x32_bf16 v[84:87], v[150:153], v[212:215], v[84:87]
	v_mfma_f32_16x16x32_bf16 v[76:79], v[158:161], v[212:215], v[76:79]
	v_mfma_f32_16x16x32_bf16 v[124:127], v[154:157], v[192:195], v[124:127]
	v_mfma_f32_16x16x32_bf16 v[120:123], v[162:165], v[192:195], v[120:123]
	v_mfma_f32_16x16x32_bf16 v[116:119], v[154:157], v[200:203], v[116:119]
	v_mfma_f32_16x16x32_bf16 v[108:111], v[162:165], v[200:203], v[108:111]
	v_mfma_f32_16x16x32_bf16 v[100:103], v[154:157], v[208:211], v[100:103]
	v_mfma_f32_16x16x32_bf16 v[92:95], v[162:165], v[208:211], v[92:95]
	v_mfma_f32_16x16x32_bf16 v[84:87], v[154:157], v[216:219], v[84:87]
	v_mfma_f32_16x16x32_bf16 v[76:79], v[162:165], v[216:219], v[76:79]
	v_mfma_f32_16x16x32_bf16 v[112:115], v[166:169], v[188:191], v[112:115]
	v_mfma_f32_16x16x32_bf16 v[104:107], v[174:177], v[188:191], v[104:107]
	v_mfma_f32_16x16x32_bf16 v[96:99], v[166:169], v[196:199], v[96:99]
	v_mfma_f32_16x16x32_bf16 v[88:91], v[174:177], v[196:199], v[88:91]
	v_mfma_f32_16x16x32_bf16 v[80:83], v[166:169], v[204:207], v[80:83]
	v_mfma_f32_16x16x32_bf16 v[72:75], v[174:177], v[204:207], v[72:75]
	v_mfma_f32_16x16x32_bf16 v[68:71], v[166:169], v[212:215], v[68:71]
	v_mfma_f32_16x16x32_bf16 v[64:67], v[174:177], v[212:215], v[64:67]
	v_mfma_f32_16x16x32_bf16 v[112:115], v[170:173], v[192:195], v[112:115]
	v_mfma_f32_16x16x32_bf16 v[104:107], v[184:187], v[192:195], v[104:107]
	v_mfma_f32_16x16x32_bf16 v[96:99], v[170:173], v[200:203], v[96:99]
	v_mfma_f32_16x16x32_bf16 v[88:91], v[184:187], v[200:203], v[88:91]
	v_mfma_f32_16x16x32_bf16 v[80:83], v[170:173], v[208:211], v[80:83]
	v_mfma_f32_16x16x32_bf16 v[72:75], v[184:187], v[208:211], v[72:75]
	v_mfma_f32_16x16x32_bf16 v[68:71], v[170:173], v[216:219], v[68:71]
	v_mfma_f32_16x16x32_bf16 v[64:67], v[184:187], v[216:219], v[64:67]
	s_setprio 0
	s_barrier
	s_mov_b32 m0, s94
	v_lshl_add_u64 v[142:143], s[46:47], 0, v[136:137]
	ds_read_b128 v[188:191], v149 offset:16384
	ds_read_b128 v[192:195], v149 offset:17408
	ds_read_b128 v[196:199], v149 offset:18432
	ds_read_b128 v[200:203], v149 offset:19456
	ds_read_b128 v[204:207], v149 offset:20480
	ds_read_b128 v[208:211], v149 offset:21504
	ds_read_b128 v[212:215], v149 offset:22528
	ds_read_b128 v[216:219], v149 offset:23552
	global_load_lds_dwordx4 v[142:143], off
	v_lshl_add_u64 v[178:179], s[46:47], 0, v[132:133]
	s_mov_b32 m0, s76
	v_lshl_add_u64 v[220:221], s[48:49], 0, v[136:137]
	global_load_lds_dwordx4 v[178:179], off
	s_mov_b32 m0, s93
	v_lshl_add_u64 v[222:223], s[44:45], 0, v[134:135]
	global_load_lds_dwordx4 v[220:221], off
	v_lshl_add_u64 v[220:221], s[48:49], 0, v[132:133]
	s_mov_b32 m0, s92
	s_nop 0
	global_load_lds_dwordx4 v[220:221], off
	v_lshl_add_u64 v[220:221], s[44:45], 0, v[138:139]
	s_mov_b32 m0, s31
	s_nop 0
	global_load_lds_dwordx4 v[220:221], off
	s_mov_b32 m0, s66
	s_nop 0
	global_load_lds_dwordx4 v[222:223], off
	s_waitcnt vmcnt(8)
	s_waitcnt lgkmcnt(0)
	s_barrier
	s_setprio 1
	s_waitcnt lgkmcnt(0)
	v_mfma_f32_16x16x32_bf16 v[60:63], v[150:153], v[188:191], v[60:63]
	v_mfma_f32_16x16x32_bf16 v[56:59], v[158:161], v[188:191], v[56:59]
	v_mfma_f32_16x16x32_bf16 v[52:55], v[150:153], v[196:199], v[52:55]
	v_mfma_f32_16x16x32_bf16 v[44:47], v[158:161], v[196:199], v[44:47]
	v_mfma_f32_16x16x32_bf16 v[36:39], v[150:153], v[204:207], v[36:39]
	v_mfma_f32_16x16x32_bf16 v[28:31], v[158:161], v[204:207], v[28:31]
	v_mfma_f32_16x16x32_bf16 v[20:23], v[150:153], v[212:215], v[20:23]
	v_mfma_f32_16x16x32_bf16 v[12:15], v[158:161], v[212:215], v[12:15]
	v_mfma_f32_16x16x32_bf16 v[60:63], v[154:157], v[192:195], v[60:63]
	v_mfma_f32_16x16x32_bf16 v[56:59], v[162:165], v[192:195], v[56:59]
	v_mfma_f32_16x16x32_bf16 v[52:55], v[154:157], v[200:203], v[52:55]
	v_mfma_f32_16x16x32_bf16 v[44:47], v[162:165], v[200:203], v[44:47]
	v_mfma_f32_16x16x32_bf16 v[36:39], v[154:157], v[208:211], v[36:39]
	v_mfma_f32_16x16x32_bf16 v[28:31], v[162:165], v[208:211], v[28:31]
	v_mfma_f32_16x16x32_bf16 v[20:23], v[154:157], v[216:219], v[20:23]
	v_mfma_f32_16x16x32_bf16 v[12:15], v[162:165], v[216:219], v[12:15]
	v_mfma_f32_16x16x32_bf16 v[48:51], v[166:169], v[188:191], v[48:51]
	v_mfma_f32_16x16x32_bf16 v[40:43], v[174:177], v[188:191], v[40:43]
	v_mfma_f32_16x16x32_bf16 v[32:35], v[166:169], v[196:199], v[32:35]
	v_mfma_f32_16x16x32_bf16 v[24:27], v[174:177], v[196:199], v[24:27]
	v_mfma_f32_16x16x32_bf16 v[16:19], v[166:169], v[204:207], v[16:19]
	v_mfma_f32_16x16x32_bf16 v[8:11], v[174:177], v[204:207], v[8:11]
	v_mfma_f32_16x16x32_bf16 v[4:7], v[166:169], v[212:215], v[4:7]
	v_mfma_f32_16x16x32_bf16 v[0:3], v[174:177], v[212:215], v[0:3]
	v_mfma_f32_16x16x32_bf16 v[48:51], v[170:173], v[192:195], v[48:51]
	v_mfma_f32_16x16x32_bf16 v[40:43], v[184:187], v[192:195], v[40:43]
	v_mfma_f32_16x16x32_bf16 v[32:35], v[170:173], v[200:203], v[32:35]
	v_mfma_f32_16x16x32_bf16 v[24:27], v[184:187], v[200:203], v[24:27]
	v_mfma_f32_16x16x32_bf16 v[16:19], v[170:173], v[208:211], v[16:19]
	v_mfma_f32_16x16x32_bf16 v[8:11], v[184:187], v[208:211], v[8:11]
	v_mfma_f32_16x16x32_bf16 v[4:7], v[170:173], v[216:219], v[4:7]
	v_mfma_f32_16x16x32_bf16 v[0:3], v[184:187], v[216:219], v[0:3]
	s_setprio 0
	s_barrier
	v_add_u32_e32 v128, s91, v145
	ds_read_b128 v[150:153], v128
	ds_read_b128 v[154:157], v128 offset:1024
	ds_read_b128 v[158:161], v128 offset:2048
	ds_read_b128 v[162:165], v128 offset:3072
	v_add_u32_e32 v128, s90, v145
	ds_read_b128 v[166:169], v128
	ds_read_b128 v[170:173], v128 offset:1024
	ds_read_b128 v[174:177], v128 offset:2048
	ds_read_b128 v[184:187], v128 offset:3072
	s_mov_b32 m0, s67
	v_lshl_add_u64 v[224:225], s[42:43], 0, v[138:139]
	ds_read_b128 v[188:191], v149 offset:32768
	ds_read_b128 v[192:195], v149 offset:33792
	ds_read_b128 v[196:199], v149 offset:34816
	ds_read_b128 v[200:203], v149 offset:35840
	ds_read_b128 v[204:207], v149 offset:36864
	ds_read_b128 v[208:211], v149 offset:37888
	ds_read_b128 v[212:215], v149 offset:38912
	ds_read_b128 v[216:219], v149 offset:39936
	global_load_lds_dwordx4 v[224:225], off
	v_lshl_add_u64 v[224:225], s[42:43], 0, v[134:135]
	s_mov_b32 m0, s68
	s_nop 0
	global_load_lds_dwordx4 v[224:225], off
	s_waitcnt vmcnt(8)
	s_waitcnt lgkmcnt(0)
	s_barrier
	s_setprio 1
	s_waitcnt lgkmcnt(0)
	v_mfma_f32_16x16x32_bf16 v[124:127], v[150:153], v[188:191], v[124:127]
	v_mfma_f32_16x16x32_bf16 v[120:123], v[158:161], v[188:191], v[120:123]
	v_mfma_f32_16x16x32_bf16 v[116:119], v[150:153], v[196:199], v[116:119]
	v_mfma_f32_16x16x32_bf16 v[108:111], v[158:161], v[196:199], v[108:111]
	v_mfma_f32_16x16x32_bf16 v[100:103], v[150:153], v[204:207], v[100:103]
	v_mfma_f32_16x16x32_bf16 v[92:95], v[158:161], v[204:207], v[92:95]
	v_mfma_f32_16x16x32_bf16 v[84:87], v[150:153], v[212:215], v[84:87]
	v_mfma_f32_16x16x32_bf16 v[76:79], v[158:161], v[212:215], v[76:79]
	v_mfma_f32_16x16x32_bf16 v[124:127], v[154:157], v[192:195], v[124:127]
	v_mfma_f32_16x16x32_bf16 v[120:123], v[162:165], v[192:195], v[120:123]
	v_mfma_f32_16x16x32_bf16 v[116:119], v[154:157], v[200:203], v[116:119]
	v_mfma_f32_16x16x32_bf16 v[108:111], v[162:165], v[200:203], v[108:111]
	v_mfma_f32_16x16x32_bf16 v[100:103], v[154:157], v[208:211], v[100:103]
	v_mfma_f32_16x16x32_bf16 v[92:95], v[162:165], v[208:211], v[92:95]
	v_mfma_f32_16x16x32_bf16 v[84:87], v[154:157], v[216:219], v[84:87]
	v_mfma_f32_16x16x32_bf16 v[76:79], v[162:165], v[216:219], v[76:79]
	v_mfma_f32_16x16x32_bf16 v[112:115], v[166:169], v[188:191], v[112:115]
	v_mfma_f32_16x16x32_bf16 v[104:107], v[174:177], v[188:191], v[104:107]
	v_mfma_f32_16x16x32_bf16 v[96:99], v[166:169], v[196:199], v[96:99]
	v_mfma_f32_16x16x32_bf16 v[88:91], v[174:177], v[196:199], v[88:91]
	v_mfma_f32_16x16x32_bf16 v[80:83], v[166:169], v[204:207], v[80:83]
	v_mfma_f32_16x16x32_bf16 v[72:75], v[174:177], v[204:207], v[72:75]
	v_mfma_f32_16x16x32_bf16 v[68:71], v[166:169], v[212:215], v[68:71]
	v_mfma_f32_16x16x32_bf16 v[64:67], v[174:177], v[212:215], v[64:67]
	v_mfma_f32_16x16x32_bf16 v[112:115], v[170:173], v[192:195], v[112:115]
	v_mfma_f32_16x16x32_bf16 v[104:107], v[184:187], v[192:195], v[104:107]
	v_mfma_f32_16x16x32_bf16 v[96:99], v[170:173], v[200:203], v[96:99]
	v_mfma_f32_16x16x32_bf16 v[88:91], v[184:187], v[200:203], v[88:91]
	v_mfma_f32_16x16x32_bf16 v[80:83], v[170:173], v[208:211], v[80:83]
	v_mfma_f32_16x16x32_bf16 v[72:75], v[184:187], v[208:211], v[72:75]
	v_mfma_f32_16x16x32_bf16 v[68:71], v[170:173], v[216:219], v[68:71]
	v_mfma_f32_16x16x32_bf16 v[64:67], v[184:187], v[216:219], v[64:67]
	s_setprio 0
	s_barrier
	s_mov_b32 m0, s89
	v_lshl_add_u64 v[142:143], v[142:143], 0, s[10:11]
	ds_read_b128 v[188:191], v149 offset:49152
	ds_read_b128 v[192:195], v149 offset:50176
	ds_read_b128 v[196:199], v149 offset:51200
	ds_read_b128 v[200:203], v149 offset:52224
	ds_read_b128 v[204:207], v149 offset:53248
	ds_read_b128 v[208:211], v149 offset:54272
	ds_read_b128 v[212:215], v149 offset:55296
	ds_read_b128 v[216:219], v149 offset:56320
	global_load_lds_dwordx4 v[142:143], off
	v_lshl_add_u64 v[142:143], v[178:179], 0, s[10:11]
	s_mov_b32 m0, s88
	s_nop 0
	global_load_lds_dwordx4 v[142:143], off
	v_lshl_add_u64 v[142:143], s[40:41], 0, v[136:137]
	s_mov_b32 m0, s96
	s_nop 0
	global_load_lds_dwordx4 v[142:143], off
	v_lshl_add_u64 v[142:143], s[40:41], 0, v[132:133]
	s_mov_b32 m0, s95
	s_nop 0
	global_load_lds_dwordx4 v[142:143], off
	v_lshl_add_u64 v[142:143], v[220:221], 0, s[10:11]
	s_mov_b32 m0, s70
	s_nop 0
	global_load_lds_dwordx4 v[142:143], off
	v_lshl_add_u64 v[142:143], v[222:223], 0, s[10:11]
	s_mov_b32 m0, s71
	s_nop 0
	global_load_lds_dwordx4 v[142:143], off
	s_waitcnt vmcnt(8)
	s_waitcnt lgkmcnt(0)
	s_barrier
	s_setprio 1
	s_waitcnt lgkmcnt(0)
	v_mfma_f32_16x16x32_bf16 v[60:63], v[150:153], v[188:191], v[60:63]
	v_mfma_f32_16x16x32_bf16 v[56:59], v[158:161], v[188:191], v[56:59]
	v_mfma_f32_16x16x32_bf16 v[52:55], v[150:153], v[196:199], v[52:55]
	v_mfma_f32_16x16x32_bf16 v[44:47], v[158:161], v[196:199], v[44:47]
	v_mfma_f32_16x16x32_bf16 v[36:39], v[150:153], v[204:207], v[36:39]
	v_mfma_f32_16x16x32_bf16 v[28:31], v[158:161], v[204:207], v[28:31]
	v_mfma_f32_16x16x32_bf16 v[20:23], v[150:153], v[212:215], v[20:23]
	v_mfma_f32_16x16x32_bf16 v[12:15], v[158:161], v[212:215], v[12:15]
	v_mfma_f32_16x16x32_bf16 v[60:63], v[154:157], v[192:195], v[60:63]
	v_mfma_f32_16x16x32_bf16 v[56:59], v[162:165], v[192:195], v[56:59]
	v_mfma_f32_16x16x32_bf16 v[52:55], v[154:157], v[200:203], v[52:55]
	v_mfma_f32_16x16x32_bf16 v[44:47], v[162:165], v[200:203], v[44:47]
	v_mfma_f32_16x16x32_bf16 v[36:39], v[154:157], v[208:211], v[36:39]
	v_mfma_f32_16x16x32_bf16 v[28:31], v[162:165], v[208:211], v[28:31]
	v_mfma_f32_16x16x32_bf16 v[20:23], v[154:157], v[216:219], v[20:23]
	v_mfma_f32_16x16x32_bf16 v[12:15], v[162:165], v[216:219], v[12:15]
	v_mfma_f32_16x16x32_bf16 v[48:51], v[166:169], v[188:191], v[48:51]
	v_mfma_f32_16x16x32_bf16 v[40:43], v[174:177], v[188:191], v[40:43]
	v_mfma_f32_16x16x32_bf16 v[32:35], v[166:169], v[196:199], v[32:35]
	v_mfma_f32_16x16x32_bf16 v[24:27], v[174:177], v[196:199], v[24:27]
	v_mfma_f32_16x16x32_bf16 v[16:19], v[166:169], v[204:207], v[16:19]
	v_mfma_f32_16x16x32_bf16 v[8:11], v[174:177], v[204:207], v[8:11]
	v_mfma_f32_16x16x32_bf16 v[4:7], v[166:169], v[212:215], v[4:7]
	v_mfma_f32_16x16x32_bf16 v[0:3], v[174:177], v[212:215], v[0:3]
	v_mfma_f32_16x16x32_bf16 v[48:51], v[170:173], v[192:195], v[48:51]
	v_mfma_f32_16x16x32_bf16 v[40:43], v[184:187], v[192:195], v[40:43]
	v_mfma_f32_16x16x32_bf16 v[32:35], v[170:173], v[200:203], v[32:35]
	v_mfma_f32_16x16x32_bf16 v[24:27], v[184:187], v[200:203], v[24:27]
	v_mfma_f32_16x16x32_bf16 v[16:19], v[170:173], v[208:211], v[16:19]
	v_mfma_f32_16x16x32_bf16 v[8:11], v[184:187], v[208:211], v[8:11]
	v_mfma_f32_16x16x32_bf16 v[4:7], v[170:173], v[216:219], v[4:7]
	v_mfma_f32_16x16x32_bf16 v[0:3], v[184:187], v[216:219], v[0:3]
	s_setprio 0
	s_barrier
	s_movk_i32 s42, 0x100
	s_andn2_b64 vcc, exec, s[38:39]
	s_mov_b64 s[40:41], -1
	s_mov_b64 s[38:39], 0
	s_cbranch_vccz .LBB0_2361
	s_and_b64 vcc, exec, s[12:13]
	s_cbranch_vccz .LBB0_2364
	s_barrier

.LBB0_2502:
	s_add_u32 s43, s36, s42
	s_addc_u32 s48, s37, 0
	s_add_u32 s46, s43, 0x100
	s_addc_u32 s47, s48, 0
	s_and_b64 s[44:45], s[40:41], exec
	s_cselect_b32 s45, s25, s47
	s_cselect_b32 s44, s85, s46
	s_add_u32 s42, s34, s42
	s_addc_u32 s46, s35, 0
	s_add_u32 s42, s42, 0x100
	s_addc_u32 s46, s46, 0
	s_and_b64 s[40:41], s[40:41], exec
	s_cselect_b32 s47, s23, s46
	s_cselect_b32 s46, s86, s42
	s_add_u32 s60, s43, 0x10080
	ds_read_b128 v[150:153], v147
	ds_read_b128 v[154:157], v147 offset:1024
	ds_read_b128 v[158:161], v147 offset:2048
	ds_read_b128 v[162:165], v147 offset:3072
	ds_read_b128 v[166:169], v148
	ds_read_b128 v[170:173], v148 offset:1024
	ds_read_b128 v[174:177], v148 offset:2048
	ds_read_b128 v[184:187], v148 offset:3072
	s_addc_u32 s61, s48, 0
	s_add_i32 s93, s73, s62
	s_add_i32 m0, s31, 0xc000
	s_add_i32 s79, s31, 0xe000
	s_add_i32 s76, s93, 0x2000
	s_add_u32 s48, s46, 0x10000
	s_addc_u32 s49, s47, 0
	s_add_i32 s92, s74, s62
	s_add_i32 s91, s92, 0x2000
	s_add_i32 s90, 0, 0x18000
	s_add_i32 s89, 0, 0x1c000
	s_add_u32 s42, s44, 0x10000
	s_addc_u32 s43, s45, 0
	s_add_i32 s88, s90, s62
	s_add_i32 s87, s88, 0x2000
	s_add_u32 s40, s46, 0x10080
	s_addc_u32 s41, s47, 0
	s_add_i32 s95, s89, s62
	s_add_i32 s94, s95, 0x2000
	v_lshl_add_u64 v[142:143], s[60:61], 0, v[134:135]
	ds_read_b128 v[188:191], v149
	ds_read_b128 v[192:195], v149 offset:1024
	ds_read_b128 v[196:199], v149 offset:2048
	ds_read_b128 v[208:211], v149 offset:3072
	ds_read_b128 v[212:215], v149 offset:4096
	ds_read_b128 v[216:219], v149 offset:5120
	ds_read_b128 v[220:223], v149 offset:6144
	ds_read_b128 v[224:227], v149 offset:7168
	global_load_lds_dwordx4 v[142:143], off
	v_lshl_add_u64 v[142:143], s[60:61], 0, v[130:131]
	s_mov_b32 m0, s79
	s_nop 0
	global_load_lds_dwordx4 v[142:143], off
	s_waitcnt vmcnt(8)
	s_waitcnt lgkmcnt(0)
	s_barrier
	s_setprio 1
	s_waitcnt lgkmcnt(0)
	v_mfma_f32_16x16x32_bf16 v[124:127], v[150:153], v[188:191], v[124:127]
	v_mfma_f32_16x16x32_bf16 v[120:123], v[158:161], v[188:191], v[120:123]
	v_mfma_f32_16x16x32_bf16 v[116:119], v[150:153], v[196:199], v[116:119]
	v_mfma_f32_16x16x32_bf16 v[108:111], v[158:161], v[196:199], v[108:111]
	v_mfma_f32_16x16x32_bf16 v[100:103], v[150:153], v[212:215], v[100:103]
	v_mfma_f32_16x16x32_bf16 v[92:95], v[158:161], v[212:215], v[92:95]
	v_mfma_f32_16x16x32_bf16 v[84:87], v[150:153], v[220:223], v[84:87]
	v_mfma_f32_16x16x32_bf16 v[76:79], v[158:161], v[220:223], v[76:79]
	v_mfma_f32_16x16x32_bf16 v[124:127], v[154:157], v[192:195], v[124:127]
	v_mfma_f32_16x16x32_bf16 v[120:123], v[162:165], v[192:195], v[120:123]
	v_mfma_f32_16x16x32_bf16 v[116:119], v[154:157], v[208:211], v[116:119]
	v_mfma_f32_16x16x32_bf16 v[108:111], v[162:165], v[208:211], v[108:111]
	v_mfma_f32_16x16x32_bf16 v[100:103], v[154:157], v[216:219], v[100:103]
	v_mfma_f32_16x16x32_bf16 v[92:95], v[162:165], v[216:219], v[92:95]
	v_mfma_f32_16x16x32_bf16 v[84:87], v[154:157], v[224:227], v[84:87]
	v_mfma_f32_16x16x32_bf16 v[76:79], v[162:165], v[224:227], v[76:79]
	v_mfma_f32_16x16x32_bf16 v[112:115], v[166:169], v[188:191], v[112:115]
	v_mfma_f32_16x16x32_bf16 v[104:107], v[174:177], v[188:191], v[104:107]
	v_mfma_f32_16x16x32_bf16 v[96:99], v[166:169], v[196:199], v[96:99]
	v_mfma_f32_16x16x32_bf16 v[88:91], v[174:177], v[196:199], v[88:91]
	v_mfma_f32_16x16x32_bf16 v[80:83], v[166:169], v[212:215], v[80:83]
	v_mfma_f32_16x16x32_bf16 v[72:75], v[174:177], v[212:215], v[72:75]
	v_mfma_f32_16x16x32_bf16 v[68:71], v[166:169], v[220:223], v[68:71]
	v_mfma_f32_16x16x32_bf16 v[64:67], v[174:177], v[220:223], v[64:67]
	v_mfma_f32_16x16x32_bf16 v[112:115], v[170:173], v[192:195], v[112:115]
	v_mfma_f32_16x16x32_bf16 v[104:107], v[184:187], v[192:195], v[104:107]
	v_mfma_f32_16x16x32_bf16 v[96:99], v[170:173], v[208:211], v[96:99]
	v_mfma_f32_16x16x32_bf16 v[88:91], v[184:187], v[208:211], v[88:91]
	v_mfma_f32_16x16x32_bf16 v[80:83], v[170:173], v[216:219], v[80:83]
	v_mfma_f32_16x16x32_bf16 v[72:75], v[184:187], v[216:219], v[72:75]
	v_mfma_f32_16x16x32_bf16 v[68:71], v[170:173], v[224:227], v[68:71]
	v_mfma_f32_16x16x32_bf16 v[64:67], v[184:187], v[224:227], v[64:67]
	s_setprio 0
	s_barrier
	s_mov_b32 m0, s93
	v_lshl_add_u64 v[142:143], s[46:47], 0, v[132:133]
	ds_read_b128 v[188:191], v149 offset:16384
	ds_read_b128 v[192:195], v149 offset:17408
	ds_read_b128 v[196:199], v149 offset:18432
	ds_read_b128 v[208:211], v149 offset:19456
	ds_read_b128 v[212:215], v149 offset:20480
	ds_read_b128 v[216:219], v149 offset:21504
	ds_read_b128 v[220:223], v149 offset:22528
	ds_read_b128 v[224:227], v149 offset:23552
	global_load_lds_dwordx4 v[142:143], off
	v_lshl_add_u64 v[178:179], s[46:47], 0, v[128:129]
	s_mov_b32 m0, s76
	v_lshl_add_u64 v[200:201], s[48:49], 0, v[132:133]
	global_load_lds_dwordx4 v[178:179], off
	s_mov_b32 m0, s92
	v_lshl_add_u64 v[228:229], s[44:45], 0, v[130:131]
	global_load_lds_dwordx4 v[200:201], off
	v_lshl_add_u64 v[200:201], s[48:49], 0, v[128:129]
	s_mov_b32 m0, s91
	s_nop 0
	global_load_lds_dwordx4 v[200:201], off
	v_lshl_add_u64 v[200:201], s[44:45], 0, v[134:135]
	s_mov_b32 m0, s31
	s_nop 0
	global_load_lds_dwordx4 v[200:201], off
	s_mov_b32 m0, s65
	s_nop 0
	global_load_lds_dwordx4 v[228:229], off
	s_waitcnt vmcnt(8)
	s_waitcnt lgkmcnt(0)
	s_barrier
	s_setprio 1
	s_waitcnt lgkmcnt(0)
	v_mfma_f32_16x16x32_bf16 v[60:63], v[150:153], v[188:191], v[60:63]
	v_mfma_f32_16x16x32_bf16 v[56:59], v[158:161], v[188:191], v[56:59]
	v_mfma_f32_16x16x32_bf16 v[52:55], v[150:153], v[196:199], v[52:55]
	v_mfma_f32_16x16x32_bf16 v[44:47], v[158:161], v[196:199], v[44:47]
	v_mfma_f32_16x16x32_bf16 v[36:39], v[150:153], v[212:215], v[36:39]
	v_mfma_f32_16x16x32_bf16 v[28:31], v[158:161], v[212:215], v[28:31]
	v_mfma_f32_16x16x32_bf16 v[20:23], v[150:153], v[220:223], v[20:23]
	v_mfma_f32_16x16x32_bf16 v[12:15], v[158:161], v[220:223], v[12:15]
	v_mfma_f32_16x16x32_bf16 v[60:63], v[154:157], v[192:195], v[60:63]
	v_mfma_f32_16x16x32_bf16 v[56:59], v[162:165], v[192:195], v[56:59]
	v_mfma_f32_16x16x32_bf16 v[52:55], v[154:157], v[208:211], v[52:55]
	v_mfma_f32_16x16x32_bf16 v[44:47], v[162:165], v[208:211], v[44:47]
	v_mfma_f32_16x16x32_bf16 v[36:39], v[154:157], v[216:219], v[36:39]
	v_mfma_f32_16x16x32_bf16 v[28:31], v[162:165], v[216:219], v[28:31]
	v_mfma_f32_16x16x32_bf16 v[20:23], v[154:157], v[224:227], v[20:23]
	v_mfma_f32_16x16x32_bf16 v[12:15], v[162:165], v[224:227], v[12:15]
	v_mfma_f32_16x16x32_bf16 v[48:51], v[166:169], v[188:191], v[48:51]
	v_mfma_f32_16x16x32_bf16 v[40:43], v[174:177], v[188:191], v[40:43]
	v_mfma_f32_16x16x32_bf16 v[32:35], v[166:169], v[196:199], v[32:35]
	v_mfma_f32_16x16x32_bf16 v[24:27], v[174:177], v[196:199], v[24:27]
	v_mfma_f32_16x16x32_bf16 v[16:19], v[166:169], v[212:215], v[16:19]
	v_mfma_f32_16x16x32_bf16 v[8:11], v[174:177], v[212:215], v[8:11]
	v_mfma_f32_16x16x32_bf16 v[4:7], v[166:169], v[220:223], v[4:7]
	v_mfma_f32_16x16x32_bf16 v[0:3], v[174:177], v[220:223], v[0:3]
	v_mfma_f32_16x16x32_bf16 v[48:51], v[170:173], v[192:195], v[48:51]
	v_mfma_f32_16x16x32_bf16 v[40:43], v[184:187], v[192:195], v[40:43]
	v_mfma_f32_16x16x32_bf16 v[32:35], v[170:173], v[208:211], v[32:35]
	v_mfma_f32_16x16x32_bf16 v[24:27], v[184:187], v[208:211], v[24:27]
	v_mfma_f32_16x16x32_bf16 v[16:19], v[170:173], v[216:219], v[16:19]
	v_mfma_f32_16x16x32_bf16 v[8:11], v[184:187], v[216:219], v[8:11]
	v_mfma_f32_16x16x32_bf16 v[4:7], v[170:173], v[224:227], v[4:7]
	v_mfma_f32_16x16x32_bf16 v[0:3], v[184:187], v[224:227], v[0:3]
	s_setprio 0
	s_barrier
	v_add_u32_e32 v136, s90, v145
	ds_read_b128 v[150:153], v136
	ds_read_b128 v[154:157], v136 offset:1024
	ds_read_b128 v[158:161], v136 offset:2048
	ds_read_b128 v[162:165], v136 offset:3072
	v_add_u32_e32 v136, s89, v145
	ds_read_b128 v[166:169], v136
	ds_read_b128 v[170:173], v136 offset:1024
	ds_read_b128 v[174:177], v136 offset:2048
	ds_read_b128 v[184:187], v136 offset:3072
	s_mov_b32 m0, s66
	v_lshl_add_u64 v[230:231], s[42:43], 0, v[134:135]
	ds_read_b128 v[188:191], v149 offset:32768
	ds_read_b128 v[192:195], v149 offset:33792
	ds_read_b128 v[196:199], v149 offset:34816
	ds_read_b128 v[208:211], v149 offset:35840
	ds_read_b128 v[212:215], v149 offset:36864
	ds_read_b128 v[216:219], v149 offset:37888
	ds_read_b128 v[220:223], v149 offset:38912
	ds_read_b128 v[224:227], v149 offset:39936
	global_load_lds_dwordx4 v[230:231], off
	v_lshl_add_u64 v[230:231], s[42:43], 0, v[130:131]
	s_mov_b32 m0, s67
	s_nop 0
	global_load_lds_dwordx4 v[230:231], off
	s_waitcnt vmcnt(8)
	s_waitcnt lgkmcnt(0)
	s_barrier
	s_setprio 1
	s_waitcnt lgkmcnt(0)
	v_mfma_f32_16x16x32_bf16 v[124:127], v[150:153], v[188:191], v[124:127]
	v_mfma_f32_16x16x32_bf16 v[120:123], v[158:161], v[188:191], v[120:123]
	v_mfma_f32_16x16x32_bf16 v[116:119], v[150:153], v[196:199], v[116:119]
	v_mfma_f32_16x16x32_bf16 v[108:111], v[158:161], v[196:199], v[108:111]
	v_mfma_f32_16x16x32_bf16 v[100:103], v[150:153], v[212:215], v[100:103]
	v_mfma_f32_16x16x32_bf16 v[92:95], v[158:161], v[212:215], v[92:95]
	v_mfma_f32_16x16x32_bf16 v[84:87], v[150:153], v[220:223], v[84:87]
	v_mfma_f32_16x16x32_bf16 v[76:79], v[158:161], v[220:223], v[76:79]
	v_mfma_f32_16x16x32_bf16 v[124:127], v[154:157], v[192:195], v[124:127]
	v_mfma_f32_16x16x32_bf16 v[120:123], v[162:165], v[192:195], v[120:123]
	v_mfma_f32_16x16x32_bf16 v[116:119], v[154:157], v[208:211], v[116:119]
	v_mfma_f32_16x16x32_bf16 v[108:111], v[162:165], v[208:211], v[108:111]
	v_mfma_f32_16x16x32_bf16 v[100:103], v[154:157], v[216:219], v[100:103]
	v_mfma_f32_16x16x32_bf16 v[92:95], v[162:165], v[216:219], v[92:95]
	v_mfma_f32_16x16x32_bf16 v[84:87], v[154:157], v[224:227], v[84:87]
	v_mfma_f32_16x16x32_bf16 v[76:79], v[162:165], v[224:227], v[76:79]
	v_mfma_f32_16x16x32_bf16 v[112:115], v[166:169], v[188:191], v[112:115]
	v_mfma_f32_16x16x32_bf16 v[104:107], v[174:177], v[188:191], v[104:107]
	v_mfma_f32_16x16x32_bf16 v[96:99], v[166:169], v[196:199], v[96:99]
	v_mfma_f32_16x16x32_bf16 v[88:91], v[174:177], v[196:199], v[88:91]
	v_mfma_f32_16x16x32_bf16 v[80:83], v[166:169], v[212:215], v[80:83]
	v_mfma_f32_16x16x32_bf16 v[72:75], v[174:177], v[212:215], v[72:75]
	v_mfma_f32_16x16x32_bf16 v[68:71], v[166:169], v[220:223], v[68:71]
	v_mfma_f32_16x16x32_bf16 v[64:67], v[174:177], v[220:223], v[64:67]
	v_mfma_f32_16x16x32_bf16 v[112:115], v[170:173], v[192:195], v[112:115]
	v_mfma_f32_16x16x32_bf16 v[104:107], v[184:187], v[192:195], v[104:107]
	v_mfma_f32_16x16x32_bf16 v[96:99], v[170:173], v[208:211], v[96:99]
	v_mfma_f32_16x16x32_bf16 v[88:91], v[184:187], v[208:211], v[88:91]
	v_mfma_f32_16x16x32_bf16 v[80:83], v[170:173], v[216:219], v[80:83]
	v_mfma_f32_16x16x32_bf16 v[72:75], v[184:187], v[216:219], v[72:75]
	v_mfma_f32_16x16x32_bf16 v[68:71], v[170:173], v[224:227], v[68:71]
	v_mfma_f32_16x16x32_bf16 v[64:67], v[184:187], v[224:227], v[64:67]
	s_setprio 0
	s_barrier
	s_mov_b32 m0, s88
	v_lshl_add_u64 v[142:143], v[142:143], 0, s[10:11]
	ds_read_b128 v[188:191], v149 offset:49152
	ds_read_b128 v[192:195], v149 offset:50176
	ds_read_b128 v[196:199], v149 offset:51200
	ds_read_b128 v[208:211], v149 offset:52224
	ds_read_b128 v[212:215], v149 offset:53248
	ds_read_b128 v[216:219], v149 offset:54272
	ds_read_b128 v[220:223], v149 offset:55296
	ds_read_b128 v[224:227], v149 offset:56320
	global_load_lds_dwordx4 v[142:143], off
	v_lshl_add_u64 v[142:143], v[178:179], 0, s[10:11]
	s_mov_b32 m0, s87
	s_nop 0
	global_load_lds_dwordx4 v[142:143], off
	v_lshl_add_u64 v[142:143], s[40:41], 0, v[132:133]
	s_mov_b32 m0, s95
	s_nop 0
	global_load_lds_dwordx4 v[142:143], off
	v_lshl_add_u64 v[142:143], s[40:41], 0, v[128:129]
	s_mov_b32 m0, s94
	s_nop 0
	global_load_lds_dwordx4 v[142:143], off
	v_lshl_add_u64 v[142:143], v[200:201], 0, s[10:11]
	s_mov_b32 m0, s69
	s_nop 0
	global_load_lds_dwordx4 v[142:143], off
	v_lshl_add_u64 v[142:143], v[228:229], 0, s[10:11]
	s_mov_b32 m0, s70
	s_nop 0
	global_load_lds_dwordx4 v[142:143], off
	s_waitcnt vmcnt(8)
	s_waitcnt lgkmcnt(0)
	s_barrier
	s_setprio 1
	s_waitcnt lgkmcnt(0)
	v_mfma_f32_16x16x32_bf16 v[60:63], v[150:153], v[188:191], v[60:63]
	v_mfma_f32_16x16x32_bf16 v[56:59], v[158:161], v[188:191], v[56:59]
	v_mfma_f32_16x16x32_bf16 v[52:55], v[150:153], v[196:199], v[52:55]
	v_mfma_f32_16x16x32_bf16 v[44:47], v[158:161], v[196:199], v[44:47]
	v_mfma_f32_16x16x32_bf16 v[36:39], v[150:153], v[212:215], v[36:39]
	v_mfma_f32_16x16x32_bf16 v[28:31], v[158:161], v[212:215], v[28:31]
	v_mfma_f32_16x16x32_bf16 v[20:23], v[150:153], v[220:223], v[20:23]
	v_mfma_f32_16x16x32_bf16 v[12:15], v[158:161], v[220:223], v[12:15]
	v_mfma_f32_16x16x32_bf16 v[60:63], v[154:157], v[192:195], v[60:63]
	v_mfma_f32_16x16x32_bf16 v[56:59], v[162:165], v[192:195], v[56:59]
	v_mfma_f32_16x16x32_bf16 v[52:55], v[154:157], v[208:211], v[52:55]
	v_mfma_f32_16x16x32_bf16 v[44:47], v[162:165], v[208:211], v[44:47]
	v_mfma_f32_16x16x32_bf16 v[36:39], v[154:157], v[216:219], v[36:39]
	v_mfma_f32_16x16x32_bf16 v[28:31], v[162:165], v[216:219], v[28:31]
	v_mfma_f32_16x16x32_bf16 v[20:23], v[154:157], v[224:227], v[20:23]
	v_mfma_f32_16x16x32_bf16 v[12:15], v[162:165], v[224:227], v[12:15]
	v_mfma_f32_16x16x32_bf16 v[48:51], v[166:169], v[188:191], v[48:51]
	v_mfma_f32_16x16x32_bf16 v[40:43], v[174:177], v[188:191], v[40:43]
	v_mfma_f32_16x16x32_bf16 v[32:35], v[166:169], v[196:199], v[32:35]
	v_mfma_f32_16x16x32_bf16 v[24:27], v[174:177], v[196:199], v[24:27]
	v_mfma_f32_16x16x32_bf16 v[16:19], v[166:169], v[212:215], v[16:19]
	v_mfma_f32_16x16x32_bf16 v[8:11], v[174:177], v[212:215], v[8:11]
	v_mfma_f32_16x16x32_bf16 v[4:7], v[166:169], v[220:223], v[4:7]
	v_mfma_f32_16x16x32_bf16 v[0:3], v[174:177], v[220:223], v[0:3]
	v_mfma_f32_16x16x32_bf16 v[48:51], v[170:173], v[192:195], v[48:51]
	v_mfma_f32_16x16x32_bf16 v[40:43], v[184:187], v[192:195], v[40:43]
	v_mfma_f32_16x16x32_bf16 v[32:35], v[170:173], v[208:211], v[32:35]
	v_mfma_f32_16x16x32_bf16 v[24:27], v[184:187], v[208:211], v[24:27]
	v_mfma_f32_16x16x32_bf16 v[16:19], v[170:173], v[216:219], v[16:19]
	v_mfma_f32_16x16x32_bf16 v[8:11], v[184:187], v[216:219], v[8:11]
	v_mfma_f32_16x16x32_bf16 v[4:7], v[170:173], v[224:227], v[4:7]
	v_mfma_f32_16x16x32_bf16 v[0:3], v[184:187], v[224:227], v[0:3]
	s_setprio 0
	s_barrier
	s_movk_i32 s42, 0x100
	s_andn2_b64 vcc, exec, s[38:39]
	s_mov_b64 s[40:41], -1
	s_mov_b64 s[38:39], 0
	s_cbranch_vccz .LBB0_2502
	s_and_b64 vcc, exec, s[12:13]
	s_cbranch_vccz .LBB0_2505
	s_barrier

.LBB0_2666:
	ds_read_b128 v[136:139], v145
	ds_read_b128 v[150:153], v145 offset:1024
	ds_read_b128 v[154:157], v145 offset:2048
	ds_read_b128 v[158:161], v145 offset:3072
	ds_read_b128 v[162:165], v146
	ds_read_b128 v[166:169], v146 offset:1024
	ds_read_b128 v[170:173], v146 offset:2048
	ds_read_b128 v[174:177], v146 offset:3072
	s_add_i32 s87, s48, 2
	s_add_u32 s49, s46, 0xfffc0080
	s_addc_u32 s60, s47, -1
	s_cmp_eq_u32 s31, s48
	s_cselect_b32 s48, s40, s35
	s_cselect_b32 s61, s39, s60
	s_cselect_b32 s60, s38, s49
	s_cselect_b32 s49, s41, s37
	v_lshl_add_u64 v[140:141], s[46:47], 0, v[134:135]
	s_add_i32 m0, s45, 0xc000
	ds_read_b128 v[184:187], v147
	ds_read_b128 v[188:191], v147 offset:1024
	ds_read_b128 v[192:195], v147 offset:2048
	ds_read_b128 v[196:199], v147 offset:3072
	ds_read_b128 v[200:203], v147 offset:4096
	ds_read_b128 v[204:207], v147 offset:5120
	ds_read_b128 v[208:211], v147 offset:6144
	ds_read_b128 v[212:215], v147 offset:7168
	global_load_lds_dwordx4 v[140:141], off
	v_lshl_add_u64 v[140:141], s[46:47], 0, v[132:133]
	s_add_i32 m0, s45, 0xe000
	s_nop 0
	global_load_lds_dwordx4 v[140:141], off
	s_waitcnt vmcnt(8)
	s_waitcnt lgkmcnt(0)
	s_barrier
	s_setprio 1
	s_waitcnt lgkmcnt(0)
	v_mfma_f32_16x16x32_bf16 v[124:127], v[136:139], v[184:187], v[124:127]
	v_mfma_f32_16x16x32_bf16 v[120:123], v[154:157], v[184:187], v[120:123]
	v_mfma_f32_16x16x32_bf16 v[116:119], v[136:139], v[192:195], v[116:119]
	v_mfma_f32_16x16x32_bf16 v[112:115], v[154:157], v[192:195], v[112:115]
	v_mfma_f32_16x16x32_bf16 v[104:107], v[136:139], v[200:203], v[104:107]
	v_mfma_f32_16x16x32_bf16 v[96:99], v[154:157], v[200:203], v[96:99]
	v_mfma_f32_16x16x32_bf16 v[88:91], v[136:139], v[208:211], v[88:91]
	v_mfma_f32_16x16x32_bf16 v[80:83], v[154:157], v[208:211], v[80:83]
	v_mfma_f32_16x16x32_bf16 v[124:127], v[150:153], v[188:191], v[124:127]
	v_mfma_f32_16x16x32_bf16 v[120:123], v[158:161], v[188:191], v[120:123]
	v_mfma_f32_16x16x32_bf16 v[116:119], v[150:153], v[196:199], v[116:119]
	v_mfma_f32_16x16x32_bf16 v[112:115], v[158:161], v[196:199], v[112:115]
	v_mfma_f32_16x16x32_bf16 v[104:107], v[150:153], v[204:207], v[104:107]
	v_mfma_f32_16x16x32_bf16 v[96:99], v[158:161], v[204:207], v[96:99]
	v_mfma_f32_16x16x32_bf16 v[88:91], v[150:153], v[212:215], v[88:91]
	v_mfma_f32_16x16x32_bf16 v[80:83], v[158:161], v[212:215], v[80:83]
	v_mfma_f32_16x16x32_bf16 v[108:111], v[162:165], v[184:187], v[108:111]
	v_mfma_f32_16x16x32_bf16 v[100:103], v[170:173], v[184:187], v[100:103]
	v_mfma_f32_16x16x32_bf16 v[92:95], v[162:165], v[192:195], v[92:95]
	v_mfma_f32_16x16x32_bf16 v[84:87], v[170:173], v[192:195], v[84:87]
	v_mfma_f32_16x16x32_bf16 v[76:79], v[162:165], v[200:203], v[76:79]
	v_mfma_f32_16x16x32_bf16 v[72:75], v[170:173], v[200:203], v[72:75]
	v_mfma_f32_16x16x32_bf16 v[68:71], v[162:165], v[208:211], v[68:71]
	v_mfma_f32_16x16x32_bf16 v[64:67], v[170:173], v[208:211], v[64:67]
	v_mfma_f32_16x16x32_bf16 v[108:111], v[166:169], v[188:191], v[108:111]
	v_mfma_f32_16x16x32_bf16 v[100:103], v[174:177], v[188:191], v[100:103]
	v_mfma_f32_16x16x32_bf16 v[92:95], v[166:169], v[196:199], v[92:95]
	v_mfma_f32_16x16x32_bf16 v[84:87], v[174:177], v[196:199], v[84:87]
	v_mfma_f32_16x16x32_bf16 v[76:79], v[166:169], v[204:207], v[76:79]
	v_mfma_f32_16x16x32_bf16 v[72:75], v[174:177], v[204:207], v[72:75]
	v_mfma_f32_16x16x32_bf16 v[68:71], v[166:169], v[212:215], v[68:71]
	v_mfma_f32_16x16x32_bf16 v[64:67], v[174:177], v[212:215], v[64:67]
	s_setprio 0
	s_barrier
	s_add_i32 s76, s83, s63
	v_lshl_add_u64 v[140:141], s[48:49], 0, v[128:129]
	s_mov_b32 m0, s76
	ds_read_b128 v[184:187], v147 offset:16384
	ds_read_b128 v[188:191], v147 offset:17408
	ds_read_b128 v[192:195], v147 offset:18432
	ds_read_b128 v[196:199], v147 offset:19456
	ds_read_b128 v[200:203], v147 offset:20480
	ds_read_b128 v[204:207], v147 offset:21504
	ds_read_b128 v[208:211], v147 offset:22528
	ds_read_b128 v[212:215], v147 offset:23552
	global_load_lds_dwordx4 v[140:141], off
	s_add_i32 m0, s76, 0x2000
	s_add_u32 s88, s48, 0x40000
	v_lshl_add_u64 v[178:179], s[48:49], 0, v[130:131]
	s_addc_u32 s89, s49, 0
	s_add_i32 s76, s84, s63
	global_load_lds_dwordx4 v[178:179], off
	v_lshl_add_u64 v[216:217], s[88:89], 0, v[128:129]
	s_mov_b32 m0, s76
	v_lshl_add_u64 v[218:219], s[60:61], 0, v[130:131]
	global_load_lds_dwordx4 v[216:217], off
	v_lshl_add_u64 v[216:217], s[88:89], 0, v[130:131]
	s_add_i32 m0, s76, 0x2000
	s_nop 0
	global_load_lds_dwordx4 v[216:217], off
	v_lshl_add_u64 v[216:217], s[60:61], 0, v[128:129]
	s_mov_b32 m0, s45
	s_nop 0
	global_load_lds_dwordx4 v[216:217], off
	s_mov_b32 m0, s64
	s_nop 0
	global_load_lds_dwordx4 v[218:219], off
	s_waitcnt vmcnt(8)
	s_waitcnt lgkmcnt(0)
	s_barrier
	s_setprio 1
	s_waitcnt lgkmcnt(0)
	v_mfma_f32_16x16x32_bf16 v[60:63], v[136:139], v[184:187], v[60:63]
	v_mfma_f32_16x16x32_bf16 v[56:59], v[154:157], v[184:187], v[56:59]
	v_mfma_f32_16x16x32_bf16 v[52:55], v[136:139], v[192:195], v[52:55]
	v_mfma_f32_16x16x32_bf16 v[48:51], v[154:157], v[192:195], v[48:51]
	v_mfma_f32_16x16x32_bf16 v[40:43], v[136:139], v[200:203], v[40:43]
	v_mfma_f32_16x16x32_bf16 v[32:35], v[154:157], v[200:203], v[32:35]
	v_mfma_f32_16x16x32_bf16 v[24:27], v[136:139], v[208:211], v[24:27]
	v_mfma_f32_16x16x32_bf16 v[16:19], v[154:157], v[208:211], v[16:19]
	v_mfma_f32_16x16x32_bf16 v[60:63], v[150:153], v[188:191], v[60:63]
	v_mfma_f32_16x16x32_bf16 v[56:59], v[158:161], v[188:191], v[56:59]
	v_mfma_f32_16x16x32_bf16 v[52:55], v[150:153], v[196:199], v[52:55]
	v_mfma_f32_16x16x32_bf16 v[48:51], v[158:161], v[196:199], v[48:51]
	v_mfma_f32_16x16x32_bf16 v[40:43], v[150:153], v[204:207], v[40:43]
	v_mfma_f32_16x16x32_bf16 v[32:35], v[158:161], v[204:207], v[32:35]
	v_mfma_f32_16x16x32_bf16 v[24:27], v[150:153], v[212:215], v[24:27]
	v_mfma_f32_16x16x32_bf16 v[16:19], v[158:161], v[212:215], v[16:19]
	v_mfma_f32_16x16x32_bf16 v[44:47], v[162:165], v[184:187], v[44:47]
	v_mfma_f32_16x16x32_bf16 v[36:39], v[170:173], v[184:187], v[36:39]
	v_mfma_f32_16x16x32_bf16 v[28:31], v[162:165], v[192:195], v[28:31]
	v_mfma_f32_16x16x32_bf16 v[20:23], v[170:173], v[192:195], v[20:23]
	v_mfma_f32_16x16x32_bf16 v[12:15], v[162:165], v[200:203], v[12:15]
	v_mfma_f32_16x16x32_bf16 v[8:11], v[170:173], v[200:203], v[8:11]
	v_mfma_f32_16x16x32_bf16 v[4:7], v[162:165], v[208:211], v[4:7]
	v_mfma_f32_16x16x32_bf16 v[0:3], v[170:173], v[208:211], v[0:3]
	v_mfma_f32_16x16x32_bf16 v[44:47], v[166:169], v[188:191], v[44:47]
	v_mfma_f32_16x16x32_bf16 v[36:39], v[174:177], v[188:191], v[36:39]
	v_mfma_f32_16x16x32_bf16 v[28:31], v[166:169], v[196:199], v[28:31]
	v_mfma_f32_16x16x32_bf16 v[20:23], v[174:177], v[196:199], v[20:23]
	v_mfma_f32_16x16x32_bf16 v[12:15], v[166:169], v[204:207], v[12:15]
	v_mfma_f32_16x16x32_bf16 v[8:11], v[174:177], v[204:207], v[8:11]
	v_mfma_f32_16x16x32_bf16 v[4:7], v[166:169], v[212:215], v[4:7]
	v_mfma_f32_16x16x32_bf16 v[0:3], v[174:177], v[212:215], v[0:3]
	s_setprio 0
	s_barrier
	s_add_i32 s76, 0, 0x18000
	v_add_u32_e32 v149, s76, v143
	s_add_i32 s88, 0, 0x1c000
	ds_read_b128 v[136:139], v149
	ds_read_b128 v[150:153], v149 offset:1024
	ds_read_b128 v[154:157], v149 offset:2048
	ds_read_b128 v[158:161], v149 offset:3072
	v_add_u32_e32 v149, s88, v143
	ds_read_b128 v[162:165], v149
	ds_read_b128 v[166:169], v149 offset:1024
	ds_read_b128 v[170:173], v149 offset:2048
	ds_read_b128 v[174:177], v149 offset:3072
	s_add_u32 s60, s60, 0x40000
	s_addc_u32 s61, s61, 0
	s_mov_b32 m0, s65
	v_lshl_add_u64 v[220:221], s[60:61], 0, v[128:129]
	ds_read_b128 v[184:187], v147 offset:32768
	ds_read_b128 v[188:191], v147 offset:33792
	ds_read_b128 v[192:195], v147 offset:34816
	ds_read_b128 v[196:199], v147 offset:35840
	ds_read_b128 v[200:203], v147 offset:36864
	ds_read_b128 v[204:207], v147 offset:37888
	ds_read_b128 v[208:211], v147 offset:38912
	ds_read_b128 v[212:215], v147 offset:39936
	global_load_lds_dwordx4 v[220:221], off
	v_lshl_add_u64 v[220:221], s[60:61], 0, v[130:131]
	s_mov_b32 m0, s66
	s_nop 0
	global_load_lds_dwordx4 v[220:221], off
	s_waitcnt vmcnt(8)
	s_waitcnt lgkmcnt(0)
	s_barrier
	s_setprio 1
	s_waitcnt lgkmcnt(0)
	v_mfma_f32_16x16x32_bf16 v[124:127], v[136:139], v[184:187], v[124:127]
	v_mfma_f32_16x16x32_bf16 v[120:123], v[154:157], v[184:187], v[120:123]
	v_mfma_f32_16x16x32_bf16 v[116:119], v[136:139], v[192:195], v[116:119]
	v_mfma_f32_16x16x32_bf16 v[112:115], v[154:157], v[192:195], v[112:115]
	v_mfma_f32_16x16x32_bf16 v[104:107], v[136:139], v[200:203], v[104:107]
	v_mfma_f32_16x16x32_bf16 v[96:99], v[154:157], v[200:203], v[96:99]
	v_mfma_f32_16x16x32_bf16 v[88:91], v[136:139], v[208:211], v[88:91]
	v_mfma_f32_16x16x32_bf16 v[80:83], v[154:157], v[208:211], v[80:83]
	v_mfma_f32_16x16x32_bf16 v[124:127], v[150:153], v[188:191], v[124:127]
	v_mfma_f32_16x16x32_bf16 v[120:123], v[158:161], v[188:191], v[120:123]
	v_mfma_f32_16x16x32_bf16 v[116:119], v[150:153], v[196:199], v[116:119]
	v_mfma_f32_16x16x32_bf16 v[112:115], v[158:161], v[196:199], v[112:115]
	v_mfma_f32_16x16x32_bf16 v[104:107], v[150:153], v[204:207], v[104:107]
	v_mfma_f32_16x16x32_bf16 v[96:99], v[158:161], v[204:207], v[96:99]
	v_mfma_f32_16x16x32_bf16 v[88:91], v[150:153], v[212:215], v[88:91]
	v_mfma_f32_16x16x32_bf16 v[80:83], v[158:161], v[212:215], v[80:83]
	v_mfma_f32_16x16x32_bf16 v[108:111], v[162:165], v[184:187], v[108:111]
	v_mfma_f32_16x16x32_bf16 v[100:103], v[170:173], v[184:187], v[100:103]
	v_mfma_f32_16x16x32_bf16 v[92:95], v[162:165], v[192:195], v[92:95]
	v_mfma_f32_16x16x32_bf16 v[84:87], v[170:173], v[192:195], v[84:87]
	v_mfma_f32_16x16x32_bf16 v[76:79], v[162:165], v[200:203], v[76:79]
	v_mfma_f32_16x16x32_bf16 v[72:75], v[170:173], v[200:203], v[72:75]
	v_mfma_f32_16x16x32_bf16 v[68:71], v[162:165], v[208:211], v[68:71]
	v_mfma_f32_16x16x32_bf16 v[64:67], v[170:173], v[208:211], v[64:67]
	v_mfma_f32_16x16x32_bf16 v[108:111], v[166:169], v[188:191], v[108:111]
	v_mfma_f32_16x16x32_bf16 v[100:103], v[174:177], v[188:191], v[100:103]
	v_mfma_f32_16x16x32_bf16 v[92:95], v[166:169], v[196:199], v[92:95]
	v_mfma_f32_16x16x32_bf16 v[84:87], v[174:177], v[196:199], v[84:87]
	v_mfma_f32_16x16x32_bf16 v[76:79], v[166:169], v[204:207], v[76:79]
	v_mfma_f32_16x16x32_bf16 v[72:75], v[174:177], v[204:207], v[72:75]
	v_mfma_f32_16x16x32_bf16 v[68:71], v[166:169], v[212:215], v[68:71]
	v_mfma_f32_16x16x32_bf16 v[64:67], v[174:177], v[212:215], v[64:67]
	s_setprio 0
	s_barrier
	s_add_i32 s60, s76, s63
	v_lshl_add_u64 v[140:141], v[140:141], 0, s[26:27]
	s_mov_b32 m0, s60
	ds_read_b128 v[184:187], v147 offset:49152
	ds_read_b128 v[188:191], v147 offset:50176
	ds_read_b128 v[192:195], v147 offset:51200
	ds_read_b128 v[196:199], v147 offset:52224
	ds_read_b128 v[200:203], v147 offset:53248
	ds_read_b128 v[204:207], v147 offset:54272
	ds_read_b128 v[208:211], v147 offset:55296
	ds_read_b128 v[212:215], v147 offset:56320
	global_load_lds_dwordx4 v[140:141], off
	s_add_i32 m0, s60, 0x2000
	s_add_u32 s48, s48, 0x40080
	v_lshl_add_u64 v[140:141], v[178:179], 0, s[26:27]
	s_addc_u32 s49, s49, 0
	s_add_i32 s60, s88, s63
	global_load_lds_dwordx4 v[140:141], off
	v_lshl_add_u64 v[140:141], s[48:49], 0, v[128:129]
	s_mov_b32 m0, s60
	s_nop 0
	global_load_lds_dwordx4 v[140:141], off
	v_lshl_add_u64 v[140:141], s[48:49], 0, v[130:131]
	s_add_i32 m0, s60, 0x2000
	s_nop 0
	global_load_lds_dwordx4 v[140:141], off
	v_lshl_add_u64 v[140:141], v[216:217], 0, s[26:27]
	s_mov_b32 m0, s69
	s_nop 0
	global_load_lds_dwordx4 v[140:141], off
	v_lshl_add_u64 v[140:141], v[218:219], 0, s[26:27]
	s_mov_b32 m0, s70
	s_nop 0
	global_load_lds_dwordx4 v[140:141], off
	s_waitcnt vmcnt(8)
	s_waitcnt lgkmcnt(0)
	s_barrier
	s_setprio 1
	s_waitcnt lgkmcnt(0)
	v_mfma_f32_16x16x32_bf16 v[60:63], v[136:139], v[184:187], v[60:63]
	v_mfma_f32_16x16x32_bf16 v[56:59], v[154:157], v[184:187], v[56:59]
	v_mfma_f32_16x16x32_bf16 v[52:55], v[136:139], v[192:195], v[52:55]
	v_mfma_f32_16x16x32_bf16 v[48:51], v[154:157], v[192:195], v[48:51]
	v_mfma_f32_16x16x32_bf16 v[40:43], v[136:139], v[200:203], v[40:43]
	v_mfma_f32_16x16x32_bf16 v[32:35], v[154:157], v[200:203], v[32:35]
	v_mfma_f32_16x16x32_bf16 v[24:27], v[136:139], v[208:211], v[24:27]
	v_mfma_f32_16x16x32_bf16 v[16:19], v[154:157], v[208:211], v[16:19]
	v_mfma_f32_16x16x32_bf16 v[60:63], v[150:153], v[188:191], v[60:63]
	v_mfma_f32_16x16x32_bf16 v[56:59], v[158:161], v[188:191], v[56:59]
	v_mfma_f32_16x16x32_bf16 v[52:55], v[150:153], v[196:199], v[52:55]
	v_mfma_f32_16x16x32_bf16 v[48:51], v[158:161], v[196:199], v[48:51]
	v_mfma_f32_16x16x32_bf16 v[40:43], v[150:153], v[204:207], v[40:43]
	v_mfma_f32_16x16x32_bf16 v[32:35], v[158:161], v[204:207], v[32:35]
	v_mfma_f32_16x16x32_bf16 v[24:27], v[150:153], v[212:215], v[24:27]
	v_mfma_f32_16x16x32_bf16 v[16:19], v[158:161], v[212:215], v[16:19]
	v_mfma_f32_16x16x32_bf16 v[44:47], v[162:165], v[184:187], v[44:47]
	v_mfma_f32_16x16x32_bf16 v[36:39], v[170:173], v[184:187], v[36:39]
	v_mfma_f32_16x16x32_bf16 v[28:31], v[162:165], v[192:195], v[28:31]
	v_mfma_f32_16x16x32_bf16 v[20:23], v[170:173], v[192:195], v[20:23]
	v_mfma_f32_16x16x32_bf16 v[12:15], v[162:165], v[200:203], v[12:15]
	v_mfma_f32_16x16x32_bf16 v[8:11], v[170:173], v[200:203], v[8:11]
	v_mfma_f32_16x16x32_bf16 v[4:7], v[162:165], v[208:211], v[4:7]
	v_mfma_f32_16x16x32_bf16 v[0:3], v[170:173], v[208:211], v[0:3]
	v_mfma_f32_16x16x32_bf16 v[44:47], v[166:169], v[188:191], v[44:47]
	v_mfma_f32_16x16x32_bf16 v[36:39], v[174:177], v[188:191], v[36:39]
	v_mfma_f32_16x16x32_bf16 v[28:31], v[166:169], v[196:199], v[28:31]
	v_mfma_f32_16x16x32_bf16 v[20:23], v[174:177], v[196:199], v[20:23]
	v_mfma_f32_16x16x32_bf16 v[12:15], v[166:169], v[204:207], v[12:15]
	v_mfma_f32_16x16x32_bf16 v[8:11], v[174:177], v[204:207], v[8:11]
	v_mfma_f32_16x16x32_bf16 v[4:7], v[166:169], v[212:215], v[4:7]
	v_mfma_f32_16x16x32_bf16 v[0:3], v[174:177], v[212:215], v[0:3]
	s_setprio 0
	s_barrier
	s_add_u32 s35, s35, 0x100
	s_addc_u32 s37, s37, 0
	s_add_u32 s46, s46, 0x100
	s_addc_u32 s47, s47, 0
	s_cmp_ge_i32 s87, s43
	s_mov_b32 s48, s87
	s_cbranch_scc0 .LBB0_2666
	s_and_b64 vcc, exec, s[28:29]
	s_cbranch_vccz .LBB0_2669
	s_barrier

.LBB0_2890:
	ds_read_b128 v[136:139], v147
	ds_read_b128 v[140:143], v147 offset:1024
	ds_read_b128 v[150:153], v147 offset:2048
	ds_read_b128 v[154:157], v147 offset:3072
	ds_read_b128 v[158:161], v148
	ds_read_b128 v[162:165], v148 offset:1024
	ds_read_b128 v[166:169], v148 offset:2048
	ds_read_b128 v[170:173], v148 offset:3072
	s_add_i32 s94, s42, 2
	s_add_u32 s43, s40, 0xfff50080
	s_addc_u32 s44, s41, -1
	s_cmp_eq_u32 s35, s42
	s_cselect_b32 s42, s38, s92
	s_cselect_b32 s45, s37, s44
	s_cselect_b32 s44, s36, s43
	s_cselect_b32 s43, s39, s93
	v_lshl_add_u64 v[178:179], s[40:41], 0, v[134:135]
	s_add_i32 m0, s57, 0xc000
	ds_read_b128 v[174:177], v149
	ds_read_b128 v[182:185], v149 offset:1024
	ds_read_b128 v[186:189], v149 offset:2048
	ds_read_b128 v[190:193], v149 offset:3072
	ds_read_b128 v[194:197], v149 offset:4096
	ds_read_b128 v[198:201], v149 offset:5120
	ds_read_b128 v[202:205], v149 offset:6144
	ds_read_b128 v[206:209], v149 offset:7168
	global_load_lds_dwordx4 v[178:179], off
	v_lshl_add_u64 v[178:179], s[40:41], 0, v[132:133]
	s_add_i32 m0, s57, 0xe000
	s_nop 0
	global_load_lds_dwordx4 v[178:179], off
	s_waitcnt vmcnt(8)
	s_waitcnt lgkmcnt(0)
	s_barrier
	s_setprio 1
	s_waitcnt lgkmcnt(0)
	v_mfma_f32_16x16x32_bf16 v[124:127], v[136:139], v[174:177], v[124:127]
	v_mfma_f32_16x16x32_bf16 v[120:123], v[150:153], v[174:177], v[120:123]
	v_mfma_f32_16x16x32_bf16 v[108:111], v[136:139], v[186:189], v[108:111]
	v_mfma_f32_16x16x32_bf16 v[104:107], v[150:153], v[186:189], v[104:107]
	v_mfma_f32_16x16x32_bf16 v[92:95], v[136:139], v[194:197], v[92:95]
	v_mfma_f32_16x16x32_bf16 v[88:91], v[150:153], v[194:197], v[88:91]
	v_mfma_f32_16x16x32_bf16 v[76:79], v[136:139], v[202:205], v[76:79]
	v_mfma_f32_16x16x32_bf16 v[72:75], v[150:153], v[202:205], v[72:75]
	v_mfma_f32_16x16x32_bf16 v[124:127], v[140:143], v[182:185], v[124:127]
	v_mfma_f32_16x16x32_bf16 v[120:123], v[154:157], v[182:185], v[120:123]
	v_mfma_f32_16x16x32_bf16 v[108:111], v[140:143], v[190:193], v[108:111]
	v_mfma_f32_16x16x32_bf16 v[104:107], v[154:157], v[190:193], v[104:107]
	v_mfma_f32_16x16x32_bf16 v[92:95], v[140:143], v[198:201], v[92:95]
	v_mfma_f32_16x16x32_bf16 v[88:91], v[154:157], v[198:201], v[88:91]
	v_mfma_f32_16x16x32_bf16 v[76:79], v[140:143], v[206:209], v[76:79]
	v_mfma_f32_16x16x32_bf16 v[72:75], v[154:157], v[206:209], v[72:75]
	v_mfma_f32_16x16x32_bf16 v[116:119], v[158:161], v[174:177], v[116:119]
	v_mfma_f32_16x16x32_bf16 v[112:115], v[166:169], v[174:177], v[112:115]
	v_mfma_f32_16x16x32_bf16 v[100:103], v[158:161], v[186:189], v[100:103]
	v_mfma_f32_16x16x32_bf16 v[96:99], v[166:169], v[186:189], v[96:99]
	v_mfma_f32_16x16x32_bf16 v[84:87], v[158:161], v[194:197], v[84:87]
	v_mfma_f32_16x16x32_bf16 v[80:83], v[166:169], v[194:197], v[80:83]
	v_mfma_f32_16x16x32_bf16 v[68:71], v[158:161], v[202:205], v[68:71]
	v_mfma_f32_16x16x32_bf16 v[64:67], v[166:169], v[202:205], v[64:67]
	v_mfma_f32_16x16x32_bf16 v[116:119], v[162:165], v[182:185], v[116:119]
	v_mfma_f32_16x16x32_bf16 v[112:115], v[170:173], v[182:185], v[112:115]
	v_mfma_f32_16x16x32_bf16 v[100:103], v[162:165], v[190:193], v[100:103]
	v_mfma_f32_16x16x32_bf16 v[96:99], v[170:173], v[190:193], v[96:99]
	v_mfma_f32_16x16x32_bf16 v[84:87], v[162:165], v[198:201], v[84:87]
	v_mfma_f32_16x16x32_bf16 v[80:83], v[170:173], v[198:201], v[80:83]
	v_mfma_f32_16x16x32_bf16 v[68:71], v[162:165], v[206:209], v[68:71]
	v_mfma_f32_16x16x32_bf16 v[64:67], v[170:173], v[206:209], v[64:67]
	s_setprio 0
	s_barrier
	s_add_i32 s76, s79, s49
	v_lshl_add_u64 v[178:179], s[42:43], 0, v[128:129]
	s_mov_b32 m0, s76
	ds_read_b128 v[174:177], v149 offset:16384
	ds_read_b128 v[182:185], v149 offset:17408
	ds_read_b128 v[186:189], v149 offset:18432
	ds_read_b128 v[190:193], v149 offset:19456
	ds_read_b128 v[194:197], v149 offset:20480
	ds_read_b128 v[198:201], v149 offset:21504
	ds_read_b128 v[202:205], v149 offset:22528
	ds_read_b128 v[206:209], v149 offset:23552
	global_load_lds_dwordx4 v[178:179], off
	s_add_i32 m0, s76, 0x2000
	s_add_u32 s96, s42, 0xb0000
	v_lshl_add_u64 v[210:211], s[42:43], 0, v[130:131]
	s_addc_u32 s97, s43, 0
	s_add_i32 s76, s80, s49
	global_load_lds_dwordx4 v[210:211], off
	v_lshl_add_u64 v[212:213], s[96:97], 0, v[128:129]
	s_mov_b32 m0, s76
	v_lshl_add_u64 v[214:215], s[44:45], 0, v[130:131]
	global_load_lds_dwordx4 v[212:213], off
	v_lshl_add_u64 v[212:213], s[96:97], 0, v[130:131]
	s_add_i32 m0, s76, 0x2000
	s_nop 0
	global_load_lds_dwordx4 v[212:213], off
	v_lshl_add_u64 v[212:213], s[44:45], 0, v[128:129]
	s_mov_b32 m0, s57
	s_nop 0
	global_load_lds_dwordx4 v[212:213], off
	s_mov_b32 m0, s59
	s_nop 0
	global_load_lds_dwordx4 v[214:215], off
	s_waitcnt vmcnt(8)
	s_waitcnt lgkmcnt(0)
	s_barrier
	s_setprio 1
	s_waitcnt lgkmcnt(0)
	v_mfma_f32_16x16x32_bf16 v[60:63], v[136:139], v[174:177], v[60:63]
	v_mfma_f32_16x16x32_bf16 v[56:59], v[150:153], v[174:177], v[56:59]
	v_mfma_f32_16x16x32_bf16 v[44:47], v[136:139], v[186:189], v[44:47]
	v_mfma_f32_16x16x32_bf16 v[40:43], v[150:153], v[186:189], v[40:43]
	v_mfma_f32_16x16x32_bf16 v[28:31], v[136:139], v[194:197], v[28:31]
	v_mfma_f32_16x16x32_bf16 v[24:27], v[150:153], v[194:197], v[24:27]
	v_mfma_f32_16x16x32_bf16 v[12:15], v[136:139], v[202:205], v[12:15]
	v_mfma_f32_16x16x32_bf16 v[8:11], v[150:153], v[202:205], v[8:11]
	v_mfma_f32_16x16x32_bf16 v[60:63], v[140:143], v[182:185], v[60:63]
	v_mfma_f32_16x16x32_bf16 v[56:59], v[154:157], v[182:185], v[56:59]
	v_mfma_f32_16x16x32_bf16 v[44:47], v[140:143], v[190:193], v[44:47]
	v_mfma_f32_16x16x32_bf16 v[40:43], v[154:157], v[190:193], v[40:43]
	v_mfma_f32_16x16x32_bf16 v[28:31], v[140:143], v[198:201], v[28:31]
	v_mfma_f32_16x16x32_bf16 v[24:27], v[154:157], v[198:201], v[24:27]
	v_mfma_f32_16x16x32_bf16 v[12:15], v[140:143], v[206:209], v[12:15]
	v_mfma_f32_16x16x32_bf16 v[8:11], v[154:157], v[206:209], v[8:11]
	v_mfma_f32_16x16x32_bf16 v[52:55], v[158:161], v[174:177], v[52:55]
	v_mfma_f32_16x16x32_bf16 v[48:51], v[166:169], v[174:177], v[48:51]
	v_mfma_f32_16x16x32_bf16 v[36:39], v[158:161], v[186:189], v[36:39]
	v_mfma_f32_16x16x32_bf16 v[32:35], v[166:169], v[186:189], v[32:35]
	v_mfma_f32_16x16x32_bf16 v[20:23], v[158:161], v[194:197], v[20:23]
	v_mfma_f32_16x16x32_bf16 v[16:19], v[166:169], v[194:197], v[16:19]
	v_mfma_f32_16x16x32_bf16 v[4:7], v[158:161], v[202:205], v[4:7]
	v_mfma_f32_16x16x32_bf16 v[0:3], v[166:169], v[202:205], v[0:3]
	v_mfma_f32_16x16x32_bf16 v[52:55], v[162:165], v[182:185], v[52:55]
	v_mfma_f32_16x16x32_bf16 v[48:51], v[170:173], v[182:185], v[48:51]
	v_mfma_f32_16x16x32_bf16 v[36:39], v[162:165], v[190:193], v[36:39]
	v_mfma_f32_16x16x32_bf16 v[32:35], v[170:173], v[190:193], v[32:35]
	v_mfma_f32_16x16x32_bf16 v[20:23], v[162:165], v[198:201], v[20:23]
	v_mfma_f32_16x16x32_bf16 v[16:19], v[170:173], v[198:201], v[16:19]
	v_mfma_f32_16x16x32_bf16 v[4:7], v[162:165], v[206:209], v[4:7]
	v_mfma_f32_16x16x32_bf16 v[0:3], v[170:173], v[206:209], v[0:3]
	s_setprio 0
	s_barrier
	s_add_i32 s76, 0, 0x18000
	s_add_i32 s95, 0, 0x1c000
	v_add_u32_e32 v154, s76, v145
	v_add_u32_e32 v170, s95, v145
	ds_read_b128 v[136:139], v154
	ds_read_b128 v[140:143], v154 offset:1024
	ds_read_b128 v[150:153], v154 offset:2048
	ds_read_b128 v[154:157], v154 offset:3072
	ds_read_b128 v[158:161], v170
	ds_read_b128 v[162:165], v170 offset:1024
	ds_read_b128 v[166:169], v170 offset:2048
	ds_read_b128 v[170:173], v170 offset:3072
	s_add_u32 s44, s44, 0xb0000
	s_addc_u32 s45, s45, 0
	s_mov_b32 m0, s60
	v_lshl_add_u64 v[216:217], s[44:45], 0, v[128:129]
	ds_read_b128 v[174:177], v149 offset:32768
	ds_read_b128 v[182:185], v149 offset:33792
	ds_read_b128 v[186:189], v149 offset:34816
	ds_read_b128 v[190:193], v149 offset:35840
	ds_read_b128 v[194:197], v149 offset:36864
	ds_read_b128 v[198:201], v149 offset:37888
	ds_read_b128 v[202:205], v149 offset:38912
	ds_read_b128 v[206:209], v149 offset:39936
	global_load_lds_dwordx4 v[216:217], off
	v_lshl_add_u64 v[216:217], s[44:45], 0, v[130:131]
	s_mov_b32 m0, s61
	s_nop 0
	global_load_lds_dwordx4 v[216:217], off
	s_waitcnt vmcnt(8)
	s_waitcnt lgkmcnt(0)
	s_barrier
	s_setprio 1
	s_waitcnt lgkmcnt(0)
	v_mfma_f32_16x16x32_bf16 v[124:127], v[136:139], v[174:177], v[124:127]
	v_mfma_f32_16x16x32_bf16 v[120:123], v[150:153], v[174:177], v[120:123]
	v_mfma_f32_16x16x32_bf16 v[108:111], v[136:139], v[186:189], v[108:111]
	v_mfma_f32_16x16x32_bf16 v[104:107], v[150:153], v[186:189], v[104:107]
	v_mfma_f32_16x16x32_bf16 v[92:95], v[136:139], v[194:197], v[92:95]
	v_mfma_f32_16x16x32_bf16 v[88:91], v[150:153], v[194:197], v[88:91]
	v_mfma_f32_16x16x32_bf16 v[76:79], v[136:139], v[202:205], v[76:79]
	v_mfma_f32_16x16x32_bf16 v[72:75], v[150:153], v[202:205], v[72:75]
	v_mfma_f32_16x16x32_bf16 v[124:127], v[140:143], v[182:185], v[124:127]
	v_mfma_f32_16x16x32_bf16 v[120:123], v[154:157], v[182:185], v[120:123]
	v_mfma_f32_16x16x32_bf16 v[108:111], v[140:143], v[190:193], v[108:111]
	v_mfma_f32_16x16x32_bf16 v[104:107], v[154:157], v[190:193], v[104:107]
	v_mfma_f32_16x16x32_bf16 v[92:95], v[140:143], v[198:201], v[92:95]
	v_mfma_f32_16x16x32_bf16 v[88:91], v[154:157], v[198:201], v[88:91]
	v_mfma_f32_16x16x32_bf16 v[76:79], v[140:143], v[206:209], v[76:79]
	v_mfma_f32_16x16x32_bf16 v[72:75], v[154:157], v[206:209], v[72:75]
	v_mfma_f32_16x16x32_bf16 v[116:119], v[158:161], v[174:177], v[116:119]
	v_mfma_f32_16x16x32_bf16 v[112:115], v[166:169], v[174:177], v[112:115]
	v_mfma_f32_16x16x32_bf16 v[100:103], v[158:161], v[186:189], v[100:103]
	v_mfma_f32_16x16x32_bf16 v[96:99], v[166:169], v[186:189], v[96:99]
	v_mfma_f32_16x16x32_bf16 v[84:87], v[158:161], v[194:197], v[84:87]
	v_mfma_f32_16x16x32_bf16 v[80:83], v[166:169], v[194:197], v[80:83]
	v_mfma_f32_16x16x32_bf16 v[68:71], v[158:161], v[202:205], v[68:71]
	v_mfma_f32_16x16x32_bf16 v[64:67], v[166:169], v[202:205], v[64:67]
	v_mfma_f32_16x16x32_bf16 v[116:119], v[162:165], v[182:185], v[116:119]
	v_mfma_f32_16x16x32_bf16 v[112:115], v[170:173], v[182:185], v[112:115]
	v_mfma_f32_16x16x32_bf16 v[100:103], v[162:165], v[190:193], v[100:103]
	v_mfma_f32_16x16x32_bf16 v[96:99], v[170:173], v[190:193], v[96:99]
	v_mfma_f32_16x16x32_bf16 v[84:87], v[162:165], v[198:201], v[84:87]
	v_mfma_f32_16x16x32_bf16 v[80:83], v[170:173], v[198:201], v[80:83]
	v_mfma_f32_16x16x32_bf16 v[68:71], v[162:165], v[206:209], v[68:71]
	v_mfma_f32_16x16x32_bf16 v[64:67], v[170:173], v[206:209], v[64:67]
	s_setprio 0
	s_barrier
	s_add_i32 s44, s76, s49
	v_lshl_add_u64 v[178:179], v[178:179], 0, s[22:23]
	s_mov_b32 m0, s44
	ds_read_b128 v[174:177], v149 offset:49152
	ds_read_b128 v[182:185], v149 offset:50176
	ds_read_b128 v[186:189], v149 offset:51200
	ds_read_b128 v[190:193], v149 offset:52224
	ds_read_b128 v[194:197], v149 offset:53248
	ds_read_b128 v[198:201], v149 offset:54272
	ds_read_b128 v[202:205], v149 offset:55296
	ds_read_b128 v[206:209], v149 offset:56320
	global_load_lds_dwordx4 v[178:179], off
	s_add_i32 m0, s44, 0x2000
	s_add_u32 s42, s42, 0xb0080
	v_lshl_add_u64 v[178:179], v[210:211], 0, s[22:23]
	s_addc_u32 s43, s43, 0
	s_add_i32 s44, s95, s49
	global_load_lds_dwordx4 v[178:179], off
	v_lshl_add_u64 v[178:179], s[42:43], 0, v[128:129]
	s_mov_b32 m0, s44
	s_nop 0
	global_load_lds_dwordx4 v[178:179], off
	v_lshl_add_u64 v[178:179], s[42:43], 0, v[130:131]
	s_add_i32 m0, s44, 0x2000
	s_nop 0
	global_load_lds_dwordx4 v[178:179], off
	v_lshl_add_u64 v[178:179], v[212:213], 0, s[22:23]
	s_mov_b32 m0, s64
	s_nop 0
	global_load_lds_dwordx4 v[178:179], off
	v_lshl_add_u64 v[178:179], v[214:215], 0, s[22:23]
	s_mov_b32 m0, s65
	s_nop 0
	global_load_lds_dwordx4 v[178:179], off
	s_waitcnt vmcnt(8)
	s_waitcnt lgkmcnt(0)
	s_barrier
	s_setprio 1
	s_waitcnt lgkmcnt(0)
	v_mfma_f32_16x16x32_bf16 v[60:63], v[136:139], v[174:177], v[60:63]
	v_mfma_f32_16x16x32_bf16 v[56:59], v[150:153], v[174:177], v[56:59]
	v_mfma_f32_16x16x32_bf16 v[44:47], v[136:139], v[186:189], v[44:47]
	v_mfma_f32_16x16x32_bf16 v[40:43], v[150:153], v[186:189], v[40:43]
	v_mfma_f32_16x16x32_bf16 v[28:31], v[136:139], v[194:197], v[28:31]
	v_mfma_f32_16x16x32_bf16 v[24:27], v[150:153], v[194:197], v[24:27]
	v_mfma_f32_16x16x32_bf16 v[12:15], v[136:139], v[202:205], v[12:15]
	v_mfma_f32_16x16x32_bf16 v[8:11], v[150:153], v[202:205], v[8:11]
	v_mfma_f32_16x16x32_bf16 v[60:63], v[140:143], v[182:185], v[60:63]
	v_mfma_f32_16x16x32_bf16 v[56:59], v[154:157], v[182:185], v[56:59]
	v_mfma_f32_16x16x32_bf16 v[44:47], v[140:143], v[190:193], v[44:47]
	v_mfma_f32_16x16x32_bf16 v[40:43], v[154:157], v[190:193], v[40:43]
	v_mfma_f32_16x16x32_bf16 v[28:31], v[140:143], v[198:201], v[28:31]
	v_mfma_f32_16x16x32_bf16 v[24:27], v[154:157], v[198:201], v[24:27]
	v_mfma_f32_16x16x32_bf16 v[12:15], v[140:143], v[206:209], v[12:15]
	v_mfma_f32_16x16x32_bf16 v[8:11], v[154:157], v[206:209], v[8:11]
	v_mfma_f32_16x16x32_bf16 v[52:55], v[158:161], v[174:177], v[52:55]
	v_mfma_f32_16x16x32_bf16 v[48:51], v[166:169], v[174:177], v[48:51]
	v_mfma_f32_16x16x32_bf16 v[36:39], v[158:161], v[186:189], v[36:39]
	v_mfma_f32_16x16x32_bf16 v[32:35], v[166:169], v[186:189], v[32:35]
	v_mfma_f32_16x16x32_bf16 v[20:23], v[158:161], v[194:197], v[20:23]
	v_mfma_f32_16x16x32_bf16 v[16:19], v[166:169], v[194:197], v[16:19]
	v_mfma_f32_16x16x32_bf16 v[4:7], v[158:161], v[202:205], v[4:7]
	v_mfma_f32_16x16x32_bf16 v[0:3], v[166:169], v[202:205], v[0:3]
	v_mfma_f32_16x16x32_bf16 v[52:55], v[162:165], v[182:185], v[52:55]
	v_mfma_f32_16x16x32_bf16 v[48:51], v[170:173], v[182:185], v[48:51]
	v_mfma_f32_16x16x32_bf16 v[36:39], v[162:165], v[190:193], v[36:39]
	v_mfma_f32_16x16x32_bf16 v[32:35], v[170:173], v[190:193], v[32:35]
	v_mfma_f32_16x16x32_bf16 v[20:23], v[162:165], v[198:201], v[20:23]
	v_mfma_f32_16x16x32_bf16 v[16:19], v[170:173], v[198:201], v[16:19]
	v_mfma_f32_16x16x32_bf16 v[4:7], v[162:165], v[206:209], v[4:7]
	v_mfma_f32_16x16x32_bf16 v[0:3], v[170:173], v[206:209], v[0:3]
	s_setprio 0
	s_barrier
	s_add_u32 s92, s92, 0x100
	s_addc_u32 s93, s93, 0
	s_add_u32 s40, s40, 0x100
	s_addc_u32 s41, s41, 0
	s_cmp_ge_i32 s94, s91
	s_mov_b32 s42, s94
	s_cbranch_scc0 .LBB0_2890
	s_and_b64 vcc, exec, s[24:25]
	s_cbranch_vccz .LBB0_2893
